# v36 with the per-block s_setprio flips of the GEMM MFMA blocks removed and one static s_setprio 1 for waves 4-7 during the GEMM phases (section 7.4)
# baseline (speedup 1.0000x reference)
; #define REP(k) for (int rep_ = 0; rep_ < ((DUP) == (k) ? 2 : 1); ++rep_)
;     __device__ bool next(int i, Unit& u) const {
;         if (G == 256) { if (i >= R) return false; const int xcd = c & 7, r = c >> 3; u.pm = (xcd >> 1) * 8 + (r & 7); u.pn = (2 * i + (xcd & 1)) * 4 + (r >> 3); return true; }
;         const int L = i * G + c; if (L >= 32 * 8 * R) return false; u.pm = L & 31; u.pn = L >> 5; return true;
; __global__ void __launch_bounds__(NT, 2) fwd(Args args) {
;     ...
;     REP(1) {
;         pg8::Gemm g{XB, WIN, DM, DM, DM, 0}; EpiIn E{ssq, UBF, out + O_POOLP, QB, KB, VB, out + O_FKP, out + O_FVP};
;         pg8::BalancedOrder S{2, bx, G}; pg8::gemm_phase<EpiIn, pg8::BalancedOrder, true>(lds, g, S, E);
.LBB0_99:
	s_or_b64 exec, exec, s[4:5]
	s_cmpk_lg_i32 s76, 0x100
	s_cselect_b64 s[20:21], -1, 0
	s_cmpk_gt_i32 s86, 0x1ff
	s_cselect_b64 s[18:19], -1, 0
	s_lshl_b32 s2, s86, 2
	s_and_b32 s4, s2, 24
	s_bfe_u32 s5, s86, 0x30003
	s_or_b32 s26, s4, s5
	s_and_b32 s2, s2, 4
	s_ashr_i32 s4, s86, 6
	s_ashr_i32 s24, s86, 5
	s_and_b32 s25, s86, 31
	s_add_i32 s27, s2, s4
	s_cmpk_eq_i32 s76, 0x100
	s_cselect_b64 s[22:23], -1, 0
	v_writelane_b32 v242, s22, 10
	s_mov_b64 s[10:11], s[0:1]
	s_mov_b64 s[12:13], s[0:1]
	v_writelane_b32 v242, s23, 11
	s_and_b64 s[22:23], s[22:23], exec
	s_mov_b64 s[14:15], s[0:1]
	s_mov_b64 s[6:7], s[0:1]
	s_mov_b64 s[16:17], s[0:1]
	s_mov_b64 s[4:5], s[0:1]
	s_mov_b64 s[8:9], s[0:1]
	s_mov_b64 s[28:29], s[0:1]
	s_mov_b64 s[30:31], s[0:1]
	s_mov_b64 s[34:35], s[0:1]
	s_waitcnt lgkmcnt(0)
	v_mov_b32_e32 v2, v0
	s_cselect_b32 s22, s27, s24
	s_cselect_b32 s60, s26, s25
	s_and_b64 s[18:19], s[20:21], s[18:19]
	s_barrier
	v_readlane_b32 s99, v242, 0
	s_nop 1
	s_cmp_gt_u32 s99, 3
	s_cbranch_scc0 .Lsp_0
	s_setprio 1

; #define PG8_STAGE(bufoff, gbase, voff) do { _Pragma("unroll") for (int _i = 0; _i < 2; ++_i) { unsigned keep_; \
;         asm volatile("s_mov_b32 %0, m0\n\ts_mov_b32 m0, %3\n\ts_nop 0\n\tglobal_load_lds_dwordx4 %1, %2\n\ts_mov_b32 m0, %0" \
;             : "=&s"(keep_) : "v"((voff)[_i]), "s"((const void*)(gbase)), "s"(ldsb0 + (unsigned)(bufoff) + (unsigned)(_i * 8192)) : "memory"); } } while (0)
; #define PG8_LDA(dst, b, h) do { _Pragma("unroll") for (int m = 0; m < 4; ++m) _Pragma("unroll") for (int k = 0; k < 2; ++k) dst[m][k] = *(const LAS bf16x8*)(lds + PG8_SA(b, h) + aoff + m * 2048 + k * 1024); } while (0)
; #define PG8_LDB(dst, b, h) do { _Pragma("unroll") for (int n = 0; n < 2; ++n) _Pragma("unroll") for (int k = 0; k < 2; ++k) dst[n][k] = *(const LAS bf16x8*)(lds + PG8_SB(b, h) + boff + n * 2048 + k * 1024); } while (0)
; #define PG8_MMA(ai, bj, At, Bt) do { __builtin_amdgcn_s_setprio(1); _Pragma("unroll") for (int m = 0; m < 4; ++m) _Pragma("unroll") for (int n = 0; n < 2; ++n) _Pragma("unroll") for (int k = 0; k < 2; ++k) \
;         acc[ai][bj][m][n] = __builtin_amdgcn_mfma_f32_16x16x32_bf16(Bt[n][k], At[m][k], acc[ai][bj][m][n], 0, 0, 0); __builtin_amdgcn_s_setprio(0); } while (0)
; #define PG8_WAIT_V(n) asm volatile("s_waitcnt vmcnt(" #n ")" ::: "memory")
; #define PG8_WAIT_L(n) asm volatile("s_waitcnt lgkmcnt(" #n ")" ::: "memory")
; #define PG8_BAR __builtin_amdgcn_s_barrier()
; #define PG8_SCHED __builtin_amdgcn_sched_barrier(0)
; template <class Epi, class Sched, bool ALIGN_EPI>
; __device__ __forceinline__ void gemm_phase(LAS unsigned char* lds, const Gemm g, const Sched& S, const Epi& E) {
;     ...
;             PG8_LDB(B0, 0, 0); PG8_LDB(B1, 0, 1); PG8_SCHED; PG8_LDA(At, 0, 0); PG8_STAGE(PG8_SA(1, 1), a1 + hstepA, voffA);
;             PG8_WAIT_V(8); PG8_WAIT_L(0); PG8_BAR; PG8_MMA(0, 0, At, B0); PG8_MMA(0, 1, At, B1); PG8_BAR; PG8_SCHED;
;             PG8_LDA(At, 0, 1); PG8_STAGE(PG8_SB(0, 0), b2, voffB); PG8_STAGE(PG8_SB(0, 1), b2 + hstepB, voffB); PG8_STAGE(PG8_SA(0, 0), a2, voffA);
;             PG8_WAIT_V(8); PG8_WAIT_L(0); PG8_BAR; PG8_MMA(1, 0, At, B0); PG8_MMA(1, 1, At, B1); PG8_BAR; PG8_SCHED;
.LBB0_113:
	ds_read_b128 v[136:139], v157
	ds_read_b128 v[140:143], v157 offset:1024
	ds_read_b128 v[144:147], v157 offset:2048
	ds_read_b128 v[172:175], v157 offset:3072
	ds_read_b128 v[180:183], v158
	ds_read_b128 v[184:187], v158 offset:1024
	ds_read_b128 v[188:191], v158 offset:2048
	ds_read_b128 v[192:195], v158 offset:3072
	s_add_u32 s6, s4, 0x100
	s_addc_u32 s7, s5, 0
	s_cmp_eq_u32 s81, 28
	s_cselect_b32 s50, s39, s6
	s_cselect_b32 s51, s24, s7
	s_cselect_b32 s48, s58, s59
	s_cselect_b32 s49, s41, s80
	s_add_u32 s8, s50, 0x80
	s_addc_u32 s9, s51, 0
	ds_read_b128 v[196:199], v159
	ds_read_b128 v[206:209], v159 offset:1024
	ds_read_b128 v[210:213], v159 offset:2048
	ds_read_b128 v[214:217], v159 offset:3072
	ds_read_b128 v[218:221], v159 offset:4096
	ds_read_b128 v[222:225], v159 offset:5120
	ds_read_b128 v[226:229], v159 offset:6144
	ds_read_b128 v[230:233], v159 offset:7168
	s_add_u32 s4, s4, 0x80080
	s_addc_u32 s5, s5, 0
	s_mov_b32 m0, s75
	s_nop 0
	global_load_lds_dwordx4 v151, s[4:5]
	s_nop 0
	s_mov_b32 m0, s77
	s_nop 0
	global_load_lds_dwordx4 v153, s[4:5]
	s_waitcnt vmcnt(8)
	s_waitcnt lgkmcnt(0)
	s_barrier
	v_mfma_f32_16x16x32_bf16 v[126:129], v[136:139], v[196:199], v[126:129]
	v_mfma_f32_16x16x32_bf16 v[122:125], v[144:147], v[196:199], v[122:125]
	v_mfma_f32_16x16x32_bf16 v[110:113], v[136:139], v[210:213], v[110:113]
	v_mfma_f32_16x16x32_bf16 v[106:109], v[144:147], v[210:213], v[106:109]
	v_mfma_f32_16x16x32_bf16 v[94:97], v[136:139], v[218:221], v[94:97]
	v_mfma_f32_16x16x32_bf16 v[90:93], v[144:147], v[218:221], v[90:93]
	v_mfma_f32_16x16x32_bf16 v[78:81], v[136:139], v[226:229], v[78:81]
	v_mfma_f32_16x16x32_bf16 v[74:77], v[144:147], v[226:229], v[74:77]
	v_mfma_f32_16x16x32_bf16 v[126:129], v[140:143], v[206:209], v[126:129]
	v_mfma_f32_16x16x32_bf16 v[122:125], v[172:175], v[206:209], v[122:125]
	v_mfma_f32_16x16x32_bf16 v[110:113], v[140:143], v[214:217], v[110:113]
	v_mfma_f32_16x16x32_bf16 v[106:109], v[172:175], v[214:217], v[106:109]
	v_mfma_f32_16x16x32_bf16 v[94:97], v[140:143], v[222:225], v[94:97]
	v_mfma_f32_16x16x32_bf16 v[90:93], v[172:175], v[222:225], v[90:93]
	v_mfma_f32_16x16x32_bf16 v[78:81], v[140:143], v[230:233], v[78:81]
	v_mfma_f32_16x16x32_bf16 v[74:77], v[172:175], v[230:233], v[74:77]
	v_mfma_f32_16x16x32_bf16 v[118:121], v[180:183], v[196:199], v[118:121]
	v_mfma_f32_16x16x32_bf16 v[114:117], v[188:191], v[196:199], v[114:117]
	v_mfma_f32_16x16x32_bf16 v[102:105], v[180:183], v[210:213], v[102:105]
	v_mfma_f32_16x16x32_bf16 v[98:101], v[188:191], v[210:213], v[98:101]
	v_mfma_f32_16x16x32_bf16 v[86:89], v[180:183], v[218:221], v[86:89]
	v_mfma_f32_16x16x32_bf16 v[82:85], v[188:191], v[218:221], v[82:85]
	v_mfma_f32_16x16x32_bf16 v[70:73], v[180:183], v[226:229], v[70:73]
	v_mfma_f32_16x16x32_bf16 v[66:69], v[188:191], v[226:229], v[66:69]
	v_mfma_f32_16x16x32_bf16 v[118:121], v[184:187], v[206:209], v[118:121]
	v_mfma_f32_16x16x32_bf16 v[114:117], v[192:195], v[206:209], v[114:117]
	v_mfma_f32_16x16x32_bf16 v[102:105], v[184:187], v[214:217], v[102:105]
	v_mfma_f32_16x16x32_bf16 v[98:101], v[192:195], v[214:217], v[98:101]
	v_mfma_f32_16x16x32_bf16 v[86:89], v[184:187], v[222:225], v[86:89]
	v_mfma_f32_16x16x32_bf16 v[82:85], v[192:195], v[222:225], v[82:85]
	v_mfma_f32_16x16x32_bf16 v[70:73], v[184:187], v[230:233], v[70:73]
	v_mfma_f32_16x16x32_bf16 v[66:69], v[192:195], v[230:233], v[66:69]
	s_barrier
	ds_read_b128 v[196:199], v159 offset:16384
	ds_read_b128 v[206:209], v159 offset:17408
	ds_read_b128 v[210:213], v159 offset:18432
	ds_read_b128 v[214:217], v159 offset:19456
	ds_read_b128 v[218:221], v159 offset:20480
	ds_read_b128 v[222:225], v159 offset:21504
	ds_read_b128 v[226:229], v159 offset:22528
	ds_read_b128 v[230:233], v159 offset:23552
	s_mov_b32 m0, s23
	s_nop 0
	global_load_lds_dwordx4 v152, s[48:49]
	s_nop 0
	s_mov_b32 m0, s62
	s_nop 0
	global_load_lds_dwordx4 v154, s[48:49]
	s_add_u32 s4, s48, 0x80000
	s_addc_u32 s5, s49, 0
	s_mov_b32 m0, s63
	s_nop 0
	global_load_lds_dwordx4 v152, s[4:5]
	s_nop 0
	s_mov_b32 m0, s64
	s_nop 0
	global_load_lds_dwordx4 v154, s[4:5]
	s_mov_b32 m0, s61
	s_nop 0
	global_load_lds_dwordx4 v151, s[50:51]
	s_nop 0
	s_mov_b32 m0, s65
	s_nop 0
	global_load_lds_dwordx4 v153, s[50:51]
	s_waitcnt vmcnt(8)
	s_waitcnt lgkmcnt(0)
	s_barrier
	v_mfma_f32_16x16x32_bf16 v[62:65], v[136:139], v[196:199], v[62:65]
	v_mfma_f32_16x16x32_bf16 v[58:61], v[144:147], v[196:199], v[58:61]
	v_mfma_f32_16x16x32_bf16 v[46:49], v[136:139], v[210:213], v[46:49]
	v_mfma_f32_16x16x32_bf16 v[42:45], v[144:147], v[210:213], v[42:45]
	v_mfma_f32_16x16x32_bf16 v[30:33], v[136:139], v[218:221], v[30:33]
	v_mfma_f32_16x16x32_bf16 v[26:29], v[144:147], v[218:221], v[26:29]
	v_mfma_f32_16x16x32_bf16 v[14:17], v[136:139], v[226:229], v[14:17]
	v_mfma_f32_16x16x32_bf16 v[10:13], v[144:147], v[226:229], v[10:13]
	v_mfma_f32_16x16x32_bf16 v[62:65], v[140:143], v[206:209], v[62:65]
	v_mfma_f32_16x16x32_bf16 v[58:61], v[172:175], v[206:209], v[58:61]
	v_mfma_f32_16x16x32_bf16 v[46:49], v[140:143], v[214:217], v[46:49]
	v_mfma_f32_16x16x32_bf16 v[42:45], v[172:175], v[214:217], v[42:45]
	v_mfma_f32_16x16x32_bf16 v[30:33], v[140:143], v[222:225], v[30:33]
	v_mfma_f32_16x16x32_bf16 v[26:29], v[172:175], v[222:225], v[26:29]
	v_mfma_f32_16x16x32_bf16 v[14:17], v[140:143], v[230:233], v[14:17]
	v_mfma_f32_16x16x32_bf16 v[10:13], v[172:175], v[230:233], v[10:13]
	v_mfma_f32_16x16x32_bf16 v[54:57], v[180:183], v[196:199], v[54:57]
	v_mfma_f32_16x16x32_bf16 v[50:53], v[188:191], v[196:199], v[50:53]
	v_mfma_f32_16x16x32_bf16 v[38:41], v[180:183], v[210:213], v[38:41]
	v_mfma_f32_16x16x32_bf16 v[34:37], v[188:191], v[210:213], v[34:37]
	v_mfma_f32_16x16x32_bf16 v[22:25], v[180:183], v[218:221], v[22:25]
	v_mfma_f32_16x16x32_bf16 v[18:21], v[188:191], v[218:221], v[18:21]
	v_mfma_f32_16x16x32_bf16 v[6:9], v[180:183], v[226:229], v[6:9]
	v_mfma_f32_16x16x32_bf16 v[2:5], v[188:191], v[226:229], v[2:5]
	v_mfma_f32_16x16x32_bf16 v[54:57], v[184:187], v[206:209], v[54:57]
	v_mfma_f32_16x16x32_bf16 v[50:53], v[192:195], v[206:209], v[50:53]
	v_mfma_f32_16x16x32_bf16 v[38:41], v[184:187], v[214:217], v[38:41]
	v_mfma_f32_16x16x32_bf16 v[34:37], v[192:195], v[214:217], v[34:37]
	v_mfma_f32_16x16x32_bf16 v[22:25], v[184:187], v[222:225], v[22:25]
	v_mfma_f32_16x16x32_bf16 v[18:21], v[192:195], v[222:225], v[18:21]
	v_mfma_f32_16x16x32_bf16 v[6:9], v[184:187], v[230:233], v[6:9]
	v_mfma_f32_16x16x32_bf16 v[2:5], v[192:195], v[230:233], v[2:5]
	s_barrier
; #define PG8_STAGE(bufoff, gbase, voff) do { _Pragma("unroll") for (int _i = 0; _i < 2; ++_i) { unsigned keep_; \
;         asm volatile("s_mov_b32 %0, m0\n\ts_mov_b32 m0, %3\n\ts_nop 0\n\tglobal_load_lds_dwordx4 %1, %2\n\ts_mov_b32 m0, %0" \
;             : "=&s"(keep_) : "v"((voff)[_i]), "s"((const void*)(gbase)), "s"(ldsb0 + (unsigned)(bufoff) + (unsigned)(_i * 8192)) : "memory"); } } while (0)
; #define PG8_LDA(dst, b, h) do { _Pragma("unroll") for (int m = 0; m < 4; ++m) _Pragma("unroll") for (int k = 0; k < 2; ++k) dst[m][k] = *(const LAS bf16x8*)(lds + PG8_SA(b, h) + aoff + m * 2048 + k * 1024); } while (0)
; #define PG8_LDB(dst, b, h) do { _Pragma("unroll") for (int n = 0; n < 2; ++n) _Pragma("unroll") for (int k = 0; k < 2; ++k) dst[n][k] = *(const LAS bf16x8*)(lds + PG8_SB(b, h) + boff + n * 2048 + k * 1024); } while (0)
; #define PG8_MMA(ai, bj, At, Bt) do { __builtin_amdgcn_s_setprio(1); _Pragma("unroll") for (int m = 0; m < 4; ++m) _Pragma("unroll") for (int n = 0; n < 2; ++n) _Pragma("unroll") for (int k = 0; k < 2; ++k) \
;         acc[ai][bj][m][n] = __builtin_amdgcn_mfma_f32_16x16x32_bf16(Bt[n][k], At[m][k], acc[ai][bj][m][n], 0, 0, 0); __builtin_amdgcn_s_setprio(0); } while (0)
; #define PG8_WAIT_V(n) asm volatile("s_waitcnt vmcnt(" #n ")" ::: "memory")
; #define PG8_WAIT_L(n) asm volatile("s_waitcnt lgkmcnt(" #n ")" ::: "memory")
; #define PG8_BAR __builtin_amdgcn_s_barrier()
; #define PG8_SCHED __builtin_amdgcn_sched_barrier(0)
; template <class Epi, class Sched, bool ALIGN_EPI>
; __device__ __forceinline__ void gemm_phase(LAS unsigned char* lds, const Gemm g, const Sched& S, const Epi& E) {
;     ...
;             PG8_LDB(B0, 1, 0); PG8_LDB(B1, 1, 1); PG8_SCHED; PG8_LDA(At, 1, 0); PG8_STAGE(PG8_SA(0, 1), a2 + hstepA, voffA);
;             PG8_WAIT_V(8); PG8_WAIT_L(0); PG8_BAR; PG8_MMA(0, 0, At, B0); PG8_MMA(0, 1, At, B1); PG8_BAR; PG8_SCHED;
;             PG8_LDA(At, 1, 1); PG8_STAGE(PG8_SB(1, 0), b3, voffB); PG8_STAGE(PG8_SB(1, 1), b3 + hstepB, voffB); PG8_STAGE(PG8_SA(1, 0), a3, voffA);
;             PG8_WAIT_V(8); PG8_WAIT_L(0); PG8_BAR; PG8_MMA(1, 0, At, B0); PG8_MMA(1, 1, At, B1); PG8_BAR; PG8_SCHED;
	ds_read_b128 v[136:139], v160
	ds_read_b128 v[140:143], v160 offset:1024
	ds_read_b128 v[144:147], v160 offset:2048
	ds_read_b128 v[172:175], v160 offset:3072
	ds_read_b128 v[180:183], v161
	ds_read_b128 v[184:187], v161 offset:1024
	ds_read_b128 v[188:191], v161 offset:2048
	ds_read_b128 v[192:195], v161 offset:3072
	ds_read_b128 v[196:199], v159 offset:32768
	ds_read_b128 v[206:209], v159 offset:33792
	ds_read_b128 v[210:213], v159 offset:34816
	ds_read_b128 v[214:217], v159 offset:35840
	ds_read_b128 v[218:221], v159 offset:36864
	ds_read_b128 v[222:225], v159 offset:37888
	ds_read_b128 v[226:229], v159 offset:38912
	ds_read_b128 v[230:233], v159 offset:39936
	s_add_u32 s4, s50, 0x80000
	s_addc_u32 s5, s51, 0
	s_mov_b32 m0, s66
	s_nop 0
	global_load_lds_dwordx4 v151, s[4:5]
	s_nop 0
	s_mov_b32 m0, s67
	s_nop 0
	global_load_lds_dwordx4 v153, s[4:5]
	s_waitcnt vmcnt(8)
	s_waitcnt lgkmcnt(0)
	s_barrier
	v_mfma_f32_16x16x32_bf16 v[126:129], v[136:139], v[196:199], v[126:129]
	v_mfma_f32_16x16x32_bf16 v[122:125], v[144:147], v[196:199], v[122:125]
	v_mfma_f32_16x16x32_bf16 v[110:113], v[136:139], v[210:213], v[110:113]
	v_mfma_f32_16x16x32_bf16 v[106:109], v[144:147], v[210:213], v[106:109]
	v_mfma_f32_16x16x32_bf16 v[94:97], v[136:139], v[218:221], v[94:97]
	v_mfma_f32_16x16x32_bf16 v[90:93], v[144:147], v[218:221], v[90:93]
	v_mfma_f32_16x16x32_bf16 v[78:81], v[136:139], v[226:229], v[78:81]
	v_mfma_f32_16x16x32_bf16 v[74:77], v[144:147], v[226:229], v[74:77]
	v_mfma_f32_16x16x32_bf16 v[126:129], v[140:143], v[206:209], v[126:129]
	v_mfma_f32_16x16x32_bf16 v[122:125], v[172:175], v[206:209], v[122:125]
	v_mfma_f32_16x16x32_bf16 v[110:113], v[140:143], v[214:217], v[110:113]
	v_mfma_f32_16x16x32_bf16 v[106:109], v[172:175], v[214:217], v[106:109]
	v_mfma_f32_16x16x32_bf16 v[94:97], v[140:143], v[222:225], v[94:97]
	v_mfma_f32_16x16x32_bf16 v[90:93], v[172:175], v[222:225], v[90:93]
	v_mfma_f32_16x16x32_bf16 v[78:81], v[140:143], v[230:233], v[78:81]
	v_mfma_f32_16x16x32_bf16 v[74:77], v[172:175], v[230:233], v[74:77]
	v_mfma_f32_16x16x32_bf16 v[118:121], v[180:183], v[196:199], v[118:121]
	v_mfma_f32_16x16x32_bf16 v[114:117], v[188:191], v[196:199], v[114:117]
	v_mfma_f32_16x16x32_bf16 v[102:105], v[180:183], v[210:213], v[102:105]
	v_mfma_f32_16x16x32_bf16 v[98:101], v[188:191], v[210:213], v[98:101]
	v_mfma_f32_16x16x32_bf16 v[86:89], v[180:183], v[218:221], v[86:89]
	v_mfma_f32_16x16x32_bf16 v[82:85], v[188:191], v[218:221], v[82:85]
	v_mfma_f32_16x16x32_bf16 v[70:73], v[180:183], v[226:229], v[70:73]
	v_mfma_f32_16x16x32_bf16 v[66:69], v[188:191], v[226:229], v[66:69]
	v_mfma_f32_16x16x32_bf16 v[118:121], v[184:187], v[206:209], v[118:121]
	v_mfma_f32_16x16x32_bf16 v[114:117], v[192:195], v[206:209], v[114:117]
	v_mfma_f32_16x16x32_bf16 v[102:105], v[184:187], v[214:217], v[102:105]
	v_mfma_f32_16x16x32_bf16 v[98:101], v[192:195], v[214:217], v[98:101]
	v_mfma_f32_16x16x32_bf16 v[86:89], v[184:187], v[222:225], v[86:89]
	v_mfma_f32_16x16x32_bf16 v[82:85], v[192:195], v[222:225], v[82:85]
	v_mfma_f32_16x16x32_bf16 v[70:73], v[184:187], v[230:233], v[70:73]
	v_mfma_f32_16x16x32_bf16 v[66:69], v[192:195], v[230:233], v[66:69]
	s_barrier
	ds_read_b128 v[196:199], v159 offset:49152
	ds_read_b128 v[206:209], v159 offset:50176
	ds_read_b128 v[210:213], v159 offset:51200
	ds_read_b128 v[214:217], v159 offset:52224
	ds_read_b128 v[218:221], v159 offset:53248
	ds_read_b128 v[222:225], v159 offset:54272
	ds_read_b128 v[226:229], v159 offset:55296
	ds_read_b128 v[230:233], v159 offset:56320
	s_add_u32 s4, s48, 0x80
	s_addc_u32 s5, s49, 0
	s_mov_b32 m0, s69
	s_nop 0
	global_load_lds_dwordx4 v152, s[4:5]
	s_nop 0
	s_mov_b32 m0, s70
	s_nop 0
	global_load_lds_dwordx4 v154, s[4:5]
	s_add_u32 s4, s48, 0x80080
	s_addc_u32 s5, s49, 0
	s_mov_b32 m0, s73
	s_nop 0
	global_load_lds_dwordx4 v152, s[4:5]
	s_nop 0
	s_mov_b32 m0, s74
	s_nop 0
	global_load_lds_dwordx4 v154, s[4:5]
	s_mov_b32 m0, s71
	s_nop 0
	global_load_lds_dwordx4 v151, s[8:9]
	s_nop 0
	s_mov_b32 m0, s72
	s_nop 0
	global_load_lds_dwordx4 v153, s[8:9]
	s_waitcnt vmcnt(8)
	s_waitcnt lgkmcnt(0)
	s_barrier
	v_mfma_f32_16x16x32_bf16 v[62:65], v[136:139], v[196:199], v[62:65]
	v_mfma_f32_16x16x32_bf16 v[58:61], v[144:147], v[196:199], v[58:61]
	v_mfma_f32_16x16x32_bf16 v[46:49], v[136:139], v[210:213], v[46:49]
	v_mfma_f32_16x16x32_bf16 v[42:45], v[144:147], v[210:213], v[42:45]
	v_mfma_f32_16x16x32_bf16 v[30:33], v[136:139], v[218:221], v[30:33]
	v_mfma_f32_16x16x32_bf16 v[26:29], v[144:147], v[218:221], v[26:29]
	v_mfma_f32_16x16x32_bf16 v[14:17], v[136:139], v[226:229], v[14:17]
	v_mfma_f32_16x16x32_bf16 v[10:13], v[144:147], v[226:229], v[10:13]
	v_mfma_f32_16x16x32_bf16 v[62:65], v[140:143], v[206:209], v[62:65]
	v_mfma_f32_16x16x32_bf16 v[58:61], v[172:175], v[206:209], v[58:61]
	v_mfma_f32_16x16x32_bf16 v[46:49], v[140:143], v[214:217], v[46:49]
	v_mfma_f32_16x16x32_bf16 v[42:45], v[172:175], v[214:217], v[42:45]
	v_mfma_f32_16x16x32_bf16 v[30:33], v[140:143], v[222:225], v[30:33]
	v_mfma_f32_16x16x32_bf16 v[26:29], v[172:175], v[222:225], v[26:29]
	v_mfma_f32_16x16x32_bf16 v[14:17], v[140:143], v[230:233], v[14:17]
	v_mfma_f32_16x16x32_bf16 v[10:13], v[172:175], v[230:233], v[10:13]
	v_mfma_f32_16x16x32_bf16 v[54:57], v[180:183], v[196:199], v[54:57]
	v_mfma_f32_16x16x32_bf16 v[50:53], v[188:191], v[196:199], v[50:53]
	v_mfma_f32_16x16x32_bf16 v[38:41], v[180:183], v[210:213], v[38:41]
	v_mfma_f32_16x16x32_bf16 v[34:37], v[188:191], v[210:213], v[34:37]
	v_mfma_f32_16x16x32_bf16 v[22:25], v[180:183], v[218:221], v[22:25]
	v_mfma_f32_16x16x32_bf16 v[18:21], v[188:191], v[218:221], v[18:21]
	v_mfma_f32_16x16x32_bf16 v[6:9], v[180:183], v[226:229], v[6:9]
	v_mfma_f32_16x16x32_bf16 v[2:5], v[188:191], v[226:229], v[2:5]
	v_mfma_f32_16x16x32_bf16 v[54:57], v[184:187], v[206:209], v[54:57]
	v_mfma_f32_16x16x32_bf16 v[50:53], v[192:195], v[206:209], v[50:53]
	v_mfma_f32_16x16x32_bf16 v[38:41], v[184:187], v[214:217], v[38:41]
	v_mfma_f32_16x16x32_bf16 v[34:37], v[192:195], v[214:217], v[34:37]
	v_mfma_f32_16x16x32_bf16 v[22:25], v[184:187], v[222:225], v[22:25]
	v_mfma_f32_16x16x32_bf16 v[18:21], v[192:195], v[222:225], v[18:21]
	v_mfma_f32_16x16x32_bf16 v[6:9], v[184:187], v[230:233], v[6:9]
	v_mfma_f32_16x16x32_bf16 v[2:5], v[192:195], v[230:233], v[2:5]
	s_barrier
	s_add_i32 s81, s81, 2
	s_add_u32 s59, s59, 0x100
	s_addc_u32 s80, s80, 0
	s_cmp_gt_u32 s81, 29
	s_mov_b64 s[4:5], s[6:7]
	s_cbranch_scc0 .LBB0_113
	s_and_b64 vcc, exec, s[36:37]
	s_cbranch_vccz .LBB0_116
	s_barrier

; #define REP(k) for (int rep_ = 0; rep_ < ((DUP) == (k) ? 2 : 1); ++rep_)
; __global__ void __launch_bounds__(NT, 2) fwd(Args args) {
;     ...
;     REP(4) {
;         const int c0 = 4 * (tid & 255), grp = __builtin_amdgcn_readfirstlane((tid >> 6) & 3), w = 2 << grp, hlf = __builtin_amdgcn_readfirstlane(tid >> 8);
;         const int NSC_ = SEQ / 1024 + DECB * ((NKS + 1023) / 1024), GP = G > 2 * NSC_ ? G - NSC_ : G;
;         for (int pit = (G > 2 * NSC_ && bx >= GP) ? (1 << 30) : bx; pit < (512 + DECB) / 2; pit += GP) {
;             const int it = 2 * pit + hlf;
;             const bool smp = it >= 512; const int b = it - 512;
;             const int r0 = smp ? 0 : it * 16, base = smp ? SEQ + b * DECS : 0;
.LBB0_469:
	s_or_b64 exec, exec, s[4:5]
	s_sub_i32 s6, s76, 48
	s_cmpk_lt_i32 s76, 0x61
	s_cselect_b64 s[4:5], -1, 0
	s_and_b64 s[2:3], s[4:5], exec
	s_cselect_b32 s3, s76, s6
	s_cmp_lt_i32 s86, s3
	s_cselect_b64 s[6:7], -1, 0
	s_or_b64 s[10:11], s[4:5], s[6:7]
	s_cmpk_lt_i32 s86, 0x104
	s_cselect_b64 s[4:5], -1, 0
	s_and_b64 s[6:7], s[10:11], s[4:5]
	v_readfirstlane_b32 s4, v150
	v_readfirstlane_b32 s2, v148
	s_and_b64 vcc, exec, s[6:7]
	s_waitcnt lgkmcnt(0)
	s_barrier
	s_setprio 0
	s_cbranch_vccz .LBB0_549
	s_and_b32 s4, s4, 3
	s_lshl_b32 s23, 2, s4
	s_ashr_i32 s2, s2, 8
	s_cmp_lg_u32 s4, 0
	s_cselect_b64 s[14:15], -1, 0
	s_cmp_gt_u32 s4, 1
	s_cselect_b64 s[16:17], -1, 0
	s_cmp_eq_u32 s4, 3
	v_lshlrev_b32_e32 v2, 2, v148
	s_cselect_b64 s[26:27], -1, 0
	s_lshl_b32 s4, s86, 1
	v_and_b32_e32 v126, 0x3fc, v2
	s_add_i32 s24, s2, s4
	s_lshl_b32 s4, s86, 5
	s_lshl_b32 s2, s2, 4
	v_mov_b32_e32 v129, 0
	s_mov_b32 s13, 0
	v_cvt_f32_ubyte0_e32 v127, s23
	s_lshl_b32 s25, s3, 1
	s_add_i32 s28, s4, s2
	s_lshl_b32 s40, s3, 5
	s_mov_b64 s[30:31], 0xe000000
	s_movk_i32 s41, 0x2000
	s_movk_i32 s42, 0x4000
	s_movk_i32 s43, 0x6000
	s_mov_b32 s44, 0x8000
	s_mov_b32 s45, 0xa000
	s_mov_b32 s46, 0xc000
	s_mov_b32 s47, 0xe000
	s_mov_b32 s48, 0xe001000
	s_mov_b32 s49, 0xe003000
	s_mov_b32 s50, 0xe005000
	s_mov_b32 s51, 0xe007000
	s_mov_b32 s52, 0xe009000
	s_mov_b32 s53, 0xe00b000
	s_mov_b32 s54, 0xe00c000
	v_lshlrev_b32_e32 v128, 1, v126
	s_mov_b32 s55, 0x16400000
	s_mov_b32 s57, s86
	s_branch .LBB0_472

; __device__ __forceinline__ int otid() { int t = threadIdx.x; asm volatile("" : "+v"(t)); return t; }
; #define PG8_WAIT_V(n) asm volatile("s_waitcnt vmcnt(" #n ")" ::: "memory")
; #define PG8_BAR __builtin_amdgcn_s_barrier()
; template <class Epi, class Sched, bool ALIGN_EPI>
; __device__ __forceinline__ void gemm_phase(LAS unsigned char* lds, const Gemm g, const Sched& S, const Epi& E) {
;     const int tid = otid(), wid = __builtin_amdgcn_readfirstlane(tid >> 6), lane = tid & 63, wr = wid >> 2, wc = wid & 3, fr = lane & 15, fq = lane >> 4;
;     const int K = g.K, nt = K / BK;
;     unsigned voffA[2], voffB[2];
; #pragma unroll
;     for (int i = 0; i < 2; ++i) { int R, C; stage_rc(tid * 16 + i * 8192, R, C); const int Rb = (R & ~31) + perm32(R & 31);
;         voffA[i] = (unsigned)(R * g.lda + C) * 2u; voffB[i] = (unsigned)(Rb * g.ldb + C) * 2u; }
;     const size_t kstep = (size_t)(BK * 2);
;     const size_t hstepA = (size_t)HALF * g.lda * 2, hstepB = (size_t)HALF * g.ldb * 2;
;     const size_t tstepA = 2 * hstepA, tstepB = 2 * hstepB;
;     const unsigned ldsw = (unsigned)wid * 1024u;
;     const int aoff = lds_byte(wr * 64 + fr, fq * 8), boff = lds_byte(wc * 32 + fr, fq * 8);
;     ...
;     const unsigned ldsb0 = (unsigned)(uintptr_t)lds + ldsw;
;     ...
;     Unit cur, nxt; int ui = 0;
;     if (!S.next(0, cur)) return;
;     f32x4 acc[2][2][4][2];
; #pragma unroll
;     for (int a = 0; a < 2; ++a)
; #pragma unroll
;         for (int b = 0; b < 2; ++b)
; #pragma unroll
;             for (int m = 0; m < 4; ++m)
; #pragma unroll
;                 for (int n = 0; n < 2; ++n) acc[a][b][m][n] = (f32x4){0.f, 0.f, 0.f, 0.f};
;     bf16x8 At[4][2], B0[2][2], B1[2][2];
;     float pre[Epi::NPRE > 0 ? Epi::NPRE : 1];
;     if constexpr (Epi::NPRE > 0) E.preload(cur, wr, fr, pre);
;     const char* cA = (const char*)g.A + (size_t)cur.pm * tstepA + (size_t)cur.pn * g.a_koff * 2; const char* cB = (const char*)g.Bt + (size_t)cur.pn * tstepB;
;     PG8_STAGE(PG8_SB(0, 0), cB, voffB); PG8_STAGE(PG8_SB(0, 1), cB + hstepB, voffB); PG8_STAGE(PG8_SA(0, 0), cA, voffA); PG8_STAGE(PG8_SA(0, 1), cA + hstepA, voffA);
;     if (wr == 1) PG8_BAR;
;     PG8_WAIT_V(2); PG8_BAR;
;     PG8_STAGE(PG8_SB(1, 0), cB + kstep, voffB); PG8_STAGE(PG8_SA(1, 0), cA + kstep, voffA); PG8_STAGE(PG8_SB(1, 1), cB + hstepB + kstep, voffB);
;     PG8_WAIT_V(6); PG8_BAR;
.LBB0_792:
	s_or_b64 exec, exec, s[4:5]
	s_mov_b64 s[8:9], s[0:1]
	s_mov_b64 s[10:11], s[0:1]
	s_mov_b64 s[12:13], s[0:1]
	s_mov_b64 s[14:15], s[0:1]
	s_waitcnt lgkmcnt(0)
	v_mov_b32_e32 v2, v0
	s_barrier
	s_setprio 0
	s_ashr_i32 s77, s76, 31
	s_ashr_i32 s87, s86, 31
	s_and_b64 vcc, exec, s[18:19]
	v_readfirstlane_b32 s3, v2
	s_cbranch_vccz .LBB0_812
	v_bfe_i32 v5, v2, 27, 1
	v_lshlrev_b32_e32 v3, 4, v2
	v_lshrrev_b32_e32 v5, 22, v5
	v_add_u32_e32 v5, v3, v5
	v_and_b32_e32 v5, 0xfffffc00, v5
	v_sub_u32_e32 v5, v3, v5
	v_ashrrev_i32_e32 v4, 31, v2
	v_lshrrev_b32_e32 v6, 4, v5
	v_lshrrev_b32_e32 v4, 26, v4
	v_bitop3_b32 v6, v6, v5, 32 bitop3:0x6c
	v_ashrrev_i32_e32 v5, 31, v5
	v_add_u32_e32 v4, v2, v4
	v_lshrrev_b32_e32 v5, 26, v5
	v_ashrrev_i32_e32 v4, 6, v4
	v_add_u32_e32 v5, v6, v5
	v_lshlrev_b32_e32 v7, 3, v4
	v_ashrrev_i32_e32 v5, 6, v5
	v_and_b32_e32 v7, -16, v7
	v_mul_i32_i24_e32 v8, 64, v5
	v_add_u32_e32 v7, v5, v7
	v_sub_u32_e32 v6, v6, v8
	v_mov_b32_e32 v8, 1
	v_lshlrev_b32_e32 v4, 5, v4
	v_ashrrev_i16_sdwa v6, v8, sext(v6) dst_sel:DWORD dst_unused:UNUSED_PAD src0_sel:DWORD src1_sel:BYTE_0
	v_lshlrev_b32_e32 v9, 1, v7
	v_lshrrev_b32_e32 v10, 2, v7
	v_and_b32_e32 v5, 3, v5
	s_mov_b32 s2, 0x7fffe0
	v_and_b32_e32 v4, 32, v4
	v_bfe_i32 v6, v6, 0, 16
	v_and_b32_e32 v9, 24, v9
	v_and_b32_e32 v10, 4, v10
	v_and_or_b32 v5, v7, s2, v5
	v_or3_b32 v5, v5, v10, v9
	v_add_lshl_u32 v4, v4, v6, 1
	v_add_u32_e32 v3, 0x2000, v3
	v_lshl_add_u32 v144, v7, 11, v4
	v_lshl_add_u32 v145, v5, 9, v4
	v_ashrrev_i32_e32 v4, 31, v3
	v_lshrrev_b32_e32 v4, 22, v4
	v_add_u32_e32 v4, v3, v4
	v_ashrrev_i32_e32 v4, 10, v4
	v_mul_i32_i24_e32 v5, 0x400, v4
	v_sub_u32_e32 v3, v3, v5
	v_lshrrev_b32_e32 v5, 4, v3
	s_load_dwordx2 s[16:17], s[8:9], 0xb0
	s_load_dwordx2 s[18:19], s[10:11], 0xb0
	s_load_dwordx2 s[4:5], s[12:13], 0x60
	s_load_dwordx2 s[6:7], s[14:15], 0xb0
	v_bitop3_b32 v3, v5, v3, 32 bitop3:0x6c
	v_ashrrev_i32_e32 v6, 31, v3
	s_waitcnt lgkmcnt(0)
	s_add_u32 s23, s16, 0x16400000
	v_lshrrev_b32_e32 v6, 26, v6
	s_addc_u32 s24, s17, 0
	v_lshlrev_b32_e32 v5, 3, v4
	v_add_u32_e32 v6, v3, v6
	s_add_u32 s25, s18, 0x1200000
	v_and_b32_e32 v5, -16, v5
	v_ashrrev_i32_e32 v7, 6, v6
	s_addc_u32 s54, s19, 0
	v_add_u32_e32 v5, v7, v5
	v_and_b32_e32 v7, 3, v7
	s_ashr_i32 s13, s3, 6
	v_and_or_b32 v7, v5, s2, v7
	s_lshl_b32 s2, s13, 10
	s_add_i32 s56, s2, 0
	s_lshr_b32 s2, s87, 29
	s_add_i32 s2, s86, s2
	s_and_b32 s8, s2, -8
	s_sub_i32 s8, s86, s8
	s_ashr_i32 s12, s3, 8
	s_lshl_b32 s10, s8, 4
	s_ashr_i32 s2, s2, 3
	s_mul_i32 s9, s8, 17
	s_cmp_lt_i32 s8, 0
	s_cselect_b32 s8, s9, s10
	s_add_i32 s2, s8, s2
	s_ashr_i32 s8, s2, 31
	s_lshr_b32 s8, s8, 27
	s_add_i32 s8, s2, s8
	s_ashr_i32 s9, s8, 5
	s_andn2_b32 s8, s8, 31
	s_sub_i32 s2, s2, s8
	s_bfe_i32 s8, s2, 0x80000
	s_bfe_u32 s8, s8, 0x3000c
	s_add_i32 s8, s2, s8
	s_bfe_i32 s10, s8, 0x80000
	s_and_b32 s8, s8, 0xf8
	s_sub_i32 s2, s2, s8
	s_lshl_b32 s9, s9, 3
	s_sext_i32_i16 s10, s10
	s_sext_i32_i8 s2, s2
	v_and_b32_e32 v6, 0xc0, v6
	s_lshr_b32 s10, s10, 3
	s_add_i32 s28, s9, s2
	v_sub_u32_e32 v3, v3, v6
	s_ashr_i32 s29, s28, 31
	s_bfe_i64 s[14:15], s[10:11], 0x100000
	v_lshlrev_b32_e32 v4, 5, v4
	v_ashrrev_i16_sdwa v3, v8, sext(v3) dst_sel:DWORD dst_unused:UNUSED_PAD src0_sel:DWORD src1_sel:BYTE_0
	v_lshlrev_b32_e32 v6, 1, v5
	v_lshrrev_b32_e32 v8, 2, v5
	s_lshl_b64 s[8:9], s[28:29], 19
	s_lshl_b64 s[16:17], s[14:15], 9
	s_lshl_b64 s[14:15], s[14:15], 17
	v_and_b32_e32 v4, 32, v4
	v_bfe_i32 v3, v3, 0, 16
	v_and_b32_e32 v6, 24, v6
	v_and_b32_e32 v8, 4, v8
	s_add_u32 s30, s25, s14
	v_or3_b32 v6, v7, v8, v6
	v_add_lshl_u32 v3, v4, v3, 1
	s_addc_u32 s31, s54, s15
	s_add_i32 s29, s56, 0x10000
	s_mov_b32 m0, s29
	s_nop 0
	global_load_lds_dwordx4 v145, s[30:31]
	v_lshl_add_u32 v147, v6, 9, v3
	s_add_i32 s57, s56, 0x12000
	s_mov_b32 m0, s57
	s_nop 0
	global_load_lds_dwordx4 v147, s[30:31]
	s_add_u32 s2, s23, s8
	s_addc_u32 s11, s24, s9
	s_add_u32 s8, s30, 0x10000
	s_addc_u32 s9, s31, 0
	s_add_i32 s58, s56, 0x14000
	s_mov_b32 m0, s58
	s_nop 0
	global_load_lds_dwordx4 v145, s[8:9]
	s_add_i32 s59, s56, 0x16000
	s_mov_b32 m0, s59
	s_nop 0
	global_load_lds_dwordx4 v147, s[8:9]
	s_add_u32 s34, s2, s16
	s_addc_u32 s35, s11, s17
	s_mov_b32 m0, s56
	s_nop 0
	global_load_lds_dwordx4 v144, s[34:35]
	s_add_i32 s61, s56, 0x2000
	v_lshl_add_u32 v146, v5, 11, v3
	s_mov_b32 m0, s61
	s_nop 0
	global_load_lds_dwordx4 v146, s[34:35]
	s_add_u32 s14, s34, 0x40000
	s_addc_u32 s15, s35, 0
	s_add_i32 s62, s56, 0x4000
	s_mov_b32 m0, s62
	s_nop 0
	global_load_lds_dwordx4 v144, s[14:15]
	s_add_i32 s63, s56, 0x6000
	s_mov_b32 m0, s63
	s_nop 0
	global_load_lds_dwordx4 v146, s[14:15]
	s_cmp_eq_u32 s12, 1
	s_mov_b32 s55, 0
	s_cselect_b64 s[8:9], -1, 0
	s_cmp_lg_u32 s12, 1
	s_cbranch_scc1 .LBB0_795
	s_barrier

; #define PG8_STAGE(bufoff, gbase, voff) do { _Pragma("unroll") for (int _i = 0; _i < 2; ++_i) { unsigned keep_; \
;         asm volatile("s_mov_b32 %0, m0\n\ts_mov_b32 m0, %3\n\ts_nop 0\n\tglobal_load_lds_dwordx4 %1, %2\n\ts_mov_b32 m0, %0" \
;             : "=&s"(keep_) : "v"((voff)[_i]), "s"((const void*)(gbase)), "s"(ldsb0 + (unsigned)(bufoff) + (unsigned)(_i * 8192)) : "memory"); } } while (0)
; #define PG8_LDA(dst, b, h) do { _Pragma("unroll") for (int m = 0; m < 4; ++m) _Pragma("unroll") for (int k = 0; k < 2; ++k) dst[m][k] = *(const LAS bf16x8*)(lds + PG8_SA(b, h) + aoff + m * 2048 + k * 1024); } while (0)
; #define PG8_LDB(dst, b, h) do { _Pragma("unroll") for (int n = 0; n < 2; ++n) _Pragma("unroll") for (int k = 0; k < 2; ++k) dst[n][k] = *(const LAS bf16x8*)(lds + PG8_SB(b, h) + boff + n * 2048 + k * 1024); } while (0)
; #define PG8_MMA(ai, bj, At, Bt) do { __builtin_amdgcn_s_setprio(1); _Pragma("unroll") for (int m = 0; m < 4; ++m) _Pragma("unroll") for (int n = 0; n < 2; ++n) _Pragma("unroll") for (int k = 0; k < 2; ++k) \
;         acc[ai][bj][m][n] = __builtin_amdgcn_mfma_f32_16x16x32_bf16(Bt[n][k], At[m][k], acc[ai][bj][m][n], 0, 0, 0); __builtin_amdgcn_s_setprio(0); } while (0)
; #define PG8_WAIT_V(n) asm volatile("s_waitcnt vmcnt(" #n ")" ::: "memory")
; #define PG8_WAIT_L(n) asm volatile("s_waitcnt lgkmcnt(" #n ")" ::: "memory")
; #define PG8_BAR __builtin_amdgcn_s_barrier()
; #define PG8_SCHED __builtin_amdgcn_sched_barrier(0)
; template <class Epi, class Sched, bool ALIGN_EPI>
; __device__ __forceinline__ void gemm_phase(LAS unsigned char* lds, const Gemm g, const Sched& S, const Epi& E) {
;     ...
;             PG8_LDB(B0, 0, 0); PG8_LDB(B1, 0, 1); PG8_SCHED; PG8_LDA(At, 0, 0); PG8_STAGE(PG8_SA(1, 1), a1 + hstepA, voffA);
;             PG8_WAIT_V(8); PG8_WAIT_L(0); PG8_BAR; PG8_MMA(0, 0, At, B0); PG8_MMA(0, 1, At, B1); PG8_BAR; PG8_SCHED;
;             PG8_LDA(At, 0, 1); PG8_STAGE(PG8_SB(0, 0), b2, voffB); PG8_STAGE(PG8_SB(0, 1), b2 + hstepB, voffB); PG8_STAGE(PG8_SA(0, 0), a2, voffA);
;             PG8_WAIT_V(8); PG8_WAIT_L(0); PG8_BAR; PG8_MMA(1, 0, At, B0); PG8_MMA(1, 1, At, B1); PG8_BAR; PG8_SCHED;
.LBB0_805:
	s_add_u32 s48, s34, s40
	s_addc_u32 s49, s35, s41
	s_add_u32 s44, s48, 0x100
	s_addc_u32 s45, s49, 0
	s_and_b64 s[42:43], s[38:39], exec
	s_cselect_b32 s45, s3, s45
	s_cselect_b32 s44, s17, s44
	s_add_u32 s40, s30, s40
	s_addc_u32 s41, s31, s41
	s_add_u32 s42, s40, 0x100
	s_addc_u32 s43, s41, 0
	s_add_u32 s40, s44, 0x80
	s_addc_u32 s41, s45, 0
	ds_read_b128 v[130:133], v151
	s_waitcnt vmcnt(7)
	ds_read_b128 v[134:137], v151 offset:1024
	ds_read_b128 v[156:159], v151 offset:2048
	s_waitcnt vmcnt(0)
	ds_read_b128 v[160:163], v151 offset:3072
	ds_read_b128 v[164:167], v152
	ds_read_b128 v[168:171], v152 offset:1024
	ds_read_b128 v[172:175], v152 offset:2048
	ds_read_b128 v[180:183], v152 offset:3072
	s_and_b64 s[38:39], s[38:39], exec
	s_cselect_b32 s47, s15, s43
	s_cselect_b32 s46, s72, s42
	s_add_u32 s52, s48, 0x40080
	s_addc_u32 s53, s49, 0
	s_add_u32 s48, s46, 0x10000
	s_addc_u32 s49, s47, 0
	s_add_u32 s42, s44, 0x40000
	s_addc_u32 s43, s45, 0
	s_add_u32 s38, s46, 0x80
	s_addc_u32 s39, s47, 0
	s_add_u32 s50, s46, 0x10080
	s_addc_u32 s51, s47, 0
	ds_read_b128 v[184:187], v153
	ds_read_b128 v[188:191], v153 offset:1024
	ds_read_b128 v[192:195], v153 offset:2048
	ds_read_b128 v[196:199], v153 offset:3072
	ds_read_b128 v[200:203], v153 offset:4096
	ds_read_b128 v[204:207], v153 offset:5120
	ds_read_b128 v[208:211], v153 offset:6144
	ds_read_b128 v[212:215], v153 offset:7168
	s_mov_b32 m0, s70
	s_nop 0
	global_load_lds_dwordx4 v144, s[52:53]
	s_nop 0
	s_mov_b32 m0, s71
	s_nop 0
	global_load_lds_dwordx4 v146, s[52:53]
	s_waitcnt vmcnt(8)
	s_waitcnt lgkmcnt(0)
	s_barrier
	v_mfma_f32_16x16x32_bf16 v[126:129], v[130:133], v[184:187], v[126:129]
	v_mfma_f32_16x16x32_bf16 v[122:125], v[156:159], v[184:187], v[122:125]
	v_mfma_f32_16x16x32_bf16 v[118:121], v[130:133], v[192:195], v[118:121]
	v_mfma_f32_16x16x32_bf16 v[114:117], v[156:159], v[192:195], v[114:117]
	v_mfma_f32_16x16x32_bf16 v[110:113], v[130:133], v[200:203], v[110:113]
	v_mfma_f32_16x16x32_bf16 v[106:109], v[156:159], v[200:203], v[106:109]
	v_mfma_f32_16x16x32_bf16 v[102:105], v[130:133], v[208:211], v[102:105]
	v_mfma_f32_16x16x32_bf16 v[98:101], v[156:159], v[208:211], v[98:101]
	v_mfma_f32_16x16x32_bf16 v[126:129], v[134:137], v[188:191], v[126:129]
	v_mfma_f32_16x16x32_bf16 v[122:125], v[160:163], v[188:191], v[122:125]
	v_mfma_f32_16x16x32_bf16 v[118:121], v[134:137], v[196:199], v[118:121]
	v_mfma_f32_16x16x32_bf16 v[114:117], v[160:163], v[196:199], v[114:117]
	v_mfma_f32_16x16x32_bf16 v[110:113], v[134:137], v[204:207], v[110:113]
	v_mfma_f32_16x16x32_bf16 v[106:109], v[160:163], v[204:207], v[106:109]
	v_mfma_f32_16x16x32_bf16 v[102:105], v[134:137], v[212:215], v[102:105]
	v_mfma_f32_16x16x32_bf16 v[98:101], v[160:163], v[212:215], v[98:101]
	v_mfma_f32_16x16x32_bf16 v[70:73], v[164:167], v[184:187], v[70:73]
	v_mfma_f32_16x16x32_bf16 v[66:69], v[172:175], v[184:187], v[66:69]
	v_mfma_f32_16x16x32_bf16 v[58:61], v[164:167], v[192:195], v[58:61]
	v_mfma_f32_16x16x32_bf16 v[50:53], v[172:175], v[192:195], v[50:53]
	v_mfma_f32_16x16x32_bf16 v[46:49], v[164:167], v[200:203], v[46:49]
	v_mfma_f32_16x16x32_bf16 v[42:45], v[172:175], v[200:203], v[42:45]
	v_mfma_f32_16x16x32_bf16 v[38:41], v[164:167], v[208:211], v[38:41]
	v_mfma_f32_16x16x32_bf16 v[34:37], v[172:175], v[208:211], v[34:37]
	v_mfma_f32_16x16x32_bf16 v[70:73], v[168:171], v[188:191], v[70:73]
	v_mfma_f32_16x16x32_bf16 v[66:69], v[180:183], v[188:191], v[66:69]
	v_mfma_f32_16x16x32_bf16 v[58:61], v[168:171], v[196:199], v[58:61]
	v_mfma_f32_16x16x32_bf16 v[50:53], v[180:183], v[196:199], v[50:53]
	v_mfma_f32_16x16x32_bf16 v[46:49], v[168:171], v[204:207], v[46:49]
	v_mfma_f32_16x16x32_bf16 v[42:45], v[180:183], v[204:207], v[42:45]
	v_mfma_f32_16x16x32_bf16 v[38:41], v[168:171], v[212:215], v[38:41]
	v_mfma_f32_16x16x32_bf16 v[34:37], v[180:183], v[212:215], v[34:37]
	s_barrier
	ds_read_b128 v[184:187], v153 offset:16384
	ds_read_b128 v[188:191], v153 offset:17408
	ds_read_b128 v[192:195], v153 offset:18432
	ds_read_b128 v[196:199], v153 offset:19456
	ds_read_b128 v[200:203], v153 offset:20480
	ds_read_b128 v[204:207], v153 offset:21504
	ds_read_b128 v[208:211], v153 offset:22528
	ds_read_b128 v[212:215], v153 offset:23552
	s_mov_b32 m0, s29
	s_nop 0
	global_load_lds_dwordx4 v145, s[46:47]
	s_nop 0
	s_mov_b32 m0, s57
	s_nop 0
	global_load_lds_dwordx4 v147, s[46:47]
	s_mov_b32 m0, s58
	s_nop 0
	global_load_lds_dwordx4 v145, s[48:49]
	s_nop 0
	s_mov_b32 m0, s59
	s_nop 0
	global_load_lds_dwordx4 v147, s[48:49]
	s_nop 0
	s_mov_b32 m0, s56
	s_nop 0
	global_load_lds_dwordx4 v144, s[44:45]
	s_nop 0
	s_mov_b32 m0, s61
	s_nop 0
	global_load_lds_dwordx4 v146, s[44:45]
	s_waitcnt vmcnt(8)
	s_waitcnt lgkmcnt(0)
	s_barrier
; #define PG8_STAGE(bufoff, gbase, voff) do { _Pragma("unroll") for (int _i = 0; _i < 2; ++_i) { unsigned keep_; \
;         asm volatile("s_mov_b32 %0, m0\n\ts_mov_b32 m0, %3\n\ts_nop 0\n\tglobal_load_lds_dwordx4 %1, %2\n\ts_mov_b32 m0, %0" \
;             : "=&s"(keep_) : "v"((voff)[_i]), "s"((const void*)(gbase)), "s"(ldsb0 + (unsigned)(bufoff) + (unsigned)(_i * 8192)) : "memory"); } } while (0)
; #define PG8_LDA(dst, b, h) do { _Pragma("unroll") for (int m = 0; m < 4; ++m) _Pragma("unroll") for (int k = 0; k < 2; ++k) dst[m][k] = *(const LAS bf16x8*)(lds + PG8_SA(b, h) + aoff + m * 2048 + k * 1024); } while (0)
; #define PG8_LDB(dst, b, h) do { _Pragma("unroll") for (int n = 0; n < 2; ++n) _Pragma("unroll") for (int k = 0; k < 2; ++k) dst[n][k] = *(const LAS bf16x8*)(lds + PG8_SB(b, h) + boff + n * 2048 + k * 1024); } while (0)
; #define PG8_MMA(ai, bj, At, Bt) do { __builtin_amdgcn_s_setprio(1); _Pragma("unroll") for (int m = 0; m < 4; ++m) _Pragma("unroll") for (int n = 0; n < 2; ++n) _Pragma("unroll") for (int k = 0; k < 2; ++k) \
;         acc[ai][bj][m][n] = __builtin_amdgcn_mfma_f32_16x16x32_bf16(Bt[n][k], At[m][k], acc[ai][bj][m][n], 0, 0, 0); __builtin_amdgcn_s_setprio(0); } while (0)
; #define PG8_WAIT_V(n) asm volatile("s_waitcnt vmcnt(" #n ")" ::: "memory")
; #define PG8_WAIT_L(n) asm volatile("s_waitcnt lgkmcnt(" #n ")" ::: "memory")
; #define PG8_BAR __builtin_amdgcn_s_barrier()
; #define PG8_SCHED __builtin_amdgcn_sched_barrier(0)
; template <class Epi, class Sched, bool ALIGN_EPI>
; __device__ __forceinline__ void gemm_phase(LAS unsigned char* lds, const Gemm g, const Sched& S, const Epi& E) {
;     ...
;             PG8_WAIT_V(8); PG8_WAIT_L(0); PG8_BAR; PG8_MMA(1, 0, At, B0); PG8_MMA(1, 1, At, B1); PG8_BAR; PG8_SCHED;
;             PG8_LDB(B0, 1, 0); PG8_LDB(B1, 1, 1); PG8_SCHED; PG8_LDA(At, 1, 0); PG8_STAGE(PG8_SA(0, 1), a2 + hstepA, voffA);
;             PG8_WAIT_V(8); PG8_WAIT_L(0); PG8_BAR; PG8_MMA(0, 0, At, B0); PG8_MMA(0, 1, At, B1); PG8_BAR; PG8_SCHED;
	v_mfma_f32_16x16x32_bf16 v[94:97], v[130:133], v[184:187], v[94:97]
	v_mfma_f32_16x16x32_bf16 v[90:93], v[156:159], v[184:187], v[90:93]
	v_mfma_f32_16x16x32_bf16 v[86:89], v[130:133], v[192:195], v[86:89]
	v_mfma_f32_16x16x32_bf16 v[82:85], v[156:159], v[192:195], v[82:85]
	v_mfma_f32_16x16x32_bf16 v[78:81], v[130:133], v[200:203], v[78:81]
	v_mfma_f32_16x16x32_bf16 v[74:77], v[156:159], v[200:203], v[74:77]
	v_mfma_f32_16x16x32_bf16 v[62:65], v[130:133], v[208:211], v[62:65]
	v_mfma_f32_16x16x32_bf16 v[54:57], v[156:159], v[208:211], v[54:57]
	v_mfma_f32_16x16x32_bf16 v[94:97], v[134:137], v[188:191], v[94:97]
	v_mfma_f32_16x16x32_bf16 v[90:93], v[160:163], v[188:191], v[90:93]
	v_mfma_f32_16x16x32_bf16 v[86:89], v[134:137], v[196:199], v[86:89]
	v_mfma_f32_16x16x32_bf16 v[82:85], v[160:163], v[196:199], v[82:85]
	v_mfma_f32_16x16x32_bf16 v[78:81], v[134:137], v[204:207], v[78:81]
	v_mfma_f32_16x16x32_bf16 v[74:77], v[160:163], v[204:207], v[74:77]
	v_mfma_f32_16x16x32_bf16 v[62:65], v[134:137], v[212:215], v[62:65]
	v_mfma_f32_16x16x32_bf16 v[54:57], v[160:163], v[212:215], v[54:57]
	v_mfma_f32_16x16x32_bf16 v[30:33], v[164:167], v[184:187], v[30:33]
	v_mfma_f32_16x16x32_bf16 v[26:29], v[172:175], v[184:187], v[26:29]
	v_mfma_f32_16x16x32_bf16 v[22:25], v[164:167], v[192:195], v[22:25]
	v_mfma_f32_16x16x32_bf16 v[18:21], v[172:175], v[192:195], v[18:21]
	v_mfma_f32_16x16x32_bf16 v[14:17], v[164:167], v[200:203], v[14:17]
	v_mfma_f32_16x16x32_bf16 v[10:13], v[172:175], v[200:203], v[10:13]
	v_mfma_f32_16x16x32_bf16 v[6:9], v[164:167], v[208:211], v[6:9]
	v_mfma_f32_16x16x32_bf16 v[2:5], v[172:175], v[208:211], v[2:5]
	v_mfma_f32_16x16x32_bf16 v[30:33], v[168:171], v[188:191], v[30:33]
	v_mfma_f32_16x16x32_bf16 v[26:29], v[180:183], v[188:191], v[26:29]
	v_mfma_f32_16x16x32_bf16 v[22:25], v[168:171], v[196:199], v[22:25]
	v_mfma_f32_16x16x32_bf16 v[18:21], v[180:183], v[196:199], v[18:21]
	v_mfma_f32_16x16x32_bf16 v[14:17], v[168:171], v[204:207], v[14:17]
	v_mfma_f32_16x16x32_bf16 v[10:13], v[180:183], v[204:207], v[10:13]
	v_mfma_f32_16x16x32_bf16 v[6:9], v[168:171], v[212:215], v[6:9]
	v_mfma_f32_16x16x32_bf16 v[2:5], v[180:183], v[212:215], v[2:5]
	s_barrier
	ds_read_b128 v[130:133], v154
	ds_read_b128 v[134:137], v154 offset:1024
	ds_read_b128 v[156:159], v154 offset:2048
	ds_read_b128 v[160:163], v154 offset:3072
	ds_read_b128 v[164:167], v155
	ds_read_b128 v[168:171], v155 offset:1024
	ds_read_b128 v[172:175], v155 offset:2048
	ds_read_b128 v[180:183], v155 offset:3072
	ds_read_b128 v[184:187], v153 offset:32768
	ds_read_b128 v[188:191], v153 offset:33792
	ds_read_b128 v[192:195], v153 offset:34816
	ds_read_b128 v[196:199], v153 offset:35840
	ds_read_b128 v[200:203], v153 offset:36864
	ds_read_b128 v[204:207], v153 offset:37888
	ds_read_b128 v[208:211], v153 offset:38912
	ds_read_b128 v[212:215], v153 offset:39936
	s_mov_b32 m0, s62
	s_nop 0
	global_load_lds_dwordx4 v144, s[42:43]
	s_nop 0
	s_mov_b32 m0, s63
	s_nop 0
	global_load_lds_dwordx4 v146, s[42:43]
	s_waitcnt vmcnt(8)
	s_waitcnt lgkmcnt(0)
	s_barrier
	v_mfma_f32_16x16x32_bf16 v[126:129], v[130:133], v[184:187], v[126:129]
	v_mfma_f32_16x16x32_bf16 v[122:125], v[156:159], v[184:187], v[122:125]
	v_mfma_f32_16x16x32_bf16 v[118:121], v[130:133], v[192:195], v[118:121]
	v_mfma_f32_16x16x32_bf16 v[114:117], v[156:159], v[192:195], v[114:117]
	v_mfma_f32_16x16x32_bf16 v[110:113], v[130:133], v[200:203], v[110:113]
	v_mfma_f32_16x16x32_bf16 v[106:109], v[156:159], v[200:203], v[106:109]
	v_mfma_f32_16x16x32_bf16 v[102:105], v[130:133], v[208:211], v[102:105]
	v_mfma_f32_16x16x32_bf16 v[98:101], v[156:159], v[208:211], v[98:101]
	v_mfma_f32_16x16x32_bf16 v[126:129], v[134:137], v[188:191], v[126:129]
	v_mfma_f32_16x16x32_bf16 v[122:125], v[160:163], v[188:191], v[122:125]
	v_mfma_f32_16x16x32_bf16 v[118:121], v[134:137], v[196:199], v[118:121]
	v_mfma_f32_16x16x32_bf16 v[114:117], v[160:163], v[196:199], v[114:117]
	v_mfma_f32_16x16x32_bf16 v[110:113], v[134:137], v[204:207], v[110:113]
	v_mfma_f32_16x16x32_bf16 v[106:109], v[160:163], v[204:207], v[106:109]
	v_mfma_f32_16x16x32_bf16 v[102:105], v[134:137], v[212:215], v[102:105]
	v_mfma_f32_16x16x32_bf16 v[98:101], v[160:163], v[212:215], v[98:101]
	v_mfma_f32_16x16x32_bf16 v[70:73], v[164:167], v[184:187], v[70:73]
	v_mfma_f32_16x16x32_bf16 v[66:69], v[172:175], v[184:187], v[66:69]
	v_mfma_f32_16x16x32_bf16 v[58:61], v[164:167], v[192:195], v[58:61]
	v_mfma_f32_16x16x32_bf16 v[50:53], v[172:175], v[192:195], v[50:53]
	v_mfma_f32_16x16x32_bf16 v[46:49], v[164:167], v[200:203], v[46:49]
	v_mfma_f32_16x16x32_bf16 v[42:45], v[172:175], v[200:203], v[42:45]
	v_mfma_f32_16x16x32_bf16 v[38:41], v[164:167], v[208:211], v[38:41]
	v_mfma_f32_16x16x32_bf16 v[34:37], v[172:175], v[208:211], v[34:37]
	v_mfma_f32_16x16x32_bf16 v[70:73], v[168:171], v[188:191], v[70:73]
	v_mfma_f32_16x16x32_bf16 v[66:69], v[180:183], v[188:191], v[66:69]
	v_mfma_f32_16x16x32_bf16 v[58:61], v[168:171], v[196:199], v[58:61]
	v_mfma_f32_16x16x32_bf16 v[50:53], v[180:183], v[196:199], v[50:53]
	v_mfma_f32_16x16x32_bf16 v[46:49], v[168:171], v[204:207], v[46:49]
	v_mfma_f32_16x16x32_bf16 v[42:45], v[180:183], v[204:207], v[42:45]
	v_mfma_f32_16x16x32_bf16 v[38:41], v[168:171], v[212:215], v[38:41]
	v_mfma_f32_16x16x32_bf16 v[34:37], v[180:183], v[212:215], v[34:37]
	s_barrier
; #define PG8_STAGE(bufoff, gbase, voff) do { _Pragma("unroll") for (int _i = 0; _i < 2; ++_i) { unsigned keep_; \
;         asm volatile("s_mov_b32 %0, m0\n\ts_mov_b32 m0, %3\n\ts_nop 0\n\tglobal_load_lds_dwordx4 %1, %2\n\ts_mov_b32 m0, %0" \
;             : "=&s"(keep_) : "v"((voff)[_i]), "s"((const void*)(gbase)), "s"(ldsb0 + (unsigned)(bufoff) + (unsigned)(_i * 8192)) : "memory"); } } while (0)
; #define PG8_LDA(dst, b, h) do { _Pragma("unroll") for (int m = 0; m < 4; ++m) _Pragma("unroll") for (int k = 0; k < 2; ++k) dst[m][k] = *(const LAS bf16x8*)(lds + PG8_SA(b, h) + aoff + m * 2048 + k * 1024); } while (0)
; #define PG8_MMA(ai, bj, At, Bt) do { __builtin_amdgcn_s_setprio(1); _Pragma("unroll") for (int m = 0; m < 4; ++m) _Pragma("unroll") for (int n = 0; n < 2; ++n) _Pragma("unroll") for (int k = 0; k < 2; ++k) \
;         acc[ai][bj][m][n] = __builtin_amdgcn_mfma_f32_16x16x32_bf16(Bt[n][k], At[m][k], acc[ai][bj][m][n], 0, 0, 0); __builtin_amdgcn_s_setprio(0); } while (0)
; #define PG8_WAIT_V(n) asm volatile("s_waitcnt vmcnt(" #n ")" ::: "memory")
; #define PG8_WAIT_L(n) asm volatile("s_waitcnt lgkmcnt(" #n ")" ::: "memory")
; #define PG8_BAR __builtin_amdgcn_s_barrier()
; #define PG8_SCHED __builtin_amdgcn_sched_barrier(0)
; template <class Epi, class Sched, bool ALIGN_EPI>
; __device__ __forceinline__ void gemm_phase(LAS unsigned char* lds, const Gemm g, const Sched& S, const Epi& E) {
;     ...
;             PG8_LDA(At, 1, 1); PG8_STAGE(PG8_SB(1, 0), b3, voffB); PG8_STAGE(PG8_SB(1, 1), b3 + hstepB, voffB); PG8_STAGE(PG8_SA(1, 0), a3, voffA);
;             PG8_WAIT_V(8); PG8_WAIT_L(0); PG8_BAR; PG8_MMA(1, 0, At, B0); PG8_MMA(1, 1, At, B1); PG8_BAR; PG8_SCHED;
	ds_read_b128 v[184:187], v153 offset:49152
	ds_read_b128 v[188:191], v153 offset:50176
	ds_read_b128 v[192:195], v153 offset:51200
	ds_read_b128 v[196:199], v153 offset:52224
	ds_read_b128 v[200:203], v153 offset:53248
	ds_read_b128 v[204:207], v153 offset:54272
	ds_read_b128 v[208:211], v153 offset:55296
	ds_read_b128 v[212:215], v153 offset:56320
	s_mov_b32 m0, s64
	s_nop 0
	global_load_lds_dwordx4 v145, s[38:39]
	s_nop 0
	s_mov_b32 m0, s65
	s_nop 0
	global_load_lds_dwordx4 v147, s[38:39]
	s_mov_b32 m0, s68
	s_nop 0
	global_load_lds_dwordx4 v145, s[50:51]
	s_nop 0
	s_mov_b32 m0, s69
	s_nop 0
	global_load_lds_dwordx4 v147, s[50:51]
	s_nop 0
	s_mov_b32 m0, s66
	s_nop 0
	global_load_lds_dwordx4 v144, s[40:41]
	s_nop 0
	s_mov_b32 m0, s67
	s_nop 0
	global_load_lds_dwordx4 v146, s[40:41]
	s_waitcnt vmcnt(8)
	s_waitcnt lgkmcnt(0)
	s_barrier
	v_mfma_f32_16x16x32_bf16 v[94:97], v[130:133], v[184:187], v[94:97]
	v_mfma_f32_16x16x32_bf16 v[90:93], v[156:159], v[184:187], v[90:93]
	v_mfma_f32_16x16x32_bf16 v[86:89], v[130:133], v[192:195], v[86:89]
	v_mfma_f32_16x16x32_bf16 v[82:85], v[156:159], v[192:195], v[82:85]
	v_mfma_f32_16x16x32_bf16 v[78:81], v[130:133], v[200:203], v[78:81]
	v_mfma_f32_16x16x32_bf16 v[74:77], v[156:159], v[200:203], v[74:77]
	v_mfma_f32_16x16x32_bf16 v[62:65], v[130:133], v[208:211], v[62:65]
	v_mfma_f32_16x16x32_bf16 v[54:57], v[156:159], v[208:211], v[54:57]
	v_mfma_f32_16x16x32_bf16 v[94:97], v[134:137], v[188:191], v[94:97]
	v_mfma_f32_16x16x32_bf16 v[90:93], v[160:163], v[188:191], v[90:93]
	v_mfma_f32_16x16x32_bf16 v[86:89], v[134:137], v[196:199], v[86:89]
	v_mfma_f32_16x16x32_bf16 v[82:85], v[160:163], v[196:199], v[82:85]
	v_mfma_f32_16x16x32_bf16 v[78:81], v[134:137], v[204:207], v[78:81]
	v_mfma_f32_16x16x32_bf16 v[74:77], v[160:163], v[204:207], v[74:77]
	v_mfma_f32_16x16x32_bf16 v[62:65], v[134:137], v[212:215], v[62:65]
	v_mfma_f32_16x16x32_bf16 v[54:57], v[160:163], v[212:215], v[54:57]
	v_mfma_f32_16x16x32_bf16 v[30:33], v[164:167], v[184:187], v[30:33]
	v_mfma_f32_16x16x32_bf16 v[26:29], v[172:175], v[184:187], v[26:29]
	v_mfma_f32_16x16x32_bf16 v[22:25], v[164:167], v[192:195], v[22:25]
	v_mfma_f32_16x16x32_bf16 v[18:21], v[172:175], v[192:195], v[18:21]
	v_mfma_f32_16x16x32_bf16 v[14:17], v[164:167], v[200:203], v[14:17]
	v_mfma_f32_16x16x32_bf16 v[10:13], v[172:175], v[200:203], v[10:13]
	v_mfma_f32_16x16x32_bf16 v[6:9], v[164:167], v[208:211], v[6:9]
	v_mfma_f32_16x16x32_bf16 v[2:5], v[172:175], v[208:211], v[2:5]
	v_mfma_f32_16x16x32_bf16 v[30:33], v[168:171], v[188:191], v[30:33]
	v_mfma_f32_16x16x32_bf16 v[26:29], v[180:183], v[188:191], v[26:29]
	v_mfma_f32_16x16x32_bf16 v[22:25], v[168:171], v[196:199], v[22:25]
	v_mfma_f32_16x16x32_bf16 v[18:21], v[180:183], v[196:199], v[18:21]
	v_mfma_f32_16x16x32_bf16 v[14:17], v[168:171], v[204:207], v[14:17]
	v_mfma_f32_16x16x32_bf16 v[10:13], v[180:183], v[204:207], v[10:13]
	v_mfma_f32_16x16x32_bf16 v[6:9], v[168:171], v[212:215], v[6:9]
	v_mfma_f32_16x16x32_bf16 v[2:5], v[180:183], v[212:215], v[2:5]
	s_barrier
	s_andn2_b64 vcc, exec, s[36:37]
	s_mov_b64 s[38:39], -1
	s_mov_b64 s[36:37], 0
	s_mov_b64 s[40:41], 0x100
	s_cbranch_vccz .LBB0_805
	s_and_b64 vcc, exec, s[12:13]
	s_cbranch_vccz .LBB0_808
	s_barrier

.LBB0_1120:
	s_or_b64 exec, exec, s[4:5]
	s_mov_b64 s[10:11], s[0:1]
	s_mov_b64 s[12:13], s[0:1]
	s_mov_b64 s[4:5], s[0:1]
	s_mov_b64 s[2:3], s[0:1]
	s_waitcnt lgkmcnt(0)
	s_barrier
	v_readlane_b32 s99, v242, 0
	s_nop 1
	s_cmp_gt_u32 s99, 3
	s_cbranch_scc0 .Lsp_3
	s_setprio 1

; #define PG8_STAGE(bufoff, gbase, voff) do { _Pragma("unroll") for (int _i = 0; _i < 2; ++_i) { unsigned keep_; \
;         asm volatile("s_mov_b32 %0, m0\n\ts_mov_b32 m0, %3\n\ts_nop 0\n\tglobal_load_lds_dwordx4 %1, %2\n\ts_mov_b32 m0, %0" \
;             : "=&s"(keep_) : "v"((voff)[_i]), "s"((const void*)(gbase)), "s"(ldsb0 + (unsigned)(bufoff) + (unsigned)(_i * 8192)) : "memory"); } } while (0)
; #define PG8_LDA(dst, b, h) do { _Pragma("unroll") for (int m = 0; m < 4; ++m) _Pragma("unroll") for (int k = 0; k < 2; ++k) dst[m][k] = *(const LAS bf16x8*)(lds + PG8_SA(b, h) + aoff + m * 2048 + k * 1024); } while (0)
; #define PG8_LDB(dst, b, h) do { _Pragma("unroll") for (int n = 0; n < 2; ++n) _Pragma("unroll") for (int k = 0; k < 2; ++k) dst[n][k] = *(const LAS bf16x8*)(lds + PG8_SB(b, h) + boff + n * 2048 + k * 1024); } while (0)
; #define PG8_MMA(ai, bj, At, Bt) do { __builtin_amdgcn_s_setprio(1); _Pragma("unroll") for (int m = 0; m < 4; ++m) _Pragma("unroll") for (int n = 0; n < 2; ++n) _Pragma("unroll") for (int k = 0; k < 2; ++k) \
;         acc[ai][bj][m][n] = __builtin_amdgcn_mfma_f32_16x16x32_bf16(Bt[n][k], At[m][k], acc[ai][bj][m][n], 0, 0, 0); __builtin_amdgcn_s_setprio(0); } while (0)
; #define PG8_WAIT_V(n) asm volatile("s_waitcnt vmcnt(" #n ")" ::: "memory")
; #define PG8_WAIT_L(n) asm volatile("s_waitcnt lgkmcnt(" #n ")" ::: "memory")
; #define PG8_BAR __builtin_amdgcn_s_barrier()
; #define PG8_SCHED __builtin_amdgcn_sched_barrier(0)
; template <class Epi, class Sched, bool ALIGN_EPI>
; __device__ __forceinline__ void gemm_phase(LAS unsigned char* lds, const Gemm g, const Sched& S, const Epi& E) {
;     ...
;             PG8_LDB(B0, 0, 0); PG8_LDB(B1, 0, 1); PG8_SCHED; PG8_LDA(At, 0, 0); PG8_STAGE(PG8_SA(1, 1), a1 + hstepA, voffA);
;             PG8_WAIT_V(8); PG8_WAIT_L(0); PG8_BAR; PG8_MMA(0, 0, At, B0); PG8_MMA(0, 1, At, B1); PG8_BAR; PG8_SCHED;
;             PG8_LDA(At, 0, 1); PG8_STAGE(PG8_SB(0, 0), b2, voffB); PG8_STAGE(PG8_SB(0, 1), b2 + hstepB, voffB); PG8_STAGE(PG8_SA(0, 0), a2, voffA);
;             PG8_WAIT_V(8); PG8_WAIT_L(0); PG8_BAR; PG8_MMA(1, 0, At, B0); PG8_MMA(1, 1, At, B1); PG8_BAR; PG8_SCHED;
.LBB0_1137:
	ds_read_b128 v[110:113], v206
	ds_read_b128 v[126:129], v206 offset:1024
	ds_read_b128 v[130:133], v206 offset:2048
	ds_read_b128 v[142:145], v206 offset:3072
	ds_read_b128 v[146:149], v207
	ds_read_b128 v[150:153], v207 offset:1024
	ds_read_b128 v[154:157], v207 offset:2048
	ds_read_b128 v[158:161], v207 offset:3072
	s_cmp_eq_u32 s63, 28
	s_cselect_b32 s40, s5, s19
	s_cselect_b32 s41, s3, s27
	s_cselect_b32 s38, s7, s61
	s_cselect_b32 s39, s6, s62
	s_add_u32 s36, s40, 0x80
	s_addc_u32 s37, s41, 0
	ds_read_b128 v[162:165], v208
	ds_read_b128 v[166:169], v208 offset:1024
	ds_read_b128 v[170:173], v208 offset:2048
	ds_read_b128 v[174:177], v208 offset:3072
	ds_read_b128 v[188:191], v208 offset:4096
	ds_read_b128 v[192:195], v208 offset:5120
	ds_read_b128 v[196:199], v208 offset:6144
	ds_read_b128 v[212:215], v208 offset:7168
	s_mov_b32 m0, s58
	s_nop 0
	global_load_lds_dwordx4 v179, s[34:35]
	s_nop 0
	s_mov_b32 m0, s59
	s_nop 0
	global_load_lds_dwordx4 v201, s[34:35]
	s_waitcnt vmcnt(8)
	s_waitcnt lgkmcnt(0)
	s_barrier
	v_mfma_f32_16x16x32_bf16 v[138:141], v[110:113], v[162:165], v[138:141]
	v_mfma_f32_16x16x32_bf16 v[134:137], v[130:133], v[162:165], v[134:137]
	v_mfma_f32_16x16x32_bf16 v[114:117], v[110:113], v[170:173], v[114:117]
	v_mfma_f32_16x16x32_bf16 v[106:109], v[130:133], v[170:173], v[106:109]
	v_mfma_f32_16x16x32_bf16 v[94:97], v[110:113], v[188:191], v[94:97]
	v_mfma_f32_16x16x32_bf16 v[90:93], v[130:133], v[188:191], v[90:93]
	v_mfma_f32_16x16x32_bf16 v[78:81], v[110:113], v[196:199], v[78:81]
	v_mfma_f32_16x16x32_bf16 v[74:77], v[130:133], v[196:199], v[74:77]
	v_mfma_f32_16x16x32_bf16 v[138:141], v[126:129], v[166:169], v[138:141]
	v_mfma_f32_16x16x32_bf16 v[134:137], v[142:145], v[166:169], v[134:137]
	v_mfma_f32_16x16x32_bf16 v[114:117], v[126:129], v[174:177], v[114:117]
	v_mfma_f32_16x16x32_bf16 v[106:109], v[142:145], v[174:177], v[106:109]
	v_mfma_f32_16x16x32_bf16 v[94:97], v[126:129], v[192:195], v[94:97]
	v_mfma_f32_16x16x32_bf16 v[90:93], v[142:145], v[192:195], v[90:93]
	v_mfma_f32_16x16x32_bf16 v[78:81], v[126:129], v[212:215], v[78:81]
	v_mfma_f32_16x16x32_bf16 v[74:77], v[142:145], v[212:215], v[74:77]
	v_mfma_f32_16x16x32_bf16 v[122:125], v[146:149], v[162:165], v[122:125]
	v_mfma_f32_16x16x32_bf16 v[118:121], v[154:157], v[162:165], v[118:121]
	v_mfma_f32_16x16x32_bf16 v[102:105], v[146:149], v[170:173], v[102:105]
	v_mfma_f32_16x16x32_bf16 v[98:101], v[154:157], v[170:173], v[98:101]
	v_mfma_f32_16x16x32_bf16 v[86:89], v[146:149], v[188:191], v[86:89]
	v_mfma_f32_16x16x32_bf16 v[82:85], v[154:157], v[188:191], v[82:85]
	v_mfma_f32_16x16x32_bf16 v[70:73], v[146:149], v[196:199], v[70:73]
	v_mfma_f32_16x16x32_bf16 v[66:69], v[154:157], v[196:199], v[66:69]
	v_mfma_f32_16x16x32_bf16 v[122:125], v[150:153], v[166:169], v[122:125]
	v_mfma_f32_16x16x32_bf16 v[118:121], v[158:161], v[166:169], v[118:121]
	v_mfma_f32_16x16x32_bf16 v[102:105], v[150:153], v[174:177], v[102:105]
	v_mfma_f32_16x16x32_bf16 v[98:101], v[158:161], v[174:177], v[98:101]
	v_mfma_f32_16x16x32_bf16 v[86:89], v[150:153], v[192:195], v[86:89]
	v_mfma_f32_16x16x32_bf16 v[82:85], v[158:161], v[192:195], v[82:85]
	v_mfma_f32_16x16x32_bf16 v[70:73], v[150:153], v[212:215], v[70:73]
	v_mfma_f32_16x16x32_bf16 v[66:69], v[158:161], v[212:215], v[66:69]
	s_barrier
	ds_read_b128 v[162:165], v208 offset:16384
	ds_read_b128 v[166:169], v208 offset:17408
	ds_read_b128 v[170:173], v208 offset:18432
	ds_read_b128 v[174:177], v208 offset:19456
	ds_read_b128 v[188:191], v208 offset:20480
	ds_read_b128 v[192:195], v208 offset:21504
	ds_read_b128 v[196:199], v208 offset:22528
	ds_read_b128 v[212:215], v208 offset:23552
	s_mov_b32 m0, s45
	s_nop 0
	global_load_lds_dwordx4 v200, s[38:39]
	s_nop 0
	s_mov_b32 m0, s46
	s_nop 0
	global_load_lds_dwordx4 v203, s[38:39]
	s_add_u32 s64, s38, 0x80000
	s_addc_u32 s65, s39, 0
	s_mov_b32 m0, s47
	s_nop 0
	global_load_lds_dwordx4 v200, s[64:65]
	s_nop 0
	s_mov_b32 m0, s48
	s_nop 0
	global_load_lds_dwordx4 v203, s[64:65]
	s_mov_b32 m0, s44
	s_nop 0
	global_load_lds_dwordx4 v179, s[40:41]
	s_nop 0
	s_mov_b32 m0, s49
	s_nop 0
	global_load_lds_dwordx4 v201, s[40:41]
	s_waitcnt vmcnt(8)
	s_waitcnt lgkmcnt(0)
	s_barrier
	v_mfma_f32_16x16x32_bf16 v[62:65], v[110:113], v[162:165], v[62:65]
	v_mfma_f32_16x16x32_bf16 v[58:61], v[130:133], v[162:165], v[58:61]
	v_mfma_f32_16x16x32_bf16 v[46:49], v[110:113], v[170:173], v[46:49]
	v_mfma_f32_16x16x32_bf16 v[42:45], v[130:133], v[170:173], v[42:45]
	v_mfma_f32_16x16x32_bf16 v[30:33], v[110:113], v[188:191], v[30:33]
	v_mfma_f32_16x16x32_bf16 v[26:29], v[130:133], v[188:191], v[26:29]
	v_mfma_f32_16x16x32_bf16 v[14:17], v[110:113], v[196:199], v[14:17]
	v_mfma_f32_16x16x32_bf16 v[10:13], v[130:133], v[196:199], v[10:13]
	v_mfma_f32_16x16x32_bf16 v[62:65], v[126:129], v[166:169], v[62:65]
	v_mfma_f32_16x16x32_bf16 v[58:61], v[142:145], v[166:169], v[58:61]
	v_mfma_f32_16x16x32_bf16 v[46:49], v[126:129], v[174:177], v[46:49]
	v_mfma_f32_16x16x32_bf16 v[42:45], v[142:145], v[174:177], v[42:45]
	v_mfma_f32_16x16x32_bf16 v[30:33], v[126:129], v[192:195], v[30:33]
	v_mfma_f32_16x16x32_bf16 v[26:29], v[142:145], v[192:195], v[26:29]
	v_mfma_f32_16x16x32_bf16 v[14:17], v[126:129], v[212:215], v[14:17]
	v_mfma_f32_16x16x32_bf16 v[10:13], v[142:145], v[212:215], v[10:13]
	v_mfma_f32_16x16x32_bf16 v[54:57], v[146:149], v[162:165], v[54:57]
	v_mfma_f32_16x16x32_bf16 v[50:53], v[154:157], v[162:165], v[50:53]
	v_mfma_f32_16x16x32_bf16 v[38:41], v[146:149], v[170:173], v[38:41]
	v_mfma_f32_16x16x32_bf16 v[34:37], v[154:157], v[170:173], v[34:37]
	v_mfma_f32_16x16x32_bf16 v[22:25], v[146:149], v[188:191], v[22:25]
	v_mfma_f32_16x16x32_bf16 v[18:21], v[154:157], v[188:191], v[18:21]
	v_mfma_f32_16x16x32_bf16 v[6:9], v[146:149], v[196:199], v[6:9]
	v_mfma_f32_16x16x32_bf16 v[2:5], v[154:157], v[196:199], v[2:5]
	v_mfma_f32_16x16x32_bf16 v[54:57], v[150:153], v[166:169], v[54:57]
	v_mfma_f32_16x16x32_bf16 v[50:53], v[158:161], v[166:169], v[50:53]
	v_mfma_f32_16x16x32_bf16 v[38:41], v[150:153], v[174:177], v[38:41]
	v_mfma_f32_16x16x32_bf16 v[34:37], v[158:161], v[174:177], v[34:37]
	v_mfma_f32_16x16x32_bf16 v[22:25], v[150:153], v[192:195], v[22:25]
	v_mfma_f32_16x16x32_bf16 v[18:21], v[158:161], v[192:195], v[18:21]
	v_mfma_f32_16x16x32_bf16 v[6:9], v[150:153], v[212:215], v[6:9]
	v_mfma_f32_16x16x32_bf16 v[2:5], v[158:161], v[212:215], v[2:5]
	s_barrier
; #define PG8_STAGE(bufoff, gbase, voff) do { _Pragma("unroll") for (int _i = 0; _i < 2; ++_i) { unsigned keep_; \
;         asm volatile("s_mov_b32 %0, m0\n\ts_mov_b32 m0, %3\n\ts_nop 0\n\tglobal_load_lds_dwordx4 %1, %2\n\ts_mov_b32 m0, %0" \
;             : "=&s"(keep_) : "v"((voff)[_i]), "s"((const void*)(gbase)), "s"(ldsb0 + (unsigned)(bufoff) + (unsigned)(_i * 8192)) : "memory"); } } while (0)
; #define PG8_LDA(dst, b, h) do { _Pragma("unroll") for (int m = 0; m < 4; ++m) _Pragma("unroll") for (int k = 0; k < 2; ++k) dst[m][k] = *(const LAS bf16x8*)(lds + PG8_SA(b, h) + aoff + m * 2048 + k * 1024); } while (0)
; #define PG8_LDB(dst, b, h) do { _Pragma("unroll") for (int n = 0; n < 2; ++n) _Pragma("unroll") for (int k = 0; k < 2; ++k) dst[n][k] = *(const LAS bf16x8*)(lds + PG8_SB(b, h) + boff + n * 2048 + k * 1024); } while (0)
; #define PG8_MMA(ai, bj, At, Bt) do { __builtin_amdgcn_s_setprio(1); _Pragma("unroll") for (int m = 0; m < 4; ++m) _Pragma("unroll") for (int n = 0; n < 2; ++n) _Pragma("unroll") for (int k = 0; k < 2; ++k) \
;         acc[ai][bj][m][n] = __builtin_amdgcn_mfma_f32_16x16x32_bf16(Bt[n][k], At[m][k], acc[ai][bj][m][n], 0, 0, 0); __builtin_amdgcn_s_setprio(0); } while (0)
; #define PG8_WAIT_V(n) asm volatile("s_waitcnt vmcnt(" #n ")" ::: "memory")
; #define PG8_WAIT_L(n) asm volatile("s_waitcnt lgkmcnt(" #n ")" ::: "memory")
; #define PG8_BAR __builtin_amdgcn_s_barrier()
; #define PG8_SCHED __builtin_amdgcn_sched_barrier(0)
; template <class Epi, class Sched, bool ALIGN_EPI>
; __device__ __forceinline__ void gemm_phase(LAS unsigned char* lds, const Gemm g, const Sched& S, const Epi& E) {
;     ...
;             PG8_LDB(B0, 1, 0); PG8_LDB(B1, 1, 1); PG8_SCHED; PG8_LDA(At, 1, 0); PG8_STAGE(PG8_SA(0, 1), a2 + hstepA, voffA);
;             PG8_WAIT_V(8); PG8_WAIT_L(0); PG8_BAR; PG8_MMA(0, 0, At, B0); PG8_MMA(0, 1, At, B1); PG8_BAR; PG8_SCHED;
;             PG8_LDA(At, 1, 1); PG8_STAGE(PG8_SB(1, 0), b3, voffB); PG8_STAGE(PG8_SB(1, 1), b3 + hstepB, voffB); PG8_STAGE(PG8_SA(1, 0), a3, voffA);
;             PG8_WAIT_V(8); PG8_WAIT_L(0); PG8_BAR; PG8_MMA(1, 0, At, B0); PG8_MMA(1, 1, At, B1); PG8_BAR; PG8_SCHED;
	ds_read_b128 v[110:113], v209
	ds_read_b128 v[126:129], v209 offset:1024
	ds_read_b128 v[130:133], v209 offset:2048
	ds_read_b128 v[142:145], v209 offset:3072
	ds_read_b128 v[146:149], v210
	ds_read_b128 v[150:153], v210 offset:1024
	ds_read_b128 v[154:157], v210 offset:2048
	ds_read_b128 v[158:161], v210 offset:3072
	ds_read_b128 v[162:165], v208 offset:32768
	ds_read_b128 v[166:169], v208 offset:33792
	ds_read_b128 v[170:173], v208 offset:34816
	ds_read_b128 v[174:177], v208 offset:35840
	ds_read_b128 v[188:191], v208 offset:36864
	ds_read_b128 v[192:195], v208 offset:37888
	ds_read_b128 v[196:199], v208 offset:38912
	ds_read_b128 v[212:215], v208 offset:39936
	s_add_u32 s40, s40, 0x80000
	s_addc_u32 s41, s41, 0
	s_mov_b32 m0, s50
	s_nop 0
	global_load_lds_dwordx4 v179, s[40:41]
	s_nop 0
	s_mov_b32 m0, s51
	s_nop 0
	global_load_lds_dwordx4 v201, s[40:41]
	s_waitcnt vmcnt(8)
	s_waitcnt lgkmcnt(0)
	s_barrier
	v_mfma_f32_16x16x32_bf16 v[138:141], v[110:113], v[162:165], v[138:141]
	v_mfma_f32_16x16x32_bf16 v[134:137], v[130:133], v[162:165], v[134:137]
	v_mfma_f32_16x16x32_bf16 v[114:117], v[110:113], v[170:173], v[114:117]
	v_mfma_f32_16x16x32_bf16 v[106:109], v[130:133], v[170:173], v[106:109]
	v_mfma_f32_16x16x32_bf16 v[94:97], v[110:113], v[188:191], v[94:97]
	v_mfma_f32_16x16x32_bf16 v[90:93], v[130:133], v[188:191], v[90:93]
	v_mfma_f32_16x16x32_bf16 v[78:81], v[110:113], v[196:199], v[78:81]
	v_mfma_f32_16x16x32_bf16 v[74:77], v[130:133], v[196:199], v[74:77]
	v_mfma_f32_16x16x32_bf16 v[138:141], v[126:129], v[166:169], v[138:141]
	v_mfma_f32_16x16x32_bf16 v[134:137], v[142:145], v[166:169], v[134:137]
	v_mfma_f32_16x16x32_bf16 v[114:117], v[126:129], v[174:177], v[114:117]
	v_mfma_f32_16x16x32_bf16 v[106:109], v[142:145], v[174:177], v[106:109]
	v_mfma_f32_16x16x32_bf16 v[94:97], v[126:129], v[192:195], v[94:97]
	v_mfma_f32_16x16x32_bf16 v[90:93], v[142:145], v[192:195], v[90:93]
	v_mfma_f32_16x16x32_bf16 v[78:81], v[126:129], v[212:215], v[78:81]
	v_mfma_f32_16x16x32_bf16 v[74:77], v[142:145], v[212:215], v[74:77]
	v_mfma_f32_16x16x32_bf16 v[122:125], v[146:149], v[162:165], v[122:125]
	v_mfma_f32_16x16x32_bf16 v[118:121], v[154:157], v[162:165], v[118:121]
	v_mfma_f32_16x16x32_bf16 v[102:105], v[146:149], v[170:173], v[102:105]
	v_mfma_f32_16x16x32_bf16 v[98:101], v[154:157], v[170:173], v[98:101]
	v_mfma_f32_16x16x32_bf16 v[86:89], v[146:149], v[188:191], v[86:89]
	v_mfma_f32_16x16x32_bf16 v[82:85], v[154:157], v[188:191], v[82:85]
	v_mfma_f32_16x16x32_bf16 v[70:73], v[146:149], v[196:199], v[70:73]
	v_mfma_f32_16x16x32_bf16 v[66:69], v[154:157], v[196:199], v[66:69]
	v_mfma_f32_16x16x32_bf16 v[122:125], v[150:153], v[166:169], v[122:125]
	v_mfma_f32_16x16x32_bf16 v[118:121], v[158:161], v[166:169], v[118:121]
	v_mfma_f32_16x16x32_bf16 v[102:105], v[150:153], v[174:177], v[102:105]
	v_mfma_f32_16x16x32_bf16 v[98:101], v[158:161], v[174:177], v[98:101]
	v_mfma_f32_16x16x32_bf16 v[86:89], v[150:153], v[192:195], v[86:89]
	v_mfma_f32_16x16x32_bf16 v[82:85], v[158:161], v[192:195], v[82:85]
	v_mfma_f32_16x16x32_bf16 v[70:73], v[150:153], v[212:215], v[70:73]
	v_mfma_f32_16x16x32_bf16 v[66:69], v[158:161], v[212:215], v[66:69]
	s_barrier
	ds_read_b128 v[162:165], v208 offset:49152
	ds_read_b128 v[166:169], v208 offset:50176
	ds_read_b128 v[170:173], v208 offset:51200
	ds_read_b128 v[174:177], v208 offset:52224
	ds_read_b128 v[188:191], v208 offset:53248
	ds_read_b128 v[192:195], v208 offset:54272
	ds_read_b128 v[196:199], v208 offset:55296
	ds_read_b128 v[212:215], v208 offset:56320
	s_add_u32 s40, s38, 0x80
	s_addc_u32 s41, s39, 0
	s_mov_b32 m0, s52
	s_nop 0
	global_load_lds_dwordx4 v200, s[40:41]
	s_add_u32 s38, s38, 0x80080
	s_mov_b32 m0, s53
	s_nop 0
	global_load_lds_dwordx4 v203, s[40:41]
	s_addc_u32 s39, s39, 0
	s_mov_b32 m0, s56
	s_nop 0
	global_load_lds_dwordx4 v200, s[38:39]
	s_nop 0
	s_mov_b32 m0, s57
	s_nop 0
	global_load_lds_dwordx4 v203, s[38:39]
	s_mov_b32 m0, s54
	s_nop 0
	global_load_lds_dwordx4 v179, s[36:37]
	s_nop 0
	s_mov_b32 m0, s55
	s_nop 0
	global_load_lds_dwordx4 v201, s[36:37]
	s_waitcnt vmcnt(8)
	s_waitcnt lgkmcnt(0)
	s_barrier
	v_mfma_f32_16x16x32_bf16 v[62:65], v[110:113], v[162:165], v[62:65]
	v_mfma_f32_16x16x32_bf16 v[58:61], v[130:133], v[162:165], v[58:61]
	v_mfma_f32_16x16x32_bf16 v[46:49], v[110:113], v[170:173], v[46:49]
	v_mfma_f32_16x16x32_bf16 v[42:45], v[130:133], v[170:173], v[42:45]
	v_mfma_f32_16x16x32_bf16 v[30:33], v[110:113], v[188:191], v[30:33]
	v_mfma_f32_16x16x32_bf16 v[26:29], v[130:133], v[188:191], v[26:29]
	v_mfma_f32_16x16x32_bf16 v[14:17], v[110:113], v[196:199], v[14:17]
	v_mfma_f32_16x16x32_bf16 v[10:13], v[130:133], v[196:199], v[10:13]
	v_mfma_f32_16x16x32_bf16 v[62:65], v[126:129], v[166:169], v[62:65]
	v_mfma_f32_16x16x32_bf16 v[58:61], v[142:145], v[166:169], v[58:61]
	v_mfma_f32_16x16x32_bf16 v[46:49], v[126:129], v[174:177], v[46:49]
	v_mfma_f32_16x16x32_bf16 v[42:45], v[142:145], v[174:177], v[42:45]
	v_mfma_f32_16x16x32_bf16 v[30:33], v[126:129], v[192:195], v[30:33]
	v_mfma_f32_16x16x32_bf16 v[26:29], v[142:145], v[192:195], v[26:29]
	v_mfma_f32_16x16x32_bf16 v[14:17], v[126:129], v[212:215], v[14:17]
	v_mfma_f32_16x16x32_bf16 v[10:13], v[142:145], v[212:215], v[10:13]
	v_mfma_f32_16x16x32_bf16 v[54:57], v[146:149], v[162:165], v[54:57]
	v_mfma_f32_16x16x32_bf16 v[50:53], v[154:157], v[162:165], v[50:53]
	v_mfma_f32_16x16x32_bf16 v[38:41], v[146:149], v[170:173], v[38:41]
	v_mfma_f32_16x16x32_bf16 v[34:37], v[154:157], v[170:173], v[34:37]
	v_mfma_f32_16x16x32_bf16 v[22:25], v[146:149], v[188:191], v[22:25]
	v_mfma_f32_16x16x32_bf16 v[18:21], v[154:157], v[188:191], v[18:21]
	v_mfma_f32_16x16x32_bf16 v[6:9], v[146:149], v[196:199], v[6:9]
	v_mfma_f32_16x16x32_bf16 v[2:5], v[154:157], v[196:199], v[2:5]
	v_mfma_f32_16x16x32_bf16 v[54:57], v[150:153], v[166:169], v[54:57]
	v_mfma_f32_16x16x32_bf16 v[50:53], v[158:161], v[166:169], v[50:53]
	v_mfma_f32_16x16x32_bf16 v[38:41], v[150:153], v[174:177], v[38:41]
	v_mfma_f32_16x16x32_bf16 v[34:37], v[158:161], v[174:177], v[34:37]
	v_mfma_f32_16x16x32_bf16 v[22:25], v[150:153], v[192:195], v[22:25]
	v_mfma_f32_16x16x32_bf16 v[18:21], v[158:161], v[192:195], v[18:21]
	v_mfma_f32_16x16x32_bf16 v[6:9], v[150:153], v[212:215], v[6:9]
	v_mfma_f32_16x16x32_bf16 v[2:5], v[158:161], v[212:215], v[2:5]
	s_barrier
	s_add_i32 s63, s63, 2
	s_add_u32 s19, s19, 0x100
	s_addc_u32 s27, s27, 0
	s_add_u32 s61, s61, 0x100
	s_addc_u32 s62, s62, 0
	s_add_u32 s34, s34, 0x100
	s_addc_u32 s35, s35, 0
	s_cmp_gt_u32 s63, 29
	s_cbranch_scc0 .LBB0_1137
	s_and_b64 vcc, exec, s[16:17]
	s_cbranch_vccz .LBB0_1140
	s_barrier

.LBB0_1205:
	s_or_b64 exec, exec, s[4:5]
	s_cmpk_lt_i32 s94, 0x5ac
	s_cselect_b64 s[6:7], -1, 0
	s_mov_b64 s[4:5], s[0:1]
	s_mov_b64 s[8:9], s[0:1]
	s_mov_b64 s[12:13], s[0:1]
	s_mov_b64 s[14:15], s[0:1]
	s_waitcnt lgkmcnt(0)
	v_mov_b32_e32 v2, v0
	s_barrier
	v_readlane_b32 s99, v242, 0
	s_nop 1
	s_cmp_gt_u32 s99, 3
	s_cbranch_scc0 .Lsp_4
	s_setprio 1

; #define PG8_STAGE(bufoff, gbase, voff) do { _Pragma("unroll") for (int _i = 0; _i < 2; ++_i) { unsigned keep_; \
;         asm volatile("s_mov_b32 %0, m0\n\ts_mov_b32 m0, %3\n\ts_nop 0\n\tglobal_load_lds_dwordx4 %1, %2\n\ts_mov_b32 m0, %0" \
;             : "=&s"(keep_) : "v"((voff)[_i]), "s"((const void*)(gbase)), "s"(ldsb0 + (unsigned)(bufoff) + (unsigned)(_i * 8192)) : "memory"); } } while (0)
; #define PG8_LDA(dst, b, h) do { _Pragma("unroll") for (int m = 0; m < 4; ++m) _Pragma("unroll") for (int k = 0; k < 2; ++k) dst[m][k] = *(const LAS bf16x8*)(lds + PG8_SA(b, h) + aoff + m * 2048 + k * 1024); } while (0)
; #define PG8_LDB(dst, b, h) do { _Pragma("unroll") for (int n = 0; n < 2; ++n) _Pragma("unroll") for (int k = 0; k < 2; ++k) dst[n][k] = *(const LAS bf16x8*)(lds + PG8_SB(b, h) + boff + n * 2048 + k * 1024); } while (0)
; #define PG8_MMA(ai, bj, At, Bt) do { __builtin_amdgcn_s_setprio(1); _Pragma("unroll") for (int m = 0; m < 4; ++m) _Pragma("unroll") for (int n = 0; n < 2; ++n) _Pragma("unroll") for (int k = 0; k < 2; ++k) \
;         acc[ai][bj][m][n] = __builtin_amdgcn_mfma_f32_16x16x32_bf16(Bt[n][k], At[m][k], acc[ai][bj][m][n], 0, 0, 0); __builtin_amdgcn_s_setprio(0); } while (0)
; #define PG8_WAIT_V(n) asm volatile("s_waitcnt vmcnt(" #n ")" ::: "memory")
; #define PG8_WAIT_L(n) asm volatile("s_waitcnt lgkmcnt(" #n ")" ::: "memory")
; #define PG8_BAR __builtin_amdgcn_s_barrier()
; #define PG8_SCHED __builtin_amdgcn_sched_barrier(0)
; template <class Epi, class Sched, bool ALIGN_EPI>
; __device__ __forceinline__ void gemm_phase(LAS unsigned char* lds, const Gemm g, const Sched& S, const Epi& E) {
;     ...
;             PG8_LDB(B0, 0, 0); PG8_LDB(B1, 0, 1); PG8_SCHED; PG8_LDA(At, 0, 0); PG8_STAGE(PG8_SA(1, 1), a1 + hstepA, voffA);
;             PG8_WAIT_V(8); PG8_WAIT_L(0); PG8_BAR; PG8_MMA(0, 0, At, B0); PG8_MMA(0, 1, At, B1); PG8_BAR; PG8_SCHED;
;             PG8_LDA(At, 0, 1); PG8_STAGE(PG8_SB(0, 0), b2, voffB); PG8_STAGE(PG8_SB(0, 1), b2 + hstepB, voffB); PG8_STAGE(PG8_SA(0, 0), a2, voffA);
;             PG8_WAIT_V(8); PG8_WAIT_L(0); PG8_BAR; PG8_MMA(1, 0, At, B0); PG8_MMA(1, 1, At, B1); PG8_BAR; PG8_SCHED;
.LBB0_1218:
	ds_read_b128 v[154:157], v141
	ds_read_b128 v[158:161], v141 offset:1024
	ds_read_b128 v[162:165], v141 offset:2048
	ds_read_b128 v[166:169], v141 offset:3072
	ds_read_b128 v[170:173], v142
	ds_read_b128 v[174:177], v142 offset:1024
	ds_read_b128 v[180:183], v142 offset:2048
	ds_read_b128 v[184:187], v142 offset:3072
	s_add_u32 s36, s34, 0x100
	s_addc_u32 s37, s35, 0
	s_cmp_eq_u32 s64, 28
	s_cselect_b32 s42, s5, s36
	s_cselect_b32 s43, s3, s37
	s_cselect_b32 s40, s7, s19
	s_cselect_b32 s41, s6, s27
	s_add_u32 s38, s42, 0x80
	s_addc_u32 s39, s43, 0
	ds_read_b128 v[188:191], v143
	ds_read_b128 v[192:195], v143 offset:1024
	ds_read_b128 v[196:199], v143 offset:2048
	ds_read_b128 v[204:207], v143 offset:3072
	ds_read_b128 v[208:211], v143 offset:4096
	ds_read_b128 v[212:215], v143 offset:5120
	ds_read_b128 v[216:219], v143 offset:6144
	ds_read_b128 v[220:223], v143 offset:7168
	s_add_u32 s34, s34, 0x80080
	s_addc_u32 s35, s35, 0
	s_mov_b32 m0, s61
	s_nop 0
	global_load_lds_dwordx4 v134, s[34:35]
	s_nop 0
	s_mov_b32 m0, s62
	s_nop 0
	global_load_lds_dwordx4 v136, s[34:35]
	s_waitcnt vmcnt(8)
	s_waitcnt lgkmcnt(0)
	s_barrier
	v_mfma_f32_16x16x32_bf16 v[126:129], v[154:157], v[188:191], v[126:129]
	v_mfma_f32_16x16x32_bf16 v[122:125], v[162:165], v[188:191], v[122:125]
	v_mfma_f32_16x16x32_bf16 v[110:113], v[154:157], v[196:199], v[110:113]
	v_mfma_f32_16x16x32_bf16 v[106:109], v[162:165], v[196:199], v[106:109]
	v_mfma_f32_16x16x32_bf16 v[94:97], v[154:157], v[208:211], v[94:97]
	v_mfma_f32_16x16x32_bf16 v[90:93], v[162:165], v[208:211], v[90:93]
	v_mfma_f32_16x16x32_bf16 v[78:81], v[154:157], v[216:219], v[78:81]
	v_mfma_f32_16x16x32_bf16 v[74:77], v[162:165], v[216:219], v[74:77]
	v_mfma_f32_16x16x32_bf16 v[126:129], v[158:161], v[192:195], v[126:129]
	v_mfma_f32_16x16x32_bf16 v[122:125], v[166:169], v[192:195], v[122:125]
	v_mfma_f32_16x16x32_bf16 v[110:113], v[158:161], v[204:207], v[110:113]
	v_mfma_f32_16x16x32_bf16 v[106:109], v[166:169], v[204:207], v[106:109]
	v_mfma_f32_16x16x32_bf16 v[94:97], v[158:161], v[212:215], v[94:97]
	v_mfma_f32_16x16x32_bf16 v[90:93], v[166:169], v[212:215], v[90:93]
	v_mfma_f32_16x16x32_bf16 v[78:81], v[158:161], v[220:223], v[78:81]
	v_mfma_f32_16x16x32_bf16 v[74:77], v[166:169], v[220:223], v[74:77]
	v_mfma_f32_16x16x32_bf16 v[118:121], v[170:173], v[188:191], v[118:121]
	v_mfma_f32_16x16x32_bf16 v[114:117], v[180:183], v[188:191], v[114:117]
	v_mfma_f32_16x16x32_bf16 v[102:105], v[170:173], v[196:199], v[102:105]
	v_mfma_f32_16x16x32_bf16 v[98:101], v[180:183], v[196:199], v[98:101]
	v_mfma_f32_16x16x32_bf16 v[86:89], v[170:173], v[208:211], v[86:89]
	v_mfma_f32_16x16x32_bf16 v[82:85], v[180:183], v[208:211], v[82:85]
	v_mfma_f32_16x16x32_bf16 v[70:73], v[170:173], v[216:219], v[70:73]
	v_mfma_f32_16x16x32_bf16 v[66:69], v[180:183], v[216:219], v[66:69]
	v_mfma_f32_16x16x32_bf16 v[118:121], v[174:177], v[192:195], v[118:121]
	v_mfma_f32_16x16x32_bf16 v[114:117], v[184:187], v[192:195], v[114:117]
	v_mfma_f32_16x16x32_bf16 v[102:105], v[174:177], v[204:207], v[102:105]
	v_mfma_f32_16x16x32_bf16 v[98:101], v[184:187], v[204:207], v[98:101]
	v_mfma_f32_16x16x32_bf16 v[86:89], v[174:177], v[212:215], v[86:89]
	v_mfma_f32_16x16x32_bf16 v[82:85], v[184:187], v[212:215], v[82:85]
	v_mfma_f32_16x16x32_bf16 v[70:73], v[174:177], v[220:223], v[70:73]
	v_mfma_f32_16x16x32_bf16 v[66:69], v[184:187], v[220:223], v[66:69]
	s_barrier
	ds_read_b128 v[188:191], v143 offset:16384
	ds_read_b128 v[192:195], v143 offset:17408
	ds_read_b128 v[196:199], v143 offset:18432
	ds_read_b128 v[204:207], v143 offset:19456
	ds_read_b128 v[208:211], v143 offset:20480
	ds_read_b128 v[212:215], v143 offset:21504
	ds_read_b128 v[216:219], v143 offset:22528
	ds_read_b128 v[220:223], v143 offset:23552
	s_mov_b32 m0, s47
	s_nop 0
	global_load_lds_dwordx4 v135, s[40:41]
	s_nop 0
	s_mov_b32 m0, s48
	s_nop 0
	global_load_lds_dwordx4 v137, s[40:41]
	s_add_u32 s34, s40, 0x80000
	s_addc_u32 s35, s41, 0
	s_mov_b32 m0, s49
	s_nop 0
	global_load_lds_dwordx4 v135, s[34:35]
	s_nop 0
	s_mov_b32 m0, s50
	s_nop 0
	global_load_lds_dwordx4 v137, s[34:35]
	s_mov_b32 m0, s45
	s_nop 0
	global_load_lds_dwordx4 v134, s[42:43]
	s_nop 0
	s_mov_b32 m0, s51
	s_nop 0
	global_load_lds_dwordx4 v136, s[42:43]
	s_waitcnt vmcnt(8)
	s_waitcnt lgkmcnt(0)
	s_barrier
	v_mfma_f32_16x16x32_bf16 v[62:65], v[154:157], v[188:191], v[62:65]
	v_mfma_f32_16x16x32_bf16 v[58:61], v[162:165], v[188:191], v[58:61]
	v_mfma_f32_16x16x32_bf16 v[46:49], v[154:157], v[196:199], v[46:49]
	v_mfma_f32_16x16x32_bf16 v[42:45], v[162:165], v[196:199], v[42:45]
	v_mfma_f32_16x16x32_bf16 v[30:33], v[154:157], v[208:211], v[30:33]
	v_mfma_f32_16x16x32_bf16 v[26:29], v[162:165], v[208:211], v[26:29]
	v_mfma_f32_16x16x32_bf16 v[14:17], v[154:157], v[216:219], v[14:17]
	v_mfma_f32_16x16x32_bf16 v[10:13], v[162:165], v[216:219], v[10:13]
	v_mfma_f32_16x16x32_bf16 v[62:65], v[158:161], v[192:195], v[62:65]
	v_mfma_f32_16x16x32_bf16 v[58:61], v[166:169], v[192:195], v[58:61]
	v_mfma_f32_16x16x32_bf16 v[46:49], v[158:161], v[204:207], v[46:49]
	v_mfma_f32_16x16x32_bf16 v[42:45], v[166:169], v[204:207], v[42:45]
	v_mfma_f32_16x16x32_bf16 v[30:33], v[158:161], v[212:215], v[30:33]
	v_mfma_f32_16x16x32_bf16 v[26:29], v[166:169], v[212:215], v[26:29]
	v_mfma_f32_16x16x32_bf16 v[14:17], v[158:161], v[220:223], v[14:17]
	v_mfma_f32_16x16x32_bf16 v[10:13], v[166:169], v[220:223], v[10:13]
	v_mfma_f32_16x16x32_bf16 v[54:57], v[170:173], v[188:191], v[54:57]
	v_mfma_f32_16x16x32_bf16 v[50:53], v[180:183], v[188:191], v[50:53]
	v_mfma_f32_16x16x32_bf16 v[38:41], v[170:173], v[196:199], v[38:41]
	v_mfma_f32_16x16x32_bf16 v[34:37], v[180:183], v[196:199], v[34:37]
	v_mfma_f32_16x16x32_bf16 v[22:25], v[170:173], v[208:211], v[22:25]
	v_mfma_f32_16x16x32_bf16 v[18:21], v[180:183], v[208:211], v[18:21]
	v_mfma_f32_16x16x32_bf16 v[6:9], v[170:173], v[216:219], v[6:9]
	v_mfma_f32_16x16x32_bf16 v[2:5], v[180:183], v[216:219], v[2:5]
	v_mfma_f32_16x16x32_bf16 v[54:57], v[174:177], v[192:195], v[54:57]
	v_mfma_f32_16x16x32_bf16 v[50:53], v[184:187], v[192:195], v[50:53]
	v_mfma_f32_16x16x32_bf16 v[38:41], v[174:177], v[204:207], v[38:41]
	v_mfma_f32_16x16x32_bf16 v[34:37], v[184:187], v[204:207], v[34:37]
	v_mfma_f32_16x16x32_bf16 v[22:25], v[174:177], v[212:215], v[22:25]
	v_mfma_f32_16x16x32_bf16 v[18:21], v[184:187], v[212:215], v[18:21]
	v_mfma_f32_16x16x32_bf16 v[6:9], v[174:177], v[220:223], v[6:9]
	v_mfma_f32_16x16x32_bf16 v[2:5], v[184:187], v[220:223], v[2:5]
	s_barrier
; #define PG8_STAGE(bufoff, gbase, voff) do { _Pragma("unroll") for (int _i = 0; _i < 2; ++_i) { unsigned keep_; \
;         asm volatile("s_mov_b32 %0, m0\n\ts_mov_b32 m0, %3\n\ts_nop 0\n\tglobal_load_lds_dwordx4 %1, %2\n\ts_mov_b32 m0, %0" \
;             : "=&s"(keep_) : "v"((voff)[_i]), "s"((const void*)(gbase)), "s"(ldsb0 + (unsigned)(bufoff) + (unsigned)(_i * 8192)) : "memory"); } } while (0)
; #define PG8_LDA(dst, b, h) do { _Pragma("unroll") for (int m = 0; m < 4; ++m) _Pragma("unroll") for (int k = 0; k < 2; ++k) dst[m][k] = *(const LAS bf16x8*)(lds + PG8_SA(b, h) + aoff + m * 2048 + k * 1024); } while (0)
; #define PG8_LDB(dst, b, h) do { _Pragma("unroll") for (int n = 0; n < 2; ++n) _Pragma("unroll") for (int k = 0; k < 2; ++k) dst[n][k] = *(const LAS bf16x8*)(lds + PG8_SB(b, h) + boff + n * 2048 + k * 1024); } while (0)
; #define PG8_WAIT_V(n) asm volatile("s_waitcnt vmcnt(" #n ")" ::: "memory")
; #define PG8_WAIT_L(n) asm volatile("s_waitcnt lgkmcnt(" #n ")" ::: "memory")
; #define PG8_BAR __builtin_amdgcn_s_barrier()
; #define PG8_SCHED __builtin_amdgcn_sched_barrier(0)
; template <class Epi, class Sched, bool ALIGN_EPI>
; __device__ __forceinline__ void gemm_phase(LAS unsigned char* lds, const Gemm g, const Sched& S, const Epi& E) {
;     ...
;             PG8_LDB(B0, 0, 0); PG8_LDB(B1, 0, 1); PG8_SCHED; PG8_LDA(At, 0, 0); PG8_STAGE(PG8_SA(1, 1), a1 + hstepA, voffA);
;             PG8_WAIT_V(8); PG8_WAIT_L(0); PG8_BAR; PG8_MMA(0, 0, At, B0); PG8_MMA(0, 1, At, B1); PG8_BAR; PG8_SCHED;
;             PG8_LDA(At, 0, 1); PG8_STAGE(PG8_SB(0, 0), b2, voffB); PG8_STAGE(PG8_SB(0, 1), b2 + hstepB, voffB); PG8_STAGE(PG8_SA(0, 0), a2, voffA);
;             PG8_WAIT_V(8); PG8_WAIT_L(0); PG8_BAR; PG8_MMA(1, 0, At, B0); PG8_MMA(1, 1, At, B1); PG8_BAR; PG8_SCHED;
;             PG8_LDB(B0, 1, 0); PG8_LDB(B1, 1, 1); PG8_SCHED; PG8_LDA(At, 1, 0); PG8_STAGE(PG8_SA(0, 1), a2 + hstepA, voffA);
;             PG8_WAIT_V(8); PG8_WAIT_L(0); PG8_BAR; PG8_MMA(0, 0, At, B0); PG8_MMA(0, 1, At, B1); PG8_BAR; PG8_SCHED;
;             PG8_LDA(At, 1, 1); PG8_STAGE(PG8_SB(1, 0), b3, voffB); PG8_STAGE(PG8_SB(1, 1), b3 + hstepB, voffB); PG8_STAGE(PG8_SA(1, 0), a3, voffA);
;             PG8_WAIT_V(8); PG8_WAIT_L(0); PG8_BAR; PG8_MMA(1, 0, At, B0); PG8_MMA(1, 1, At, B1); PG8_BAR; PG8_SCHED;
;         }
	ds_read_b128 v[154:157], v144
	ds_read_b128 v[158:161], v144 offset:1024
	ds_read_b128 v[162:165], v144 offset:2048
	ds_read_b128 v[166:169], v144 offset:3072
	ds_read_b128 v[170:173], v145
	ds_read_b128 v[174:177], v145 offset:1024
	ds_read_b128 v[180:183], v145 offset:2048
	ds_read_b128 v[184:187], v145 offset:3072
	ds_read_b128 v[188:191], v143 offset:32768
	ds_read_b128 v[192:195], v143 offset:33792
	ds_read_b128 v[196:199], v143 offset:34816
	ds_read_b128 v[204:207], v143 offset:35840
	ds_read_b128 v[208:211], v143 offset:36864
	ds_read_b128 v[212:215], v143 offset:37888
	ds_read_b128 v[216:219], v143 offset:38912
	ds_read_b128 v[220:223], v143 offset:39936
	s_add_u32 s34, s42, 0x80000
	s_addc_u32 s35, s43, 0
	s_mov_b32 m0, s52
	s_nop 0
	global_load_lds_dwordx4 v134, s[34:35]
	s_nop 0
	s_mov_b32 m0, s53
	s_nop 0
	global_load_lds_dwordx4 v136, s[34:35]
	s_waitcnt vmcnt(8)
	s_waitcnt lgkmcnt(0)
	s_barrier
	v_mfma_f32_16x16x32_bf16 v[126:129], v[154:157], v[188:191], v[126:129]
	v_mfma_f32_16x16x32_bf16 v[122:125], v[162:165], v[188:191], v[122:125]
	v_mfma_f32_16x16x32_bf16 v[110:113], v[154:157], v[196:199], v[110:113]
	v_mfma_f32_16x16x32_bf16 v[106:109], v[162:165], v[196:199], v[106:109]
	v_mfma_f32_16x16x32_bf16 v[94:97], v[154:157], v[208:211], v[94:97]
	v_mfma_f32_16x16x32_bf16 v[90:93], v[162:165], v[208:211], v[90:93]
	v_mfma_f32_16x16x32_bf16 v[78:81], v[154:157], v[216:219], v[78:81]
	v_mfma_f32_16x16x32_bf16 v[74:77], v[162:165], v[216:219], v[74:77]
	v_mfma_f32_16x16x32_bf16 v[126:129], v[158:161], v[192:195], v[126:129]
	v_mfma_f32_16x16x32_bf16 v[122:125], v[166:169], v[192:195], v[122:125]
	v_mfma_f32_16x16x32_bf16 v[110:113], v[158:161], v[204:207], v[110:113]
	v_mfma_f32_16x16x32_bf16 v[106:109], v[166:169], v[204:207], v[106:109]
	v_mfma_f32_16x16x32_bf16 v[94:97], v[158:161], v[212:215], v[94:97]
	v_mfma_f32_16x16x32_bf16 v[90:93], v[166:169], v[212:215], v[90:93]
	v_mfma_f32_16x16x32_bf16 v[78:81], v[158:161], v[220:223], v[78:81]
	v_mfma_f32_16x16x32_bf16 v[74:77], v[166:169], v[220:223], v[74:77]
	v_mfma_f32_16x16x32_bf16 v[118:121], v[170:173], v[188:191], v[118:121]
	v_mfma_f32_16x16x32_bf16 v[114:117], v[180:183], v[188:191], v[114:117]
	v_mfma_f32_16x16x32_bf16 v[102:105], v[170:173], v[196:199], v[102:105]
	v_mfma_f32_16x16x32_bf16 v[98:101], v[180:183], v[196:199], v[98:101]
	v_mfma_f32_16x16x32_bf16 v[86:89], v[170:173], v[208:211], v[86:89]
	v_mfma_f32_16x16x32_bf16 v[82:85], v[180:183], v[208:211], v[82:85]
	v_mfma_f32_16x16x32_bf16 v[70:73], v[170:173], v[216:219], v[70:73]
	v_mfma_f32_16x16x32_bf16 v[66:69], v[180:183], v[216:219], v[66:69]
	v_mfma_f32_16x16x32_bf16 v[118:121], v[174:177], v[192:195], v[118:121]
	v_mfma_f32_16x16x32_bf16 v[114:117], v[184:187], v[192:195], v[114:117]
	v_mfma_f32_16x16x32_bf16 v[102:105], v[174:177], v[204:207], v[102:105]
	v_mfma_f32_16x16x32_bf16 v[98:101], v[184:187], v[204:207], v[98:101]
	v_mfma_f32_16x16x32_bf16 v[86:89], v[174:177], v[212:215], v[86:89]
	v_mfma_f32_16x16x32_bf16 v[82:85], v[184:187], v[212:215], v[82:85]
	v_mfma_f32_16x16x32_bf16 v[70:73], v[174:177], v[220:223], v[70:73]
	v_mfma_f32_16x16x32_bf16 v[66:69], v[184:187], v[220:223], v[66:69]
	s_barrier
	ds_read_b128 v[188:191], v143 offset:49152
	ds_read_b128 v[192:195], v143 offset:50176
	ds_read_b128 v[196:199], v143 offset:51200
	ds_read_b128 v[204:207], v143 offset:52224
	ds_read_b128 v[208:211], v143 offset:53248
	ds_read_b128 v[212:215], v143 offset:54272
	ds_read_b128 v[216:219], v143 offset:55296
	ds_read_b128 v[220:223], v143 offset:56320
	s_add_u32 s34, s40, 0x80
	s_addc_u32 s35, s41, 0
	s_mov_b32 m0, s54
	s_nop 0
	global_load_lds_dwordx4 v135, s[34:35]
	s_nop 0
	s_mov_b32 m0, s55
	s_nop 0
	global_load_lds_dwordx4 v137, s[34:35]
	s_add_u32 s34, s40, 0x80080
	s_addc_u32 s35, s41, 0
	s_mov_b32 m0, s58
	s_nop 0
	global_load_lds_dwordx4 v135, s[34:35]
	s_nop 0
	s_mov_b32 m0, s59
	s_nop 0
	global_load_lds_dwordx4 v137, s[34:35]
	s_mov_b32 m0, s56
	s_nop 0
	global_load_lds_dwordx4 v134, s[38:39]
	s_nop 0
	s_mov_b32 m0, s57
	s_nop 0
	global_load_lds_dwordx4 v136, s[38:39]
	s_waitcnt vmcnt(8)
	s_waitcnt lgkmcnt(0)
	s_barrier
	v_mfma_f32_16x16x32_bf16 v[62:65], v[154:157], v[188:191], v[62:65]
	v_mfma_f32_16x16x32_bf16 v[58:61], v[162:165], v[188:191], v[58:61]
	v_mfma_f32_16x16x32_bf16 v[46:49], v[154:157], v[196:199], v[46:49]
	v_mfma_f32_16x16x32_bf16 v[42:45], v[162:165], v[196:199], v[42:45]
	v_mfma_f32_16x16x32_bf16 v[30:33], v[154:157], v[208:211], v[30:33]
	v_mfma_f32_16x16x32_bf16 v[26:29], v[162:165], v[208:211], v[26:29]
	v_mfma_f32_16x16x32_bf16 v[14:17], v[154:157], v[216:219], v[14:17]
	v_mfma_f32_16x16x32_bf16 v[10:13], v[162:165], v[216:219], v[10:13]
	v_mfma_f32_16x16x32_bf16 v[62:65], v[158:161], v[192:195], v[62:65]
	v_mfma_f32_16x16x32_bf16 v[58:61], v[166:169], v[192:195], v[58:61]
	v_mfma_f32_16x16x32_bf16 v[46:49], v[158:161], v[204:207], v[46:49]
	v_mfma_f32_16x16x32_bf16 v[42:45], v[166:169], v[204:207], v[42:45]
	v_mfma_f32_16x16x32_bf16 v[30:33], v[158:161], v[212:215], v[30:33]
	v_mfma_f32_16x16x32_bf16 v[26:29], v[166:169], v[212:215], v[26:29]
	v_mfma_f32_16x16x32_bf16 v[14:17], v[158:161], v[220:223], v[14:17]
	v_mfma_f32_16x16x32_bf16 v[10:13], v[166:169], v[220:223], v[10:13]
	v_mfma_f32_16x16x32_bf16 v[54:57], v[170:173], v[188:191], v[54:57]
	v_mfma_f32_16x16x32_bf16 v[50:53], v[180:183], v[188:191], v[50:53]
	v_mfma_f32_16x16x32_bf16 v[38:41], v[170:173], v[196:199], v[38:41]
	v_mfma_f32_16x16x32_bf16 v[34:37], v[180:183], v[196:199], v[34:37]
	v_mfma_f32_16x16x32_bf16 v[22:25], v[170:173], v[208:211], v[22:25]
	v_mfma_f32_16x16x32_bf16 v[18:21], v[180:183], v[208:211], v[18:21]
	v_mfma_f32_16x16x32_bf16 v[6:9], v[170:173], v[216:219], v[6:9]
	v_mfma_f32_16x16x32_bf16 v[2:5], v[180:183], v[216:219], v[2:5]
	v_mfma_f32_16x16x32_bf16 v[54:57], v[174:177], v[192:195], v[54:57]
	v_mfma_f32_16x16x32_bf16 v[50:53], v[184:187], v[192:195], v[50:53]
	v_mfma_f32_16x16x32_bf16 v[38:41], v[174:177], v[204:207], v[38:41]
	v_mfma_f32_16x16x32_bf16 v[34:37], v[184:187], v[204:207], v[34:37]
	v_mfma_f32_16x16x32_bf16 v[22:25], v[174:177], v[212:215], v[22:25]
	v_mfma_f32_16x16x32_bf16 v[18:21], v[184:187], v[212:215], v[18:21]
	v_mfma_f32_16x16x32_bf16 v[6:9], v[174:177], v[220:223], v[6:9]
	v_mfma_f32_16x16x32_bf16 v[2:5], v[184:187], v[220:223], v[2:5]
	s_barrier
	s_add_i32 s64, s64, 2
	s_add_u32 s19, s19, 0x100
	s_addc_u32 s27, s27, 0
	s_cmp_gt_u32 s64, 29
	s_mov_b64 s[34:35], s[36:37]
	s_cbranch_scc0 .LBB0_1218
	s_and_b64 vcc, exec, s[16:17]
	s_cbranch_vccz .LBB0_1221
	s_barrier

; #define PG8_STAGE(bufoff, gbase, voff) do { _Pragma("unroll") for (int _i = 0; _i < 2; ++_i) { unsigned keep_; \
;         asm volatile("s_mov_b32 %0, m0\n\ts_mov_b32 m0, %3\n\ts_nop 0\n\tglobal_load_lds_dwordx4 %1, %2\n\ts_mov_b32 m0, %0" \
;             : "=&s"(keep_) : "v"((voff)[_i]), "s"((const void*)(gbase)), "s"(ldsb0 + (unsigned)(bufoff) + (unsigned)(_i * 8192)) : "memory"); } } while (0)
; #define PG8_LDA(dst, b, h) do { _Pragma("unroll") for (int m = 0; m < 4; ++m) _Pragma("unroll") for (int k = 0; k < 2; ++k) dst[m][k] = *(const LAS bf16x8*)(lds + PG8_SA(b, h) + aoff + m * 2048 + k * 1024); } while (0)
; #define PG8_LDB(dst, b, h) do { _Pragma("unroll") for (int n = 0; n < 2; ++n) _Pragma("unroll") for (int k = 0; k < 2; ++k) dst[n][k] = *(const LAS bf16x8*)(lds + PG8_SB(b, h) + boff + n * 2048 + k * 1024); } while (0)
; #define PG8_MMA(ai, bj, At, Bt) do { __builtin_amdgcn_s_setprio(1); _Pragma("unroll") for (int m = 0; m < 4; ++m) _Pragma("unroll") for (int n = 0; n < 2; ++n) _Pragma("unroll") for (int k = 0; k < 2; ++k) \
;         acc[ai][bj][m][n] = __builtin_amdgcn_mfma_f32_16x16x32_bf16(Bt[n][k], At[m][k], acc[ai][bj][m][n], 0, 0, 0); __builtin_amdgcn_s_setprio(0); } while (0)
; #define PG8_WAIT_V(n) asm volatile("s_waitcnt vmcnt(" #n ")" ::: "memory")
; #define PG8_WAIT_L(n) asm volatile("s_waitcnt lgkmcnt(" #n ")" ::: "memory")
; #define PG8_BAR __builtin_amdgcn_s_barrier()
; #define PG8_SCHED __builtin_amdgcn_sched_barrier(0)
; template <class Epi, class Sched, bool ALIGN_EPI>
; __device__ __forceinline__ void gemm_phase(LAS unsigned char* lds, const Gemm g, const Sched& S, const Epi& E) {
;     ...
;             PG8_LDB(B0, 0, 0); PG8_LDB(B1, 0, 1); PG8_SCHED; PG8_LDA(At, 0, 0); PG8_STAGE(PG8_SA(1, 1), a1 + hstepA, voffA);
;             PG8_WAIT_V(8); PG8_WAIT_L(0); PG8_BAR; PG8_MMA(0, 0, At, B0); PG8_MMA(0, 1, At, B1); PG8_BAR; PG8_SCHED;
;             PG8_LDA(At, 0, 1); PG8_STAGE(PG8_SB(0, 0), b2, voffB); PG8_STAGE(PG8_SB(0, 1), b2 + hstepB, voffB); PG8_STAGE(PG8_SA(0, 0), a2, voffA);
;             PG8_WAIT_V(8); PG8_WAIT_L(0); PG8_BAR; PG8_MMA(1, 0, At, B0); PG8_MMA(1, 1, At, B1); PG8_BAR; PG8_SCHED;
.LBB0_1317:
	ds_read_b128 v[110:113], v206
	ds_read_b128 v[126:129], v206 offset:1024
	ds_read_b128 v[130:133], v206 offset:2048
	ds_read_b128 v[142:145], v206 offset:3072
	ds_read_b128 v[146:149], v207
	ds_read_b128 v[150:153], v207 offset:1024
	ds_read_b128 v[154:157], v207 offset:2048
	ds_read_b128 v[158:161], v207 offset:3072
	s_cmpk_eq_i32 s58, 0x54
	s_cselect_b32 s34, s14, s6
	s_cselect_b32 s35, s15, s7
	s_cselect_b32 s30, s26, s56
	s_cselect_b32 s31, s27, s57
	s_add_u32 s28, s34, 0x80
	s_addc_u32 s29, s35, 0
	ds_read_b128 v[162:165], v208
	ds_read_b128 v[166:169], v208 offset:1024
	ds_read_b128 v[170:173], v208 offset:2048
	ds_read_b128 v[174:177], v208 offset:3072
	ds_read_b128 v[188:191], v208 offset:4096
	ds_read_b128 v[192:195], v208 offset:5120
	ds_read_b128 v[196:199], v208 offset:6144
	ds_read_b128 v[212:215], v208 offset:7168
	s_mov_b32 m0, s52
	s_nop 0
	global_load_lds_dwordx4 v179, s[4:5]
	s_nop 0
	s_mov_b32 m0, s53
	s_nop 0
	global_load_lds_dwordx4 v201, s[4:5]
	s_waitcnt vmcnt(8)
	s_waitcnt lgkmcnt(0)
	s_barrier
	v_mfma_f32_16x16x32_bf16 v[138:141], v[110:113], v[162:165], v[138:141]
	v_mfma_f32_16x16x32_bf16 v[134:137], v[130:133], v[162:165], v[134:137]
	v_mfma_f32_16x16x32_bf16 v[114:117], v[110:113], v[170:173], v[114:117]
	v_mfma_f32_16x16x32_bf16 v[106:109], v[130:133], v[170:173], v[106:109]
	v_mfma_f32_16x16x32_bf16 v[94:97], v[110:113], v[188:191], v[94:97]
	v_mfma_f32_16x16x32_bf16 v[90:93], v[130:133], v[188:191], v[90:93]
	v_mfma_f32_16x16x32_bf16 v[78:81], v[110:113], v[196:199], v[78:81]
	v_mfma_f32_16x16x32_bf16 v[74:77], v[130:133], v[196:199], v[74:77]
	v_mfma_f32_16x16x32_bf16 v[138:141], v[126:129], v[166:169], v[138:141]
	v_mfma_f32_16x16x32_bf16 v[134:137], v[142:145], v[166:169], v[134:137]
	v_mfma_f32_16x16x32_bf16 v[114:117], v[126:129], v[174:177], v[114:117]
	v_mfma_f32_16x16x32_bf16 v[106:109], v[142:145], v[174:177], v[106:109]
	v_mfma_f32_16x16x32_bf16 v[94:97], v[126:129], v[192:195], v[94:97]
	v_mfma_f32_16x16x32_bf16 v[90:93], v[142:145], v[192:195], v[90:93]
	v_mfma_f32_16x16x32_bf16 v[78:81], v[126:129], v[212:215], v[78:81]
	v_mfma_f32_16x16x32_bf16 v[74:77], v[142:145], v[212:215], v[74:77]
	v_mfma_f32_16x16x32_bf16 v[122:125], v[146:149], v[162:165], v[122:125]
	v_mfma_f32_16x16x32_bf16 v[118:121], v[154:157], v[162:165], v[118:121]
	v_mfma_f32_16x16x32_bf16 v[102:105], v[146:149], v[170:173], v[102:105]
	v_mfma_f32_16x16x32_bf16 v[98:101], v[154:157], v[170:173], v[98:101]
	v_mfma_f32_16x16x32_bf16 v[86:89], v[146:149], v[188:191], v[86:89]
	v_mfma_f32_16x16x32_bf16 v[82:85], v[154:157], v[188:191], v[82:85]
	v_mfma_f32_16x16x32_bf16 v[70:73], v[146:149], v[196:199], v[70:73]
	v_mfma_f32_16x16x32_bf16 v[66:69], v[154:157], v[196:199], v[66:69]
	v_mfma_f32_16x16x32_bf16 v[122:125], v[150:153], v[166:169], v[122:125]
	v_mfma_f32_16x16x32_bf16 v[118:121], v[158:161], v[166:169], v[118:121]
	v_mfma_f32_16x16x32_bf16 v[102:105], v[150:153], v[174:177], v[102:105]
	v_mfma_f32_16x16x32_bf16 v[98:101], v[158:161], v[174:177], v[98:101]
	v_mfma_f32_16x16x32_bf16 v[86:89], v[150:153], v[192:195], v[86:89]
	v_mfma_f32_16x16x32_bf16 v[82:85], v[158:161], v[192:195], v[82:85]
	v_mfma_f32_16x16x32_bf16 v[70:73], v[150:153], v[212:215], v[70:73]
	v_mfma_f32_16x16x32_bf16 v[66:69], v[158:161], v[212:215], v[66:69]
	s_barrier
	ds_read_b128 v[162:165], v208 offset:16384
	ds_read_b128 v[166:169], v208 offset:17408
	ds_read_b128 v[170:173], v208 offset:18432
	ds_read_b128 v[174:177], v208 offset:19456
	ds_read_b128 v[188:191], v208 offset:20480
	ds_read_b128 v[192:195], v208 offset:21504
	ds_read_b128 v[196:199], v208 offset:22528
	ds_read_b128 v[212:215], v208 offset:23552
	s_mov_b32 m0, s39
	s_nop 0
	global_load_lds_dwordx4 v200, s[30:31]
	s_add_u32 s62, s30, 0x160000
	s_mov_b32 m0, s40
	s_nop 0
	global_load_lds_dwordx4 v203, s[30:31]
	s_addc_u32 s63, s31, 0
	s_mov_b32 m0, s41
	s_nop 0
	global_load_lds_dwordx4 v200, s[62:63]
	s_nop 0
	s_mov_b32 m0, s42
	s_nop 0
	global_load_lds_dwordx4 v203, s[62:63]
	s_nop 0
	s_mov_b32 m0, s38
	s_nop 0
	global_load_lds_dwordx4 v179, s[34:35]
	s_nop 0
	s_mov_b32 m0, s43
	s_nop 0
	global_load_lds_dwordx4 v201, s[34:35]
	s_waitcnt vmcnt(8)
	s_waitcnt lgkmcnt(0)
	s_barrier
	v_mfma_f32_16x16x32_bf16 v[62:65], v[110:113], v[162:165], v[62:65]
	v_mfma_f32_16x16x32_bf16 v[58:61], v[130:133], v[162:165], v[58:61]
	v_mfma_f32_16x16x32_bf16 v[46:49], v[110:113], v[170:173], v[46:49]
	v_mfma_f32_16x16x32_bf16 v[42:45], v[130:133], v[170:173], v[42:45]
	v_mfma_f32_16x16x32_bf16 v[30:33], v[110:113], v[188:191], v[30:33]
	v_mfma_f32_16x16x32_bf16 v[26:29], v[130:133], v[188:191], v[26:29]
	v_mfma_f32_16x16x32_bf16 v[14:17], v[110:113], v[196:199], v[14:17]
	v_mfma_f32_16x16x32_bf16 v[10:13], v[130:133], v[196:199], v[10:13]
	v_mfma_f32_16x16x32_bf16 v[62:65], v[126:129], v[166:169], v[62:65]
	v_mfma_f32_16x16x32_bf16 v[58:61], v[142:145], v[166:169], v[58:61]
	v_mfma_f32_16x16x32_bf16 v[46:49], v[126:129], v[174:177], v[46:49]
	v_mfma_f32_16x16x32_bf16 v[42:45], v[142:145], v[174:177], v[42:45]
	v_mfma_f32_16x16x32_bf16 v[30:33], v[126:129], v[192:195], v[30:33]
	v_mfma_f32_16x16x32_bf16 v[26:29], v[142:145], v[192:195], v[26:29]
	v_mfma_f32_16x16x32_bf16 v[14:17], v[126:129], v[212:215], v[14:17]
	v_mfma_f32_16x16x32_bf16 v[10:13], v[142:145], v[212:215], v[10:13]
	v_mfma_f32_16x16x32_bf16 v[54:57], v[146:149], v[162:165], v[54:57]
	v_mfma_f32_16x16x32_bf16 v[50:53], v[154:157], v[162:165], v[50:53]
	v_mfma_f32_16x16x32_bf16 v[38:41], v[146:149], v[170:173], v[38:41]
	v_mfma_f32_16x16x32_bf16 v[34:37], v[154:157], v[170:173], v[34:37]
	v_mfma_f32_16x16x32_bf16 v[22:25], v[146:149], v[188:191], v[22:25]
	v_mfma_f32_16x16x32_bf16 v[18:21], v[154:157], v[188:191], v[18:21]
	v_mfma_f32_16x16x32_bf16 v[6:9], v[146:149], v[196:199], v[6:9]
	v_mfma_f32_16x16x32_bf16 v[2:5], v[154:157], v[196:199], v[2:5]
	v_mfma_f32_16x16x32_bf16 v[54:57], v[150:153], v[166:169], v[54:57]
	v_mfma_f32_16x16x32_bf16 v[50:53], v[158:161], v[166:169], v[50:53]
	v_mfma_f32_16x16x32_bf16 v[38:41], v[150:153], v[174:177], v[38:41]
	v_mfma_f32_16x16x32_bf16 v[34:37], v[158:161], v[174:177], v[34:37]
	v_mfma_f32_16x16x32_bf16 v[22:25], v[150:153], v[192:195], v[22:25]
	v_mfma_f32_16x16x32_bf16 v[18:21], v[158:161], v[192:195], v[18:21]
	v_mfma_f32_16x16x32_bf16 v[6:9], v[150:153], v[212:215], v[6:9]
	v_mfma_f32_16x16x32_bf16 v[2:5], v[158:161], v[212:215], v[2:5]
	s_barrier
; #define PG8_STAGE(bufoff, gbase, voff) do { _Pragma("unroll") for (int _i = 0; _i < 2; ++_i) { unsigned keep_; \
;         asm volatile("s_mov_b32 %0, m0\n\ts_mov_b32 m0, %3\n\ts_nop 0\n\tglobal_load_lds_dwordx4 %1, %2\n\ts_mov_b32 m0, %0" \
;             : "=&s"(keep_) : "v"((voff)[_i]), "s"((const void*)(gbase)), "s"(ldsb0 + (unsigned)(bufoff) + (unsigned)(_i * 8192)) : "memory"); } } while (0)
; #define PG8_LDA(dst, b, h) do { _Pragma("unroll") for (int m = 0; m < 4; ++m) _Pragma("unroll") for (int k = 0; k < 2; ++k) dst[m][k] = *(const LAS bf16x8*)(lds + PG8_SA(b, h) + aoff + m * 2048 + k * 1024); } while (0)
; #define PG8_LDB(dst, b, h) do { _Pragma("unroll") for (int n = 0; n < 2; ++n) _Pragma("unroll") for (int k = 0; k < 2; ++k) dst[n][k] = *(const LAS bf16x8*)(lds + PG8_SB(b, h) + boff + n * 2048 + k * 1024); } while (0)
; #define PG8_MMA(ai, bj, At, Bt) do { __builtin_amdgcn_s_setprio(1); _Pragma("unroll") for (int m = 0; m < 4; ++m) _Pragma("unroll") for (int n = 0; n < 2; ++n) _Pragma("unroll") for (int k = 0; k < 2; ++k) \
;         acc[ai][bj][m][n] = __builtin_amdgcn_mfma_f32_16x16x32_bf16(Bt[n][k], At[m][k], acc[ai][bj][m][n], 0, 0, 0); __builtin_amdgcn_s_setprio(0); } while (0)
; #define PG8_WAIT_V(n) asm volatile("s_waitcnt vmcnt(" #n ")" ::: "memory")
; #define PG8_WAIT_L(n) asm volatile("s_waitcnt lgkmcnt(" #n ")" ::: "memory")
; #define PG8_BAR __builtin_amdgcn_s_barrier()
; #define PG8_SCHED __builtin_amdgcn_sched_barrier(0)
; template <class Epi, class Sched, bool ALIGN_EPI>
; __device__ __forceinline__ void gemm_phase(LAS unsigned char* lds, const Gemm g, const Sched& S, const Epi& E) {
;     ...
;             PG8_LDB(B0, 1, 0); PG8_LDB(B1, 1, 1); PG8_SCHED; PG8_LDA(At, 1, 0); PG8_STAGE(PG8_SA(0, 1), a2 + hstepA, voffA);
;             PG8_WAIT_V(8); PG8_WAIT_L(0); PG8_BAR; PG8_MMA(0, 0, At, B0); PG8_MMA(0, 1, At, B1); PG8_BAR; PG8_SCHED;
;             PG8_LDA(At, 1, 1); PG8_STAGE(PG8_SB(1, 0), b3, voffB); PG8_STAGE(PG8_SB(1, 1), b3 + hstepB, voffB); PG8_STAGE(PG8_SA(1, 0), a3, voffA);
;             PG8_WAIT_V(8); PG8_WAIT_L(0); PG8_BAR; PG8_MMA(1, 0, At, B0); PG8_MMA(1, 1, At, B1); PG8_BAR; PG8_SCHED;
;         }
	ds_read_b128 v[110:113], v209
	ds_read_b128 v[126:129], v209 offset:1024
	ds_read_b128 v[130:133], v209 offset:2048
	ds_read_b128 v[142:145], v209 offset:3072
	ds_read_b128 v[146:149], v210
	ds_read_b128 v[150:153], v210 offset:1024
	ds_read_b128 v[154:157], v210 offset:2048
	ds_read_b128 v[158:161], v210 offset:3072
	ds_read_b128 v[162:165], v208 offset:32768
	ds_read_b128 v[166:169], v208 offset:33792
	ds_read_b128 v[170:173], v208 offset:34816
	ds_read_b128 v[174:177], v208 offset:35840
	ds_read_b128 v[188:191], v208 offset:36864
	ds_read_b128 v[192:195], v208 offset:37888
	ds_read_b128 v[196:199], v208 offset:38912
	ds_read_b128 v[212:215], v208 offset:39936
	s_add_u32 s34, s34, 0x160000
	s_addc_u32 s35, s35, 0
	s_mov_b32 m0, s44
	s_nop 0
	global_load_lds_dwordx4 v179, s[34:35]
	s_nop 0
	s_mov_b32 m0, s45
	s_nop 0
	global_load_lds_dwordx4 v201, s[34:35]
	s_waitcnt vmcnt(8)
	s_waitcnt lgkmcnt(0)
	s_barrier
	v_mfma_f32_16x16x32_bf16 v[138:141], v[110:113], v[162:165], v[138:141]
	v_mfma_f32_16x16x32_bf16 v[134:137], v[130:133], v[162:165], v[134:137]
	v_mfma_f32_16x16x32_bf16 v[114:117], v[110:113], v[170:173], v[114:117]
	v_mfma_f32_16x16x32_bf16 v[106:109], v[130:133], v[170:173], v[106:109]
	v_mfma_f32_16x16x32_bf16 v[94:97], v[110:113], v[188:191], v[94:97]
	v_mfma_f32_16x16x32_bf16 v[90:93], v[130:133], v[188:191], v[90:93]
	v_mfma_f32_16x16x32_bf16 v[78:81], v[110:113], v[196:199], v[78:81]
	v_mfma_f32_16x16x32_bf16 v[74:77], v[130:133], v[196:199], v[74:77]
	v_mfma_f32_16x16x32_bf16 v[138:141], v[126:129], v[166:169], v[138:141]
	v_mfma_f32_16x16x32_bf16 v[134:137], v[142:145], v[166:169], v[134:137]
	v_mfma_f32_16x16x32_bf16 v[114:117], v[126:129], v[174:177], v[114:117]
	v_mfma_f32_16x16x32_bf16 v[106:109], v[142:145], v[174:177], v[106:109]
	v_mfma_f32_16x16x32_bf16 v[94:97], v[126:129], v[192:195], v[94:97]
	v_mfma_f32_16x16x32_bf16 v[90:93], v[142:145], v[192:195], v[90:93]
	v_mfma_f32_16x16x32_bf16 v[78:81], v[126:129], v[212:215], v[78:81]
	v_mfma_f32_16x16x32_bf16 v[74:77], v[142:145], v[212:215], v[74:77]
	v_mfma_f32_16x16x32_bf16 v[122:125], v[146:149], v[162:165], v[122:125]
	v_mfma_f32_16x16x32_bf16 v[118:121], v[154:157], v[162:165], v[118:121]
	v_mfma_f32_16x16x32_bf16 v[102:105], v[146:149], v[170:173], v[102:105]
	v_mfma_f32_16x16x32_bf16 v[98:101], v[154:157], v[170:173], v[98:101]
	v_mfma_f32_16x16x32_bf16 v[86:89], v[146:149], v[188:191], v[86:89]
	v_mfma_f32_16x16x32_bf16 v[82:85], v[154:157], v[188:191], v[82:85]
	v_mfma_f32_16x16x32_bf16 v[70:73], v[146:149], v[196:199], v[70:73]
	v_mfma_f32_16x16x32_bf16 v[66:69], v[154:157], v[196:199], v[66:69]
	v_mfma_f32_16x16x32_bf16 v[122:125], v[150:153], v[166:169], v[122:125]
	v_mfma_f32_16x16x32_bf16 v[118:121], v[158:161], v[166:169], v[118:121]
	v_mfma_f32_16x16x32_bf16 v[102:105], v[150:153], v[174:177], v[102:105]
	v_mfma_f32_16x16x32_bf16 v[98:101], v[158:161], v[174:177], v[98:101]
	v_mfma_f32_16x16x32_bf16 v[86:89], v[150:153], v[192:195], v[86:89]
	v_mfma_f32_16x16x32_bf16 v[82:85], v[158:161], v[192:195], v[82:85]
	v_mfma_f32_16x16x32_bf16 v[70:73], v[150:153], v[212:215], v[70:73]
	v_mfma_f32_16x16x32_bf16 v[66:69], v[158:161], v[212:215], v[66:69]
	s_barrier
	ds_read_b128 v[162:165], v208 offset:49152
	ds_read_b128 v[166:169], v208 offset:50176
	ds_read_b128 v[170:173], v208 offset:51200
	ds_read_b128 v[174:177], v208 offset:52224
	ds_read_b128 v[188:191], v208 offset:53248
	ds_read_b128 v[192:195], v208 offset:54272
	ds_read_b128 v[196:199], v208 offset:55296
	ds_read_b128 v[212:215], v208 offset:56320
	s_add_u32 s34, s30, 0x80
	s_addc_u32 s35, s31, 0
	s_mov_b32 m0, s46
	s_nop 0
	global_load_lds_dwordx4 v200, s[34:35]
	s_add_u32 s30, s30, 0x160080
	s_mov_b32 m0, s47
	s_nop 0
	global_load_lds_dwordx4 v203, s[34:35]
	s_addc_u32 s31, s31, 0
	s_mov_b32 m0, s50
	s_nop 0
	global_load_lds_dwordx4 v200, s[30:31]
	s_nop 0
	s_mov_b32 m0, s51
	s_nop 0
	global_load_lds_dwordx4 v203, s[30:31]
	s_mov_b32 m0, s48
	s_nop 0
	global_load_lds_dwordx4 v179, s[28:29]
	s_nop 0
	s_mov_b32 m0, s49
	s_nop 0
	global_load_lds_dwordx4 v201, s[28:29]
	s_waitcnt vmcnt(8)
	s_waitcnt lgkmcnt(0)
	s_barrier
	v_mfma_f32_16x16x32_bf16 v[62:65], v[110:113], v[162:165], v[62:65]
	v_mfma_f32_16x16x32_bf16 v[58:61], v[130:133], v[162:165], v[58:61]
	v_mfma_f32_16x16x32_bf16 v[46:49], v[110:113], v[170:173], v[46:49]
	v_mfma_f32_16x16x32_bf16 v[42:45], v[130:133], v[170:173], v[42:45]
	v_mfma_f32_16x16x32_bf16 v[30:33], v[110:113], v[188:191], v[30:33]
	v_mfma_f32_16x16x32_bf16 v[26:29], v[130:133], v[188:191], v[26:29]
	v_mfma_f32_16x16x32_bf16 v[14:17], v[110:113], v[196:199], v[14:17]
	v_mfma_f32_16x16x32_bf16 v[10:13], v[130:133], v[196:199], v[10:13]
	v_mfma_f32_16x16x32_bf16 v[62:65], v[126:129], v[166:169], v[62:65]
	v_mfma_f32_16x16x32_bf16 v[58:61], v[142:145], v[166:169], v[58:61]
	v_mfma_f32_16x16x32_bf16 v[46:49], v[126:129], v[174:177], v[46:49]
	v_mfma_f32_16x16x32_bf16 v[42:45], v[142:145], v[174:177], v[42:45]
	v_mfma_f32_16x16x32_bf16 v[30:33], v[126:129], v[192:195], v[30:33]
	v_mfma_f32_16x16x32_bf16 v[26:29], v[142:145], v[192:195], v[26:29]
	v_mfma_f32_16x16x32_bf16 v[14:17], v[126:129], v[212:215], v[14:17]
	v_mfma_f32_16x16x32_bf16 v[10:13], v[142:145], v[212:215], v[10:13]
	v_mfma_f32_16x16x32_bf16 v[54:57], v[146:149], v[162:165], v[54:57]
	v_mfma_f32_16x16x32_bf16 v[50:53], v[154:157], v[162:165], v[50:53]
	v_mfma_f32_16x16x32_bf16 v[38:41], v[146:149], v[170:173], v[38:41]
	v_mfma_f32_16x16x32_bf16 v[34:37], v[154:157], v[170:173], v[34:37]
	v_mfma_f32_16x16x32_bf16 v[22:25], v[146:149], v[188:191], v[22:25]
	v_mfma_f32_16x16x32_bf16 v[18:21], v[154:157], v[188:191], v[18:21]
	v_mfma_f32_16x16x32_bf16 v[6:9], v[146:149], v[196:199], v[6:9]
	v_mfma_f32_16x16x32_bf16 v[2:5], v[154:157], v[196:199], v[2:5]
	v_mfma_f32_16x16x32_bf16 v[54:57], v[150:153], v[166:169], v[54:57]
	v_mfma_f32_16x16x32_bf16 v[50:53], v[158:161], v[166:169], v[50:53]
	v_mfma_f32_16x16x32_bf16 v[38:41], v[150:153], v[174:177], v[38:41]
	v_mfma_f32_16x16x32_bf16 v[34:37], v[158:161], v[174:177], v[34:37]
	v_mfma_f32_16x16x32_bf16 v[22:25], v[150:153], v[192:195], v[22:25]
	v_mfma_f32_16x16x32_bf16 v[18:21], v[158:161], v[192:195], v[18:21]
	v_mfma_f32_16x16x32_bf16 v[6:9], v[150:153], v[212:215], v[6:9]
	v_mfma_f32_16x16x32_bf16 v[2:5], v[158:161], v[212:215], v[2:5]
	s_barrier
	s_add_i32 s58, s58, 2
	s_add_u32 s6, s6, 0x100
	s_addc_u32 s7, s7, 0
	s_add_u32 s56, s56, 0x100
	s_addc_u32 s57, s57, 0
	s_add_u32 s4, s4, 0x100
	s_addc_u32 s5, s5, 0
	s_cmpk_gt_u32 s58, 0x55
	s_cbranch_scc0 .LBB0_1317
	s_and_b64 vcc, exec, s[18:19]
	s_cbranch_vccz .LBB0_1320
	s_barrier

; #define REP(k) for (int rep_ = 0; rep_ < ((DUP) == (k) ? 2 : 1); ++rep_)
; __global__ void __launch_bounds__(NT, 2) fwd(Args args) {
;     ...
;     REP(11) {
;         pg8::Gemm g{HB, WQKV, DM, DM, DM, 0}; EpiQkv E{ssq + 2 * MPAD, QB, KB, VB, out + O_SKP, out + O_SVP};
;         pg8::BalancedOrder S{3, bx, G}; pg8::gemm_phase<EpiQkv, pg8::BalancedOrder, true>(lds, g, S, E);
.LBB0_1395:
	s_or_b64 exec, exec, s[4:5]
	s_cmpk_lt_i32 s94, 0x300
	v_readlane_b32 s18, v242, 10
	s_cselect_b64 s[6:7], -1, 0
	v_readlane_b32 s19, v242, 11
	s_mov_b64 s[12:13], s[0:1]
	s_mov_b64 s[14:15], s[0:1]
	s_mov_b64 s[16:17], s[0:1]
	s_mov_b64 s[8:9], s[0:1]
	s_mov_b64 s[26:27], s[0:1]
	s_mov_b64 s[4:5], s[0:1]
	s_mov_b64 s[10:11], s[0:1]
	s_mov_b64 s[30:31], s[0:1]
	s_waitcnt lgkmcnt(0)
	v_mov_b32_e32 v2, v0
	s_or_b64 s[6:7], s[18:19], s[6:7]
	s_barrier
	v_readlane_b32 s99, v242, 0
	s_nop 1
	s_cmp_gt_u32 s99, 3
	s_cbranch_scc0 .Lsp_6
	s_setprio 1

; #define PG8_STAGE(bufoff, gbase, voff) do { _Pragma("unroll") for (int _i = 0; _i < 2; ++_i) { unsigned keep_; \
;         asm volatile("s_mov_b32 %0, m0\n\ts_mov_b32 m0, %3\n\ts_nop 0\n\tglobal_load_lds_dwordx4 %1, %2\n\ts_mov_b32 m0, %0" \
;             : "=&s"(keep_) : "v"((voff)[_i]), "s"((const void*)(gbase)), "s"(ldsb0 + (unsigned)(bufoff) + (unsigned)(_i * 8192)) : "memory"); } } while (0)
; #define PG8_LDA(dst, b, h) do { _Pragma("unroll") for (int m = 0; m < 4; ++m) _Pragma("unroll") for (int k = 0; k < 2; ++k) dst[m][k] = *(const LAS bf16x8*)(lds + PG8_SA(b, h) + aoff + m * 2048 + k * 1024); } while (0)
; #define PG8_LDB(dst, b, h) do { _Pragma("unroll") for (int n = 0; n < 2; ++n) _Pragma("unroll") for (int k = 0; k < 2; ++k) dst[n][k] = *(const LAS bf16x8*)(lds + PG8_SB(b, h) + boff + n * 2048 + k * 1024); } while (0)
; #define PG8_MMA(ai, bj, At, Bt) do { __builtin_amdgcn_s_setprio(1); _Pragma("unroll") for (int m = 0; m < 4; ++m) _Pragma("unroll") for (int n = 0; n < 2; ++n) _Pragma("unroll") for (int k = 0; k < 2; ++k) \
;         acc[ai][bj][m][n] = __builtin_amdgcn_mfma_f32_16x16x32_bf16(Bt[n][k], At[m][k], acc[ai][bj][m][n], 0, 0, 0); __builtin_amdgcn_s_setprio(0); } while (0)
; #define PG8_WAIT_V(n) asm volatile("s_waitcnt vmcnt(" #n ")" ::: "memory")
; #define PG8_WAIT_L(n) asm volatile("s_waitcnt lgkmcnt(" #n ")" ::: "memory")
; #define PG8_BAR __builtin_amdgcn_s_barrier()
; #define PG8_SCHED __builtin_amdgcn_sched_barrier(0)
; template <class Epi, class Sched, bool ALIGN_EPI>
; __device__ __forceinline__ void gemm_phase(LAS unsigned char* lds, const Gemm g, const Sched& S, const Epi& E) {
;     ...
;             PG8_LDB(B0, 0, 0); PG8_LDB(B1, 0, 1); PG8_SCHED; PG8_LDA(At, 0, 0); PG8_STAGE(PG8_SA(1, 1), a1 + hstepA, voffA);
;             PG8_WAIT_V(8); PG8_WAIT_L(0); PG8_BAR; PG8_MMA(0, 0, At, B0); PG8_MMA(0, 1, At, B1); PG8_BAR; PG8_SCHED;
;             PG8_LDA(At, 0, 1); PG8_STAGE(PG8_SB(0, 0), b2, voffB); PG8_STAGE(PG8_SB(0, 1), b2 + hstepB, voffB); PG8_STAGE(PG8_SA(0, 0), a2, voffA);
;             PG8_WAIT_V(8); PG8_WAIT_L(0); PG8_BAR; PG8_MMA(1, 0, At, B0); PG8_MMA(1, 1, At, B1); PG8_BAR; PG8_SCHED;
.LBB0_1409:
	ds_read_b128 v[132:135], v146
	ds_read_b128 v[136:139], v146 offset:1024
	ds_read_b128 v[160:163], v146 offset:2048
	ds_read_b128 v[164:167], v146 offset:3072
	ds_read_b128 v[168:171], v147
	ds_read_b128 v[172:175], v147 offset:1024
	ds_read_b128 v[180:183], v147 offset:2048
	ds_read_b128 v[184:187], v147 offset:3072
	s_add_u32 s8, s4, 0x100
	s_addc_u32 s9, s5, 0
	s_cmp_eq_u32 s39, 28
	s_cselect_b32 s46, s3, s8
	s_cselect_b32 s47, s2, s9
	s_cselect_b32 s12, s7, s23
	s_cselect_b32 s13, s6, s37
	s_add_u32 s10, s46, 0x80
	s_addc_u32 s11, s47, 0
	ds_read_b128 v[188:191], v148
	ds_read_b128 v[192:195], v148 offset:1024
	ds_read_b128 v[196:199], v148 offset:2048
	ds_read_b128 v[204:207], v148 offset:3072
	ds_read_b128 v[208:211], v148 offset:4096
	ds_read_b128 v[212:215], v148 offset:5120
	ds_read_b128 v[216:219], v148 offset:6144
	ds_read_b128 v[220:223], v148 offset:7168
	s_add_u32 s4, s4, 0x80080
	s_addc_u32 s5, s5, 0
	s_mov_b32 m0, s68
	s_nop 0
	global_load_lds_dwordx4 v140, s[4:5]
	s_nop 0
	s_mov_b32 m0, s69
	s_nop 0
	global_load_lds_dwordx4 v142, s[4:5]
	s_waitcnt vmcnt(8)
	s_waitcnt lgkmcnt(0)
	s_barrier
	v_mfma_f32_16x16x32_bf16 v[126:129], v[132:135], v[188:191], v[126:129]
	v_mfma_f32_16x16x32_bf16 v[122:125], v[160:163], v[188:191], v[122:125]
	v_mfma_f32_16x16x32_bf16 v[110:113], v[132:135], v[196:199], v[110:113]
	v_mfma_f32_16x16x32_bf16 v[106:109], v[160:163], v[196:199], v[106:109]
	v_mfma_f32_16x16x32_bf16 v[94:97], v[132:135], v[208:211], v[94:97]
	v_mfma_f32_16x16x32_bf16 v[90:93], v[160:163], v[208:211], v[90:93]
	v_mfma_f32_16x16x32_bf16 v[78:81], v[132:135], v[216:219], v[78:81]
	v_mfma_f32_16x16x32_bf16 v[74:77], v[160:163], v[216:219], v[74:77]
	v_mfma_f32_16x16x32_bf16 v[126:129], v[136:139], v[192:195], v[126:129]
	v_mfma_f32_16x16x32_bf16 v[122:125], v[164:167], v[192:195], v[122:125]
	v_mfma_f32_16x16x32_bf16 v[110:113], v[136:139], v[204:207], v[110:113]
	v_mfma_f32_16x16x32_bf16 v[106:109], v[164:167], v[204:207], v[106:109]
	v_mfma_f32_16x16x32_bf16 v[94:97], v[136:139], v[212:215], v[94:97]
	v_mfma_f32_16x16x32_bf16 v[90:93], v[164:167], v[212:215], v[90:93]
	v_mfma_f32_16x16x32_bf16 v[78:81], v[136:139], v[220:223], v[78:81]
	v_mfma_f32_16x16x32_bf16 v[74:77], v[164:167], v[220:223], v[74:77]
	v_mfma_f32_16x16x32_bf16 v[118:121], v[168:171], v[188:191], v[118:121]
	v_mfma_f32_16x16x32_bf16 v[114:117], v[180:183], v[188:191], v[114:117]
	v_mfma_f32_16x16x32_bf16 v[102:105], v[168:171], v[196:199], v[102:105]
	v_mfma_f32_16x16x32_bf16 v[98:101], v[180:183], v[196:199], v[98:101]
	v_mfma_f32_16x16x32_bf16 v[86:89], v[168:171], v[208:211], v[86:89]
	v_mfma_f32_16x16x32_bf16 v[82:85], v[180:183], v[208:211], v[82:85]
	v_mfma_f32_16x16x32_bf16 v[70:73], v[168:171], v[216:219], v[70:73]
	v_mfma_f32_16x16x32_bf16 v[66:69], v[180:183], v[216:219], v[66:69]
	v_mfma_f32_16x16x32_bf16 v[118:121], v[172:175], v[192:195], v[118:121]
	v_mfma_f32_16x16x32_bf16 v[114:117], v[184:187], v[192:195], v[114:117]
	v_mfma_f32_16x16x32_bf16 v[102:105], v[172:175], v[204:207], v[102:105]
	v_mfma_f32_16x16x32_bf16 v[98:101], v[184:187], v[204:207], v[98:101]
	v_mfma_f32_16x16x32_bf16 v[86:89], v[172:175], v[212:215], v[86:89]
	v_mfma_f32_16x16x32_bf16 v[82:85], v[184:187], v[212:215], v[82:85]
	v_mfma_f32_16x16x32_bf16 v[70:73], v[172:175], v[220:223], v[70:73]
	v_mfma_f32_16x16x32_bf16 v[66:69], v[184:187], v[220:223], v[66:69]
	s_barrier
	ds_read_b128 v[188:191], v148 offset:16384
	ds_read_b128 v[192:195], v148 offset:17408
	ds_read_b128 v[196:199], v148 offset:18432
	ds_read_b128 v[204:207], v148 offset:19456
	ds_read_b128 v[208:211], v148 offset:20480
	ds_read_b128 v[212:215], v148 offset:21504
	ds_read_b128 v[216:219], v148 offset:22528
	ds_read_b128 v[220:223], v148 offset:23552
	s_mov_b32 m0, s53
	s_nop 0
	global_load_lds_dwordx4 v141, s[12:13]
	s_nop 0
	s_mov_b32 m0, s54
	s_nop 0
	global_load_lds_dwordx4 v143, s[12:13]
	s_add_u32 s4, s12, 0x80000
	s_addc_u32 s5, s13, 0
	s_mov_b32 m0, s55
	s_nop 0
	global_load_lds_dwordx4 v141, s[4:5]
	s_nop 0
	s_mov_b32 m0, s56
	s_nop 0
	global_load_lds_dwordx4 v143, s[4:5]
	s_mov_b32 m0, s52
	s_nop 0
	global_load_lds_dwordx4 v140, s[46:47]
	s_nop 0
	s_mov_b32 m0, s57
	s_nop 0
	global_load_lds_dwordx4 v142, s[46:47]
	s_waitcnt vmcnt(8)
	s_waitcnt lgkmcnt(0)
	s_barrier
	v_mfma_f32_16x16x32_bf16 v[62:65], v[132:135], v[188:191], v[62:65]
	v_mfma_f32_16x16x32_bf16 v[58:61], v[160:163], v[188:191], v[58:61]
	v_mfma_f32_16x16x32_bf16 v[46:49], v[132:135], v[196:199], v[46:49]
	v_mfma_f32_16x16x32_bf16 v[42:45], v[160:163], v[196:199], v[42:45]
	v_mfma_f32_16x16x32_bf16 v[30:33], v[132:135], v[208:211], v[30:33]
	v_mfma_f32_16x16x32_bf16 v[26:29], v[160:163], v[208:211], v[26:29]
	v_mfma_f32_16x16x32_bf16 v[14:17], v[132:135], v[216:219], v[14:17]
	v_mfma_f32_16x16x32_bf16 v[10:13], v[160:163], v[216:219], v[10:13]
	v_mfma_f32_16x16x32_bf16 v[62:65], v[136:139], v[192:195], v[62:65]
	v_mfma_f32_16x16x32_bf16 v[58:61], v[164:167], v[192:195], v[58:61]
	v_mfma_f32_16x16x32_bf16 v[46:49], v[136:139], v[204:207], v[46:49]
	v_mfma_f32_16x16x32_bf16 v[42:45], v[164:167], v[204:207], v[42:45]
	v_mfma_f32_16x16x32_bf16 v[30:33], v[136:139], v[212:215], v[30:33]
	v_mfma_f32_16x16x32_bf16 v[26:29], v[164:167], v[212:215], v[26:29]
	v_mfma_f32_16x16x32_bf16 v[14:17], v[136:139], v[220:223], v[14:17]
	v_mfma_f32_16x16x32_bf16 v[10:13], v[164:167], v[220:223], v[10:13]
	v_mfma_f32_16x16x32_bf16 v[54:57], v[168:171], v[188:191], v[54:57]
	v_mfma_f32_16x16x32_bf16 v[50:53], v[180:183], v[188:191], v[50:53]
	v_mfma_f32_16x16x32_bf16 v[38:41], v[168:171], v[196:199], v[38:41]
	v_mfma_f32_16x16x32_bf16 v[34:37], v[180:183], v[196:199], v[34:37]
	v_mfma_f32_16x16x32_bf16 v[22:25], v[168:171], v[208:211], v[22:25]
	v_mfma_f32_16x16x32_bf16 v[18:21], v[180:183], v[208:211], v[18:21]
	v_mfma_f32_16x16x32_bf16 v[6:9], v[168:171], v[216:219], v[6:9]
	v_mfma_f32_16x16x32_bf16 v[2:5], v[180:183], v[216:219], v[2:5]
	v_mfma_f32_16x16x32_bf16 v[54:57], v[172:175], v[192:195], v[54:57]
	v_mfma_f32_16x16x32_bf16 v[50:53], v[184:187], v[192:195], v[50:53]
	v_mfma_f32_16x16x32_bf16 v[38:41], v[172:175], v[204:207], v[38:41]
	v_mfma_f32_16x16x32_bf16 v[34:37], v[184:187], v[204:207], v[34:37]
	v_mfma_f32_16x16x32_bf16 v[22:25], v[172:175], v[212:215], v[22:25]
	v_mfma_f32_16x16x32_bf16 v[18:21], v[184:187], v[212:215], v[18:21]
	v_mfma_f32_16x16x32_bf16 v[6:9], v[172:175], v[220:223], v[6:9]
	v_mfma_f32_16x16x32_bf16 v[2:5], v[184:187], v[220:223], v[2:5]
	s_barrier
; #define PG8_STAGE(bufoff, gbase, voff) do { _Pragma("unroll") for (int _i = 0; _i < 2; ++_i) { unsigned keep_; \
;         asm volatile("s_mov_b32 %0, m0\n\ts_mov_b32 m0, %3\n\ts_nop 0\n\tglobal_load_lds_dwordx4 %1, %2\n\ts_mov_b32 m0, %0" \
;             : "=&s"(keep_) : "v"((voff)[_i]), "s"((const void*)(gbase)), "s"(ldsb0 + (unsigned)(bufoff) + (unsigned)(_i * 8192)) : "memory"); } } while (0)
; #define PG8_LDA(dst, b, h) do { _Pragma("unroll") for (int m = 0; m < 4; ++m) _Pragma("unroll") for (int k = 0; k < 2; ++k) dst[m][k] = *(const LAS bf16x8*)(lds + PG8_SA(b, h) + aoff + m * 2048 + k * 1024); } while (0)
; #define PG8_LDB(dst, b, h) do { _Pragma("unroll") for (int n = 0; n < 2; ++n) _Pragma("unroll") for (int k = 0; k < 2; ++k) dst[n][k] = *(const LAS bf16x8*)(lds + PG8_SB(b, h) + boff + n * 2048 + k * 1024); } while (0)
; #define PG8_MMA(ai, bj, At, Bt) do { __builtin_amdgcn_s_setprio(1); _Pragma("unroll") for (int m = 0; m < 4; ++m) _Pragma("unroll") for (int n = 0; n < 2; ++n) _Pragma("unroll") for (int k = 0; k < 2; ++k) \
;         acc[ai][bj][m][n] = __builtin_amdgcn_mfma_f32_16x16x32_bf16(Bt[n][k], At[m][k], acc[ai][bj][m][n], 0, 0, 0); __builtin_amdgcn_s_setprio(0); } while (0)
; #define PG8_WAIT_V(n) asm volatile("s_waitcnt vmcnt(" #n ")" ::: "memory")
; #define PG8_WAIT_L(n) asm volatile("s_waitcnt lgkmcnt(" #n ")" ::: "memory")
; #define PG8_BAR __builtin_amdgcn_s_barrier()
; #define PG8_SCHED __builtin_amdgcn_sched_barrier(0)
; template <class Epi, class Sched, bool ALIGN_EPI>
; __device__ __forceinline__ void gemm_phase(LAS unsigned char* lds, const Gemm g, const Sched& S, const Epi& E) {
;     ...
;             PG8_LDB(B0, 1, 0); PG8_LDB(B1, 1, 1); PG8_SCHED; PG8_LDA(At, 1, 0); PG8_STAGE(PG8_SA(0, 1), a2 + hstepA, voffA);
;             PG8_WAIT_V(8); PG8_WAIT_L(0); PG8_BAR; PG8_MMA(0, 0, At, B0); PG8_MMA(0, 1, At, B1); PG8_BAR; PG8_SCHED;
;             PG8_LDA(At, 1, 1); PG8_STAGE(PG8_SB(1, 0), b3, voffB); PG8_STAGE(PG8_SB(1, 1), b3 + hstepB, voffB); PG8_STAGE(PG8_SA(1, 0), a3, voffA);
;             PG8_WAIT_V(8); PG8_WAIT_L(0); PG8_BAR; PG8_MMA(1, 0, At, B0); PG8_MMA(1, 1, At, B1); PG8_BAR; PG8_SCHED;
;         }
	ds_read_b128 v[132:135], v149
	ds_read_b128 v[136:139], v149 offset:1024
	ds_read_b128 v[160:163], v149 offset:2048
	ds_read_b128 v[164:167], v149 offset:3072
	ds_read_b128 v[168:171], v150
	ds_read_b128 v[172:175], v150 offset:1024
	ds_read_b128 v[180:183], v150 offset:2048
	ds_read_b128 v[184:187], v150 offset:3072
	ds_read_b128 v[188:191], v148 offset:32768
	ds_read_b128 v[192:195], v148 offset:33792
	ds_read_b128 v[196:199], v148 offset:34816
	ds_read_b128 v[204:207], v148 offset:35840
	ds_read_b128 v[208:211], v148 offset:36864
	ds_read_b128 v[212:215], v148 offset:37888
	ds_read_b128 v[216:219], v148 offset:38912
	ds_read_b128 v[220:223], v148 offset:39936
	s_add_u32 s4, s46, 0x80000
	s_addc_u32 s5, s47, 0
	s_mov_b32 m0, s59
	s_nop 0
	global_load_lds_dwordx4 v140, s[4:5]
	s_nop 0
	s_mov_b32 m0, s61
	s_nop 0
	global_load_lds_dwordx4 v142, s[4:5]
	s_waitcnt vmcnt(8)
	s_waitcnt lgkmcnt(0)
	s_barrier
	v_mfma_f32_16x16x32_bf16 v[126:129], v[132:135], v[188:191], v[126:129]
	v_mfma_f32_16x16x32_bf16 v[122:125], v[160:163], v[188:191], v[122:125]
	v_mfma_f32_16x16x32_bf16 v[110:113], v[132:135], v[196:199], v[110:113]
	v_mfma_f32_16x16x32_bf16 v[106:109], v[160:163], v[196:199], v[106:109]
	v_mfma_f32_16x16x32_bf16 v[94:97], v[132:135], v[208:211], v[94:97]
	v_mfma_f32_16x16x32_bf16 v[90:93], v[160:163], v[208:211], v[90:93]
	v_mfma_f32_16x16x32_bf16 v[78:81], v[132:135], v[216:219], v[78:81]
	v_mfma_f32_16x16x32_bf16 v[74:77], v[160:163], v[216:219], v[74:77]
	v_mfma_f32_16x16x32_bf16 v[126:129], v[136:139], v[192:195], v[126:129]
	v_mfma_f32_16x16x32_bf16 v[122:125], v[164:167], v[192:195], v[122:125]
	v_mfma_f32_16x16x32_bf16 v[110:113], v[136:139], v[204:207], v[110:113]
	v_mfma_f32_16x16x32_bf16 v[106:109], v[164:167], v[204:207], v[106:109]
	v_mfma_f32_16x16x32_bf16 v[94:97], v[136:139], v[212:215], v[94:97]
	v_mfma_f32_16x16x32_bf16 v[90:93], v[164:167], v[212:215], v[90:93]
	v_mfma_f32_16x16x32_bf16 v[78:81], v[136:139], v[220:223], v[78:81]
	v_mfma_f32_16x16x32_bf16 v[74:77], v[164:167], v[220:223], v[74:77]
	v_mfma_f32_16x16x32_bf16 v[118:121], v[168:171], v[188:191], v[118:121]
	v_mfma_f32_16x16x32_bf16 v[114:117], v[180:183], v[188:191], v[114:117]
	v_mfma_f32_16x16x32_bf16 v[102:105], v[168:171], v[196:199], v[102:105]
	v_mfma_f32_16x16x32_bf16 v[98:101], v[180:183], v[196:199], v[98:101]
	v_mfma_f32_16x16x32_bf16 v[86:89], v[168:171], v[208:211], v[86:89]
	v_mfma_f32_16x16x32_bf16 v[82:85], v[180:183], v[208:211], v[82:85]
	v_mfma_f32_16x16x32_bf16 v[70:73], v[168:171], v[216:219], v[70:73]
	v_mfma_f32_16x16x32_bf16 v[66:69], v[180:183], v[216:219], v[66:69]
	v_mfma_f32_16x16x32_bf16 v[118:121], v[172:175], v[192:195], v[118:121]
	v_mfma_f32_16x16x32_bf16 v[114:117], v[184:187], v[192:195], v[114:117]
	v_mfma_f32_16x16x32_bf16 v[102:105], v[172:175], v[204:207], v[102:105]
	v_mfma_f32_16x16x32_bf16 v[98:101], v[184:187], v[204:207], v[98:101]
	v_mfma_f32_16x16x32_bf16 v[86:89], v[172:175], v[212:215], v[86:89]
	v_mfma_f32_16x16x32_bf16 v[82:85], v[184:187], v[212:215], v[82:85]
	v_mfma_f32_16x16x32_bf16 v[70:73], v[172:175], v[220:223], v[70:73]
	v_mfma_f32_16x16x32_bf16 v[66:69], v[184:187], v[220:223], v[66:69]
	s_barrier
	ds_read_b128 v[188:191], v148 offset:49152
	ds_read_b128 v[192:195], v148 offset:50176
	ds_read_b128 v[196:199], v148 offset:51200
	ds_read_b128 v[204:207], v148 offset:52224
	ds_read_b128 v[208:211], v148 offset:53248
	ds_read_b128 v[212:215], v148 offset:54272
	ds_read_b128 v[216:219], v148 offset:55296
	ds_read_b128 v[220:223], v148 offset:56320
	s_add_u32 s4, s12, 0x80
	s_addc_u32 s5, s13, 0
	s_mov_b32 m0, s62
	s_nop 0
	global_load_lds_dwordx4 v141, s[4:5]
	s_nop 0
	s_mov_b32 m0, s63
	s_nop 0
	global_load_lds_dwordx4 v143, s[4:5]
	s_add_u32 s4, s12, 0x80080
	s_addc_u32 s5, s13, 0
	s_mov_b32 m0, s66
	s_nop 0
	global_load_lds_dwordx4 v141, s[4:5]
	s_nop 0
	s_mov_b32 m0, s67
	s_nop 0
	global_load_lds_dwordx4 v143, s[4:5]
	s_mov_b32 m0, s64
	s_nop 0
	global_load_lds_dwordx4 v140, s[10:11]
	s_nop 0
	s_mov_b32 m0, s65
	s_nop 0
	global_load_lds_dwordx4 v142, s[10:11]
	s_waitcnt vmcnt(8)
	s_waitcnt lgkmcnt(0)
	s_barrier
	v_mfma_f32_16x16x32_bf16 v[62:65], v[132:135], v[188:191], v[62:65]
	v_mfma_f32_16x16x32_bf16 v[58:61], v[160:163], v[188:191], v[58:61]
	v_mfma_f32_16x16x32_bf16 v[46:49], v[132:135], v[196:199], v[46:49]
	v_mfma_f32_16x16x32_bf16 v[42:45], v[160:163], v[196:199], v[42:45]
	v_mfma_f32_16x16x32_bf16 v[30:33], v[132:135], v[208:211], v[30:33]
	v_mfma_f32_16x16x32_bf16 v[26:29], v[160:163], v[208:211], v[26:29]
	v_mfma_f32_16x16x32_bf16 v[14:17], v[132:135], v[216:219], v[14:17]
	v_mfma_f32_16x16x32_bf16 v[10:13], v[160:163], v[216:219], v[10:13]
	v_mfma_f32_16x16x32_bf16 v[62:65], v[136:139], v[192:195], v[62:65]
	v_mfma_f32_16x16x32_bf16 v[58:61], v[164:167], v[192:195], v[58:61]
	v_mfma_f32_16x16x32_bf16 v[46:49], v[136:139], v[204:207], v[46:49]
	v_mfma_f32_16x16x32_bf16 v[42:45], v[164:167], v[204:207], v[42:45]
	v_mfma_f32_16x16x32_bf16 v[30:33], v[136:139], v[212:215], v[30:33]
	v_mfma_f32_16x16x32_bf16 v[26:29], v[164:167], v[212:215], v[26:29]
	v_mfma_f32_16x16x32_bf16 v[14:17], v[136:139], v[220:223], v[14:17]
	v_mfma_f32_16x16x32_bf16 v[10:13], v[164:167], v[220:223], v[10:13]
	v_mfma_f32_16x16x32_bf16 v[54:57], v[168:171], v[188:191], v[54:57]
	v_mfma_f32_16x16x32_bf16 v[50:53], v[180:183], v[188:191], v[50:53]
	v_mfma_f32_16x16x32_bf16 v[38:41], v[168:171], v[196:199], v[38:41]
	v_mfma_f32_16x16x32_bf16 v[34:37], v[180:183], v[196:199], v[34:37]
	v_mfma_f32_16x16x32_bf16 v[22:25], v[168:171], v[208:211], v[22:25]
	v_mfma_f32_16x16x32_bf16 v[18:21], v[180:183], v[208:211], v[18:21]
	v_mfma_f32_16x16x32_bf16 v[6:9], v[168:171], v[216:219], v[6:9]
	v_mfma_f32_16x16x32_bf16 v[2:5], v[180:183], v[216:219], v[2:5]
	v_mfma_f32_16x16x32_bf16 v[54:57], v[172:175], v[192:195], v[54:57]
	v_mfma_f32_16x16x32_bf16 v[50:53], v[184:187], v[192:195], v[50:53]
	v_mfma_f32_16x16x32_bf16 v[38:41], v[172:175], v[204:207], v[38:41]
	v_mfma_f32_16x16x32_bf16 v[34:37], v[184:187], v[204:207], v[34:37]
	v_mfma_f32_16x16x32_bf16 v[22:25], v[172:175], v[212:215], v[22:25]
	v_mfma_f32_16x16x32_bf16 v[18:21], v[184:187], v[212:215], v[18:21]
	v_mfma_f32_16x16x32_bf16 v[6:9], v[172:175], v[220:223], v[6:9]
	v_mfma_f32_16x16x32_bf16 v[2:5], v[184:187], v[220:223], v[2:5]
	s_barrier
	s_add_i32 s39, s39, 2
	s_add_u32 s23, s23, 0x100
	s_addc_u32 s37, s37, 0
	s_cmp_gt_u32 s39, 29
	s_mov_b64 s[4:5], s[8:9]
	s_cbranch_scc0 .LBB0_1409
	s_and_b64 vcc, exec, s[34:35]
	s_cbranch_vccz .LBB0_1412
	s_barrier

; #define LAS __attribute__((address_space(3)))
; #define REP(k) for (int rep_ = 0; rep_ < ((DUP) == (k) ? 2 : 1); ++rep_)
; __global__ void __launch_bounds__(NT, 2) fwd(Args args) {
;     ...
;         small_gemm<2>(lds, 3 * DM / 32, DM, DM, DM, MapW2{HB + (size_t)SEQ * DM, WQKV, DM}, Epi2<EpiQS>{EpiQS{ssq + 2 * MPAD, QB, KB, VB, out + O_SKS, out + O_SVS}}, G, bx);
;     }
;     xcd_barrier(bar);
;     REP(12) {
;         for (int uix = bx; uix < 512 + DECB * SH; uix += G) {
;             att::UnitDesc D;
;             if (uix < 512) { const int h = uix & 15, q5 = (uix >> 4) & 15, qb = uix < 256 ? 31 - q5 : q5;
;                 D.Q = QB + (size_t)qb * 256 * DM + h * HD; D.Kn = KB + h * HD; D.Vn = VB + h * HD; D.Kc = nullptr; D.Vc = nullptr; D.cpitch = 0; D.npast = 0;
;                 D.cum = nullptr; D.cstride = 0; D.O = CAT + (size_t)qb * 256 * DM + h * HD; D.P0 = qb * 256; D.nq = 256; D.nk = qb * 256 + 256; D.kmax = 0.f;
;                 att::unit<1, false>((LAS char*)lds, D);
.LBB0_1606:
	s_or_b64 exec, exec, s[4:5]
	s_cmpk_gt_i32 s94, 0x27f
	s_waitcnt lgkmcnt(0)
	s_barrier
	s_setprio 0
	s_cbranch_scc1 .LBB0_1911
	v_readlane_b32 s2, v242, 14
	v_readlane_b32 s3, v242, 15
	s_lshl_b32 s3, s76, 7
	s_mov_b32 s96, 0xfff80000
	s_mov_b32 s84, 0xfffc0000
	s_add_i32 s88, s2, 0xfffffe00
	s_lshl_b32 s89, s2, 7
	v_writelane_b32 v242, s3, 13
	s_mov_b32 s87, 0
	s_waitcnt vmcnt(0)
	v_mov_b32_e32 v163, 0
	s_add_i32 s3, 0, 0x10000
	s_mov_b64 s[92:93], 0x1f00000
	s_mov_b64 s[94:95], 0x1f40000
	s_mov_b32 s97, -1
	s_mov_b32 s85, -1
	s_mov_b32 s78, s2
	v_writelane_b32 v242, s3, 12
	s_branch .LBB0_1611

.LBB0_1977:
	s_or_b64 exec, exec, s[4:5]
	s_mov_b64 s[10:11], s[0:1]
	s_mov_b64 s[12:13], s[0:1]
	s_mov_b64 s[8:9], s[0:1]
	s_mov_b64 s[2:3], s[0:1]
	s_waitcnt lgkmcnt(0)
	s_barrier
	v_readlane_b32 s99, v242, 0
	s_nop 1
	s_cmp_gt_u32 s99, 3
	s_cbranch_scc0 .Lsp_8
	s_setprio 1

; #define PG8_STAGE(bufoff, gbase, voff) do { _Pragma("unroll") for (int _i = 0; _i < 2; ++_i) { unsigned keep_; \
;         asm volatile("s_mov_b32 %0, m0\n\ts_mov_b32 m0, %3\n\ts_nop 0\n\tglobal_load_lds_dwordx4 %1, %2\n\ts_mov_b32 m0, %0" \
;             : "=&s"(keep_) : "v"((voff)[_i]), "s"((const void*)(gbase)), "s"(ldsb0 + (unsigned)(bufoff) + (unsigned)(_i * 8192)) : "memory"); } } while (0)
; #define PG8_LDA(dst, b, h) do { _Pragma("unroll") for (int m = 0; m < 4; ++m) _Pragma("unroll") for (int k = 0; k < 2; ++k) dst[m][k] = *(const LAS bf16x8*)(lds + PG8_SA(b, h) + aoff + m * 2048 + k * 1024); } while (0)
; #define PG8_LDB(dst, b, h) do { _Pragma("unroll") for (int n = 0; n < 2; ++n) _Pragma("unroll") for (int k = 0; k < 2; ++k) dst[n][k] = *(const LAS bf16x8*)(lds + PG8_SB(b, h) + boff + n * 2048 + k * 1024); } while (0)
; #define PG8_MMA(ai, bj, At, Bt) do { __builtin_amdgcn_s_setprio(1); _Pragma("unroll") for (int m = 0; m < 4; ++m) _Pragma("unroll") for (int n = 0; n < 2; ++n) _Pragma("unroll") for (int k = 0; k < 2; ++k) \
;         acc[ai][bj][m][n] = __builtin_amdgcn_mfma_f32_16x16x32_bf16(Bt[n][k], At[m][k], acc[ai][bj][m][n], 0, 0, 0); __builtin_amdgcn_s_setprio(0); } while (0)
; #define PG8_WAIT_V(n) asm volatile("s_waitcnt vmcnt(" #n ")" ::: "memory")
; #define PG8_WAIT_L(n) asm volatile("s_waitcnt lgkmcnt(" #n ")" ::: "memory")
; #define PG8_BAR __builtin_amdgcn_s_barrier()
; #define PG8_SCHED __builtin_amdgcn_sched_barrier(0)
; template <class Epi, class Sched, bool ALIGN_EPI>
; __device__ __forceinline__ void gemm_phase(LAS unsigned char* lds, const Gemm g, const Sched& S, const Epi& E) {
;     ...
;             PG8_LDB(B0, 0, 0); PG8_LDB(B1, 0, 1); PG8_SCHED; PG8_LDA(At, 0, 0); PG8_STAGE(PG8_SA(1, 1), a1 + hstepA, voffA);
;             PG8_WAIT_V(8); PG8_WAIT_L(0); PG8_BAR; PG8_MMA(0, 0, At, B0); PG8_MMA(0, 1, At, B1); PG8_BAR; PG8_SCHED;
;             PG8_LDA(At, 0, 1); PG8_STAGE(PG8_SB(0, 0), b2, voffB); PG8_STAGE(PG8_SB(0, 1), b2 + hstepB, voffB); PG8_STAGE(PG8_SA(0, 0), a2, voffA);
;             PG8_WAIT_V(8); PG8_WAIT_L(0); PG8_BAR; PG8_MMA(1, 0, At, B0); PG8_MMA(1, 1, At, B1); PG8_BAR; PG8_SCHED;
.LBB0_1994:
	ds_read_b128 v[110:113], v206
	ds_read_b128 v[126:129], v206 offset:1024
	ds_read_b128 v[130:133], v206 offset:2048
	ds_read_b128 v[142:145], v206 offset:3072
	ds_read_b128 v[146:149], v207
	ds_read_b128 v[150:153], v207 offset:1024
	ds_read_b128 v[154:157], v207 offset:2048
	ds_read_b128 v[158:161], v207 offset:3072
	s_cmp_eq_u32 s59, 28
	s_cselect_b32 s34, s5, s19
	s_cselect_b32 s35, s3, s21
	s_cselect_b32 s30, s7, s57
	s_cselect_b32 s31, s6, s58
	s_add_u32 s28, s34, 0x80
	s_addc_u32 s29, s35, 0
	ds_read_b128 v[162:165], v208
	ds_read_b128 v[166:169], v208 offset:1024
	ds_read_b128 v[170:173], v208 offset:2048
	ds_read_b128 v[174:177], v208 offset:3072
	ds_read_b128 v[188:191], v208 offset:4096
	ds_read_b128 v[192:195], v208 offset:5120
	ds_read_b128 v[196:199], v208 offset:6144
	ds_read_b128 v[212:215], v208 offset:7168
	s_mov_b32 m0, s55
	s_nop 0
	global_load_lds_dwordx4 v179, s[26:27]
	s_nop 0
	s_mov_b32 m0, s56
	s_nop 0
	global_load_lds_dwordx4 v201, s[26:27]
	s_waitcnt vmcnt(8)
	s_waitcnt lgkmcnt(0)
	s_barrier
	v_mfma_f32_16x16x32_bf16 v[138:141], v[110:113], v[162:165], v[138:141]
	v_mfma_f32_16x16x32_bf16 v[134:137], v[130:133], v[162:165], v[134:137]
	v_mfma_f32_16x16x32_bf16 v[114:117], v[110:113], v[170:173], v[114:117]
	v_mfma_f32_16x16x32_bf16 v[106:109], v[130:133], v[170:173], v[106:109]
	v_mfma_f32_16x16x32_bf16 v[94:97], v[110:113], v[188:191], v[94:97]
	v_mfma_f32_16x16x32_bf16 v[90:93], v[130:133], v[188:191], v[90:93]
	v_mfma_f32_16x16x32_bf16 v[78:81], v[110:113], v[196:199], v[78:81]
	v_mfma_f32_16x16x32_bf16 v[74:77], v[130:133], v[196:199], v[74:77]
	v_mfma_f32_16x16x32_bf16 v[138:141], v[126:129], v[166:169], v[138:141]
	v_mfma_f32_16x16x32_bf16 v[134:137], v[142:145], v[166:169], v[134:137]
	v_mfma_f32_16x16x32_bf16 v[114:117], v[126:129], v[174:177], v[114:117]
	v_mfma_f32_16x16x32_bf16 v[106:109], v[142:145], v[174:177], v[106:109]
	v_mfma_f32_16x16x32_bf16 v[94:97], v[126:129], v[192:195], v[94:97]
	v_mfma_f32_16x16x32_bf16 v[90:93], v[142:145], v[192:195], v[90:93]
	v_mfma_f32_16x16x32_bf16 v[78:81], v[126:129], v[212:215], v[78:81]
	v_mfma_f32_16x16x32_bf16 v[74:77], v[142:145], v[212:215], v[74:77]
	v_mfma_f32_16x16x32_bf16 v[122:125], v[146:149], v[162:165], v[122:125]
	v_mfma_f32_16x16x32_bf16 v[118:121], v[154:157], v[162:165], v[118:121]
	v_mfma_f32_16x16x32_bf16 v[102:105], v[146:149], v[170:173], v[102:105]
	v_mfma_f32_16x16x32_bf16 v[98:101], v[154:157], v[170:173], v[98:101]
	v_mfma_f32_16x16x32_bf16 v[86:89], v[146:149], v[188:191], v[86:89]
	v_mfma_f32_16x16x32_bf16 v[82:85], v[154:157], v[188:191], v[82:85]
	v_mfma_f32_16x16x32_bf16 v[70:73], v[146:149], v[196:199], v[70:73]
	v_mfma_f32_16x16x32_bf16 v[66:69], v[154:157], v[196:199], v[66:69]
	v_mfma_f32_16x16x32_bf16 v[122:125], v[150:153], v[166:169], v[122:125]
	v_mfma_f32_16x16x32_bf16 v[118:121], v[158:161], v[166:169], v[118:121]
	v_mfma_f32_16x16x32_bf16 v[102:105], v[150:153], v[174:177], v[102:105]
	v_mfma_f32_16x16x32_bf16 v[98:101], v[158:161], v[174:177], v[98:101]
	v_mfma_f32_16x16x32_bf16 v[86:89], v[150:153], v[192:195], v[86:89]
	v_mfma_f32_16x16x32_bf16 v[82:85], v[158:161], v[192:195], v[82:85]
	v_mfma_f32_16x16x32_bf16 v[70:73], v[150:153], v[212:215], v[70:73]
	v_mfma_f32_16x16x32_bf16 v[66:69], v[158:161], v[212:215], v[66:69]
	s_barrier
	ds_read_b128 v[162:165], v208 offset:16384
	ds_read_b128 v[166:169], v208 offset:17408
	ds_read_b128 v[170:173], v208 offset:18432
	ds_read_b128 v[174:177], v208 offset:19456
	ds_read_b128 v[188:191], v208 offset:20480
	ds_read_b128 v[192:195], v208 offset:21504
	ds_read_b128 v[196:199], v208 offset:22528
	ds_read_b128 v[212:215], v208 offset:23552
	s_mov_b32 m0, s42
	s_nop 0
	global_load_lds_dwordx4 v200, s[30:31]
	s_nop 0
	s_mov_b32 m0, s43
	s_nop 0
	global_load_lds_dwordx4 v203, s[30:31]
	s_add_u32 s60, s30, 0x80000
	s_addc_u32 s61, s31, 0
	s_mov_b32 m0, s44
	s_nop 0
	global_load_lds_dwordx4 v200, s[60:61]
	s_nop 0
	s_mov_b32 m0, s45
	s_nop 0
	global_load_lds_dwordx4 v203, s[60:61]
	s_mov_b32 m0, s41
	s_nop 0
	global_load_lds_dwordx4 v179, s[34:35]
	s_nop 0
	s_mov_b32 m0, s46
	s_nop 0
	global_load_lds_dwordx4 v201, s[34:35]
	s_waitcnt vmcnt(8)
	s_waitcnt lgkmcnt(0)
	s_barrier
	v_mfma_f32_16x16x32_bf16 v[62:65], v[110:113], v[162:165], v[62:65]
	v_mfma_f32_16x16x32_bf16 v[58:61], v[130:133], v[162:165], v[58:61]
	v_mfma_f32_16x16x32_bf16 v[46:49], v[110:113], v[170:173], v[46:49]
	v_mfma_f32_16x16x32_bf16 v[42:45], v[130:133], v[170:173], v[42:45]
	v_mfma_f32_16x16x32_bf16 v[30:33], v[110:113], v[188:191], v[30:33]
	v_mfma_f32_16x16x32_bf16 v[26:29], v[130:133], v[188:191], v[26:29]
	v_mfma_f32_16x16x32_bf16 v[14:17], v[110:113], v[196:199], v[14:17]
	v_mfma_f32_16x16x32_bf16 v[10:13], v[130:133], v[196:199], v[10:13]
	v_mfma_f32_16x16x32_bf16 v[62:65], v[126:129], v[166:169], v[62:65]
	v_mfma_f32_16x16x32_bf16 v[58:61], v[142:145], v[166:169], v[58:61]
	v_mfma_f32_16x16x32_bf16 v[46:49], v[126:129], v[174:177], v[46:49]
	v_mfma_f32_16x16x32_bf16 v[42:45], v[142:145], v[174:177], v[42:45]
	v_mfma_f32_16x16x32_bf16 v[30:33], v[126:129], v[192:195], v[30:33]
	v_mfma_f32_16x16x32_bf16 v[26:29], v[142:145], v[192:195], v[26:29]
	v_mfma_f32_16x16x32_bf16 v[14:17], v[126:129], v[212:215], v[14:17]
	v_mfma_f32_16x16x32_bf16 v[10:13], v[142:145], v[212:215], v[10:13]
	v_mfma_f32_16x16x32_bf16 v[54:57], v[146:149], v[162:165], v[54:57]
	v_mfma_f32_16x16x32_bf16 v[50:53], v[154:157], v[162:165], v[50:53]
	v_mfma_f32_16x16x32_bf16 v[38:41], v[146:149], v[170:173], v[38:41]
	v_mfma_f32_16x16x32_bf16 v[34:37], v[154:157], v[170:173], v[34:37]
	v_mfma_f32_16x16x32_bf16 v[22:25], v[146:149], v[188:191], v[22:25]
	v_mfma_f32_16x16x32_bf16 v[18:21], v[154:157], v[188:191], v[18:21]
	v_mfma_f32_16x16x32_bf16 v[6:9], v[146:149], v[196:199], v[6:9]
	v_mfma_f32_16x16x32_bf16 v[2:5], v[154:157], v[196:199], v[2:5]
	v_mfma_f32_16x16x32_bf16 v[54:57], v[150:153], v[166:169], v[54:57]
	v_mfma_f32_16x16x32_bf16 v[50:53], v[158:161], v[166:169], v[50:53]
	v_mfma_f32_16x16x32_bf16 v[38:41], v[150:153], v[174:177], v[38:41]
	v_mfma_f32_16x16x32_bf16 v[34:37], v[158:161], v[174:177], v[34:37]
	v_mfma_f32_16x16x32_bf16 v[22:25], v[150:153], v[192:195], v[22:25]
	v_mfma_f32_16x16x32_bf16 v[18:21], v[158:161], v[192:195], v[18:21]
	v_mfma_f32_16x16x32_bf16 v[6:9], v[150:153], v[212:215], v[6:9]
	v_mfma_f32_16x16x32_bf16 v[2:5], v[158:161], v[212:215], v[2:5]
	s_barrier
; #define PG8_STAGE(bufoff, gbase, voff) do { _Pragma("unroll") for (int _i = 0; _i < 2; ++_i) { unsigned keep_; \
;         asm volatile("s_mov_b32 %0, m0\n\ts_mov_b32 m0, %3\n\ts_nop 0\n\tglobal_load_lds_dwordx4 %1, %2\n\ts_mov_b32 m0, %0" \
;             : "=&s"(keep_) : "v"((voff)[_i]), "s"((const void*)(gbase)), "s"(ldsb0 + (unsigned)(bufoff) + (unsigned)(_i * 8192)) : "memory"); } } while (0)
; #define PG8_LDA(dst, b, h) do { _Pragma("unroll") for (int m = 0; m < 4; ++m) _Pragma("unroll") for (int k = 0; k < 2; ++k) dst[m][k] = *(const LAS bf16x8*)(lds + PG8_SA(b, h) + aoff + m * 2048 + k * 1024); } while (0)
; #define PG8_LDB(dst, b, h) do { _Pragma("unroll") for (int n = 0; n < 2; ++n) _Pragma("unroll") for (int k = 0; k < 2; ++k) dst[n][k] = *(const LAS bf16x8*)(lds + PG8_SB(b, h) + boff + n * 2048 + k * 1024); } while (0)
; #define PG8_MMA(ai, bj, At, Bt) do { __builtin_amdgcn_s_setprio(1); _Pragma("unroll") for (int m = 0; m < 4; ++m) _Pragma("unroll") for (int n = 0; n < 2; ++n) _Pragma("unroll") for (int k = 0; k < 2; ++k) \
;         acc[ai][bj][m][n] = __builtin_amdgcn_mfma_f32_16x16x32_bf16(Bt[n][k], At[m][k], acc[ai][bj][m][n], 0, 0, 0); __builtin_amdgcn_s_setprio(0); } while (0)
; #define PG8_WAIT_V(n) asm volatile("s_waitcnt vmcnt(" #n ")" ::: "memory")
; #define PG8_WAIT_L(n) asm volatile("s_waitcnt lgkmcnt(" #n ")" ::: "memory")
; #define PG8_BAR __builtin_amdgcn_s_barrier()
; #define PG8_SCHED __builtin_amdgcn_sched_barrier(0)
; template <class Epi, class Sched, bool ALIGN_EPI>
; __device__ __forceinline__ void gemm_phase(LAS unsigned char* lds, const Gemm g, const Sched& S, const Epi& E) {
;     ...
;             PG8_LDB(B0, 1, 0); PG8_LDB(B1, 1, 1); PG8_SCHED; PG8_LDA(At, 1, 0); PG8_STAGE(PG8_SA(0, 1), a2 + hstepA, voffA);
;             PG8_WAIT_V(8); PG8_WAIT_L(0); PG8_BAR; PG8_MMA(0, 0, At, B0); PG8_MMA(0, 1, At, B1); PG8_BAR; PG8_SCHED;
;             PG8_LDA(At, 1, 1); PG8_STAGE(PG8_SB(1, 0), b3, voffB); PG8_STAGE(PG8_SB(1, 1), b3 + hstepB, voffB); PG8_STAGE(PG8_SA(1, 0), a3, voffA);
;             PG8_WAIT_V(8); PG8_WAIT_L(0); PG8_BAR; PG8_MMA(1, 0, At, B0); PG8_MMA(1, 1, At, B1); PG8_BAR; PG8_SCHED;
;         }
	ds_read_b128 v[110:113], v209
	ds_read_b128 v[126:129], v209 offset:1024
	ds_read_b128 v[130:133], v209 offset:2048
	ds_read_b128 v[142:145], v209 offset:3072
	ds_read_b128 v[146:149], v210
	ds_read_b128 v[150:153], v210 offset:1024
	ds_read_b128 v[154:157], v210 offset:2048
	ds_read_b128 v[158:161], v210 offset:3072
	ds_read_b128 v[162:165], v208 offset:32768
	ds_read_b128 v[166:169], v208 offset:33792
	ds_read_b128 v[170:173], v208 offset:34816
	ds_read_b128 v[174:177], v208 offset:35840
	ds_read_b128 v[188:191], v208 offset:36864
	ds_read_b128 v[192:195], v208 offset:37888
	ds_read_b128 v[196:199], v208 offset:38912
	ds_read_b128 v[212:215], v208 offset:39936
	s_add_u32 s34, s34, 0x80000
	s_addc_u32 s35, s35, 0
	s_mov_b32 m0, s47
	s_nop 0
	global_load_lds_dwordx4 v179, s[34:35]
	s_nop 0
	s_mov_b32 m0, s48
	s_nop 0
	global_load_lds_dwordx4 v201, s[34:35]
	s_waitcnt vmcnt(8)
	s_waitcnt lgkmcnt(0)
	s_barrier
	v_mfma_f32_16x16x32_bf16 v[138:141], v[110:113], v[162:165], v[138:141]
	v_mfma_f32_16x16x32_bf16 v[134:137], v[130:133], v[162:165], v[134:137]
	v_mfma_f32_16x16x32_bf16 v[114:117], v[110:113], v[170:173], v[114:117]
	v_mfma_f32_16x16x32_bf16 v[106:109], v[130:133], v[170:173], v[106:109]
	v_mfma_f32_16x16x32_bf16 v[94:97], v[110:113], v[188:191], v[94:97]
	v_mfma_f32_16x16x32_bf16 v[90:93], v[130:133], v[188:191], v[90:93]
	v_mfma_f32_16x16x32_bf16 v[78:81], v[110:113], v[196:199], v[78:81]
	v_mfma_f32_16x16x32_bf16 v[74:77], v[130:133], v[196:199], v[74:77]
	v_mfma_f32_16x16x32_bf16 v[138:141], v[126:129], v[166:169], v[138:141]
	v_mfma_f32_16x16x32_bf16 v[134:137], v[142:145], v[166:169], v[134:137]
	v_mfma_f32_16x16x32_bf16 v[114:117], v[126:129], v[174:177], v[114:117]
	v_mfma_f32_16x16x32_bf16 v[106:109], v[142:145], v[174:177], v[106:109]
	v_mfma_f32_16x16x32_bf16 v[94:97], v[126:129], v[192:195], v[94:97]
	v_mfma_f32_16x16x32_bf16 v[90:93], v[142:145], v[192:195], v[90:93]
	v_mfma_f32_16x16x32_bf16 v[78:81], v[126:129], v[212:215], v[78:81]
	v_mfma_f32_16x16x32_bf16 v[74:77], v[142:145], v[212:215], v[74:77]
	v_mfma_f32_16x16x32_bf16 v[122:125], v[146:149], v[162:165], v[122:125]
	v_mfma_f32_16x16x32_bf16 v[118:121], v[154:157], v[162:165], v[118:121]
	v_mfma_f32_16x16x32_bf16 v[102:105], v[146:149], v[170:173], v[102:105]
	v_mfma_f32_16x16x32_bf16 v[98:101], v[154:157], v[170:173], v[98:101]
	v_mfma_f32_16x16x32_bf16 v[86:89], v[146:149], v[188:191], v[86:89]
	v_mfma_f32_16x16x32_bf16 v[82:85], v[154:157], v[188:191], v[82:85]
	v_mfma_f32_16x16x32_bf16 v[70:73], v[146:149], v[196:199], v[70:73]
	v_mfma_f32_16x16x32_bf16 v[66:69], v[154:157], v[196:199], v[66:69]
	v_mfma_f32_16x16x32_bf16 v[122:125], v[150:153], v[166:169], v[122:125]
	v_mfma_f32_16x16x32_bf16 v[118:121], v[158:161], v[166:169], v[118:121]
	v_mfma_f32_16x16x32_bf16 v[102:105], v[150:153], v[174:177], v[102:105]
	v_mfma_f32_16x16x32_bf16 v[98:101], v[158:161], v[174:177], v[98:101]
	v_mfma_f32_16x16x32_bf16 v[86:89], v[150:153], v[192:195], v[86:89]
	v_mfma_f32_16x16x32_bf16 v[82:85], v[158:161], v[192:195], v[82:85]
	v_mfma_f32_16x16x32_bf16 v[70:73], v[150:153], v[212:215], v[70:73]
	v_mfma_f32_16x16x32_bf16 v[66:69], v[158:161], v[212:215], v[66:69]
	s_barrier
	ds_read_b128 v[162:165], v208 offset:49152
	ds_read_b128 v[166:169], v208 offset:50176
	ds_read_b128 v[170:173], v208 offset:51200
	ds_read_b128 v[174:177], v208 offset:52224
	ds_read_b128 v[188:191], v208 offset:53248
	ds_read_b128 v[192:195], v208 offset:54272
	ds_read_b128 v[196:199], v208 offset:55296
	ds_read_b128 v[212:215], v208 offset:56320
	s_add_u32 s34, s30, 0x80
	s_addc_u32 s35, s31, 0
	s_mov_b32 m0, s49
	s_nop 0
	global_load_lds_dwordx4 v200, s[34:35]
	s_add_u32 s30, s30, 0x80080
	s_mov_b32 m0, s50
	s_nop 0
	global_load_lds_dwordx4 v203, s[34:35]
	s_addc_u32 s31, s31, 0
	s_mov_b32 m0, s53
	s_nop 0
	global_load_lds_dwordx4 v200, s[30:31]
	s_nop 0
	s_mov_b32 m0, s54
	s_nop 0
	global_load_lds_dwordx4 v203, s[30:31]
	s_mov_b32 m0, s51
	s_nop 0
	global_load_lds_dwordx4 v179, s[28:29]
	s_nop 0
	s_mov_b32 m0, s52
	s_nop 0
	global_load_lds_dwordx4 v201, s[28:29]
	s_waitcnt vmcnt(8)
	s_waitcnt lgkmcnt(0)
	s_barrier
	v_mfma_f32_16x16x32_bf16 v[62:65], v[110:113], v[162:165], v[62:65]
	v_mfma_f32_16x16x32_bf16 v[58:61], v[130:133], v[162:165], v[58:61]
	v_mfma_f32_16x16x32_bf16 v[46:49], v[110:113], v[170:173], v[46:49]
	v_mfma_f32_16x16x32_bf16 v[42:45], v[130:133], v[170:173], v[42:45]
	v_mfma_f32_16x16x32_bf16 v[30:33], v[110:113], v[188:191], v[30:33]
	v_mfma_f32_16x16x32_bf16 v[26:29], v[130:133], v[188:191], v[26:29]
	v_mfma_f32_16x16x32_bf16 v[14:17], v[110:113], v[196:199], v[14:17]
	v_mfma_f32_16x16x32_bf16 v[10:13], v[130:133], v[196:199], v[10:13]
	v_mfma_f32_16x16x32_bf16 v[62:65], v[126:129], v[166:169], v[62:65]
	v_mfma_f32_16x16x32_bf16 v[58:61], v[142:145], v[166:169], v[58:61]
	v_mfma_f32_16x16x32_bf16 v[46:49], v[126:129], v[174:177], v[46:49]
	v_mfma_f32_16x16x32_bf16 v[42:45], v[142:145], v[174:177], v[42:45]
	v_mfma_f32_16x16x32_bf16 v[30:33], v[126:129], v[192:195], v[30:33]
	v_mfma_f32_16x16x32_bf16 v[26:29], v[142:145], v[192:195], v[26:29]
	v_mfma_f32_16x16x32_bf16 v[14:17], v[126:129], v[212:215], v[14:17]
	v_mfma_f32_16x16x32_bf16 v[10:13], v[142:145], v[212:215], v[10:13]
	v_mfma_f32_16x16x32_bf16 v[54:57], v[146:149], v[162:165], v[54:57]
	v_mfma_f32_16x16x32_bf16 v[50:53], v[154:157], v[162:165], v[50:53]
	v_mfma_f32_16x16x32_bf16 v[38:41], v[146:149], v[170:173], v[38:41]
	v_mfma_f32_16x16x32_bf16 v[34:37], v[154:157], v[170:173], v[34:37]
	v_mfma_f32_16x16x32_bf16 v[22:25], v[146:149], v[188:191], v[22:25]
	v_mfma_f32_16x16x32_bf16 v[18:21], v[154:157], v[188:191], v[18:21]
	v_mfma_f32_16x16x32_bf16 v[6:9], v[146:149], v[196:199], v[6:9]
	v_mfma_f32_16x16x32_bf16 v[2:5], v[154:157], v[196:199], v[2:5]
	v_mfma_f32_16x16x32_bf16 v[54:57], v[150:153], v[166:169], v[54:57]
	v_mfma_f32_16x16x32_bf16 v[50:53], v[158:161], v[166:169], v[50:53]
	v_mfma_f32_16x16x32_bf16 v[38:41], v[150:153], v[174:177], v[38:41]
	v_mfma_f32_16x16x32_bf16 v[34:37], v[158:161], v[174:177], v[34:37]
	v_mfma_f32_16x16x32_bf16 v[22:25], v[150:153], v[192:195], v[22:25]
	v_mfma_f32_16x16x32_bf16 v[18:21], v[158:161], v[192:195], v[18:21]
	v_mfma_f32_16x16x32_bf16 v[6:9], v[150:153], v[212:215], v[6:9]
	v_mfma_f32_16x16x32_bf16 v[2:5], v[158:161], v[212:215], v[2:5]
	s_barrier
	s_add_i32 s59, s59, 2
	s_add_u32 s19, s19, 0x100
	s_addc_u32 s21, s21, 0
	s_add_u32 s57, s57, 0x100
	s_addc_u32 s58, s58, 0
	s_add_u32 s26, s26, 0x100
	s_addc_u32 s27, s27, 0
	s_cmp_gt_u32 s59, 29
	s_cbranch_scc0 .LBB0_1994
	s_and_b64 vcc, exec, s[16:17]
	s_cbranch_vccz .LBB0_1997
	s_barrier

.LBB0_2062:
	s_or_b64 exec, exec, s[4:5]
	v_readlane_b32 s6, v242, 20
	s_mov_b64 s[4:5], s[0:1]
	s_mov_b64 s[8:9], s[0:1]
	s_mov_b64 s[12:13], s[0:1]
	s_mov_b64 s[14:15], s[0:1]
	s_waitcnt lgkmcnt(0)
	v_mov_b32_e32 v2, v0
	v_readlane_b32 s7, v242, 21
	s_barrier
	v_readlane_b32 s99, v242, 0
	s_nop 1
	s_cmp_gt_u32 s99, 3
	s_cbranch_scc0 .Lsp_9
	s_setprio 1

; #define PG8_STAGE(bufoff, gbase, voff) do { _Pragma("unroll") for (int _i = 0; _i < 2; ++_i) { unsigned keep_; \
;         asm volatile("s_mov_b32 %0, m0\n\ts_mov_b32 m0, %3\n\ts_nop 0\n\tglobal_load_lds_dwordx4 %1, %2\n\ts_mov_b32 m0, %0" \
;             : "=&s"(keep_) : "v"((voff)[_i]), "s"((const void*)(gbase)), "s"(ldsb0 + (unsigned)(bufoff) + (unsigned)(_i * 8192)) : "memory"); } } while (0)
; #define PG8_LDA(dst, b, h) do { _Pragma("unroll") for (int m = 0; m < 4; ++m) _Pragma("unroll") for (int k = 0; k < 2; ++k) dst[m][k] = *(const LAS bf16x8*)(lds + PG8_SA(b, h) + aoff + m * 2048 + k * 1024); } while (0)
; #define PG8_LDB(dst, b, h) do { _Pragma("unroll") for (int n = 0; n < 2; ++n) _Pragma("unroll") for (int k = 0; k < 2; ++k) dst[n][k] = *(const LAS bf16x8*)(lds + PG8_SB(b, h) + boff + n * 2048 + k * 1024); } while (0)
; #define PG8_MMA(ai, bj, At, Bt) do { __builtin_amdgcn_s_setprio(1); _Pragma("unroll") for (int m = 0; m < 4; ++m) _Pragma("unroll") for (int n = 0; n < 2; ++n) _Pragma("unroll") for (int k = 0; k < 2; ++k) \
;         acc[ai][bj][m][n] = __builtin_amdgcn_mfma_f32_16x16x32_bf16(Bt[n][k], At[m][k], acc[ai][bj][m][n], 0, 0, 0); __builtin_amdgcn_s_setprio(0); } while (0)
; #define PG8_WAIT_V(n) asm volatile("s_waitcnt vmcnt(" #n ")" ::: "memory")
; #define PG8_WAIT_L(n) asm volatile("s_waitcnt lgkmcnt(" #n ")" ::: "memory")
; #define PG8_BAR __builtin_amdgcn_s_barrier()
; #define PG8_SCHED __builtin_amdgcn_sched_barrier(0)
; template <class Epi, class Sched, bool ALIGN_EPI>
; __device__ __forceinline__ void gemm_phase(LAS unsigned char* lds, const Gemm g, const Sched& S, const Epi& E) {
;     ...
;             PG8_LDB(B0, 0, 0); PG8_LDB(B1, 0, 1); PG8_SCHED; PG8_LDA(At, 0, 0); PG8_STAGE(PG8_SA(1, 1), a1 + hstepA, voffA);
;             PG8_WAIT_V(8); PG8_WAIT_L(0); PG8_BAR; PG8_MMA(0, 0, At, B0); PG8_MMA(0, 1, At, B1); PG8_BAR; PG8_SCHED;
;             PG8_LDA(At, 0, 1); PG8_STAGE(PG8_SB(0, 0), b2, voffB); PG8_STAGE(PG8_SB(0, 1), b2 + hstepB, voffB); PG8_STAGE(PG8_SA(0, 0), a2, voffA);
;             PG8_WAIT_V(8); PG8_WAIT_L(0); PG8_BAR; PG8_MMA(1, 0, At, B0); PG8_MMA(1, 1, At, B1); PG8_BAR; PG8_SCHED;
.LBB0_2075:
	ds_read_b128 v[154:157], v141
	ds_read_b128 v[158:161], v141 offset:1024
	ds_read_b128 v[162:165], v141 offset:2048
	ds_read_b128 v[166:169], v141 offset:3072
	ds_read_b128 v[170:173], v142
	ds_read_b128 v[174:177], v142 offset:1024
	ds_read_b128 v[180:183], v142 offset:2048
	ds_read_b128 v[184:187], v142 offset:3072
	s_add_u32 s28, s26, 0x100
	s_addc_u32 s29, s27, 0
	s_cmp_eq_u32 s60, 28
	s_cselect_b32 s36, s5, s28
	s_cselect_b32 s37, s3, s29
	s_cselect_b32 s34, s7, s19
	s_cselect_b32 s35, s6, s21
	s_add_u32 s30, s36, 0x80
	s_addc_u32 s31, s37, 0
	ds_read_b128 v[188:191], v143
	ds_read_b128 v[192:195], v143 offset:1024
	ds_read_b128 v[196:199], v143 offset:2048
	ds_read_b128 v[204:207], v143 offset:3072
	ds_read_b128 v[208:211], v143 offset:4096
	ds_read_b128 v[212:215], v143 offset:5120
	ds_read_b128 v[216:219], v143 offset:6144
	ds_read_b128 v[220:223], v143 offset:7168
	s_add_u32 s26, s26, 0x80080
	s_addc_u32 s27, s27, 0
	s_mov_b32 m0, s57
	s_nop 0
	global_load_lds_dwordx4 v134, s[26:27]
	s_nop 0
	s_mov_b32 m0, s58
	s_nop 0
	global_load_lds_dwordx4 v136, s[26:27]
	s_waitcnt vmcnt(8)
	s_waitcnt lgkmcnt(0)
	s_barrier
	v_mfma_f32_16x16x32_bf16 v[126:129], v[154:157], v[188:191], v[126:129]
	v_mfma_f32_16x16x32_bf16 v[122:125], v[162:165], v[188:191], v[122:125]
	v_mfma_f32_16x16x32_bf16 v[110:113], v[154:157], v[196:199], v[110:113]
	v_mfma_f32_16x16x32_bf16 v[106:109], v[162:165], v[196:199], v[106:109]
	v_mfma_f32_16x16x32_bf16 v[94:97], v[154:157], v[208:211], v[94:97]
	v_mfma_f32_16x16x32_bf16 v[90:93], v[162:165], v[208:211], v[90:93]
	v_mfma_f32_16x16x32_bf16 v[78:81], v[154:157], v[216:219], v[78:81]
	v_mfma_f32_16x16x32_bf16 v[74:77], v[162:165], v[216:219], v[74:77]
	v_mfma_f32_16x16x32_bf16 v[126:129], v[158:161], v[192:195], v[126:129]
	v_mfma_f32_16x16x32_bf16 v[122:125], v[166:169], v[192:195], v[122:125]
	v_mfma_f32_16x16x32_bf16 v[110:113], v[158:161], v[204:207], v[110:113]
	v_mfma_f32_16x16x32_bf16 v[106:109], v[166:169], v[204:207], v[106:109]
	v_mfma_f32_16x16x32_bf16 v[94:97], v[158:161], v[212:215], v[94:97]
	v_mfma_f32_16x16x32_bf16 v[90:93], v[166:169], v[212:215], v[90:93]
	v_mfma_f32_16x16x32_bf16 v[78:81], v[158:161], v[220:223], v[78:81]
	v_mfma_f32_16x16x32_bf16 v[74:77], v[166:169], v[220:223], v[74:77]
	v_mfma_f32_16x16x32_bf16 v[118:121], v[170:173], v[188:191], v[118:121]
	v_mfma_f32_16x16x32_bf16 v[114:117], v[180:183], v[188:191], v[114:117]
	v_mfma_f32_16x16x32_bf16 v[102:105], v[170:173], v[196:199], v[102:105]
	v_mfma_f32_16x16x32_bf16 v[98:101], v[180:183], v[196:199], v[98:101]
	v_mfma_f32_16x16x32_bf16 v[86:89], v[170:173], v[208:211], v[86:89]
	v_mfma_f32_16x16x32_bf16 v[82:85], v[180:183], v[208:211], v[82:85]
	v_mfma_f32_16x16x32_bf16 v[70:73], v[170:173], v[216:219], v[70:73]
	v_mfma_f32_16x16x32_bf16 v[66:69], v[180:183], v[216:219], v[66:69]
	v_mfma_f32_16x16x32_bf16 v[118:121], v[174:177], v[192:195], v[118:121]
	v_mfma_f32_16x16x32_bf16 v[114:117], v[184:187], v[192:195], v[114:117]
	v_mfma_f32_16x16x32_bf16 v[102:105], v[174:177], v[204:207], v[102:105]
	v_mfma_f32_16x16x32_bf16 v[98:101], v[184:187], v[204:207], v[98:101]
	v_mfma_f32_16x16x32_bf16 v[86:89], v[174:177], v[212:215], v[86:89]
	v_mfma_f32_16x16x32_bf16 v[82:85], v[184:187], v[212:215], v[82:85]
	v_mfma_f32_16x16x32_bf16 v[70:73], v[174:177], v[220:223], v[70:73]
	v_mfma_f32_16x16x32_bf16 v[66:69], v[184:187], v[220:223], v[66:69]
	s_barrier
	ds_read_b128 v[188:191], v143 offset:16384
	ds_read_b128 v[192:195], v143 offset:17408
	ds_read_b128 v[196:199], v143 offset:18432
	ds_read_b128 v[204:207], v143 offset:19456
	ds_read_b128 v[208:211], v143 offset:20480
	ds_read_b128 v[212:215], v143 offset:21504
	ds_read_b128 v[216:219], v143 offset:22528
	ds_read_b128 v[220:223], v143 offset:23552
	s_mov_b32 m0, s44
	s_nop 0
	global_load_lds_dwordx4 v135, s[34:35]
	s_nop 0
	s_mov_b32 m0, s45
	s_nop 0
	global_load_lds_dwordx4 v137, s[34:35]
	s_add_u32 s26, s34, 0x80000
	s_addc_u32 s27, s35, 0
	s_mov_b32 m0, s46
	s_nop 0
	global_load_lds_dwordx4 v135, s[26:27]
	s_nop 0
	s_mov_b32 m0, s47
	s_nop 0
	global_load_lds_dwordx4 v137, s[26:27]
	s_mov_b32 m0, s42
	s_nop 0
	global_load_lds_dwordx4 v134, s[36:37]
	s_nop 0
	s_mov_b32 m0, s48
	s_nop 0
	global_load_lds_dwordx4 v136, s[36:37]
	s_waitcnt vmcnt(8)
	s_waitcnt lgkmcnt(0)
	s_barrier
	v_mfma_f32_16x16x32_bf16 v[62:65], v[154:157], v[188:191], v[62:65]
	v_mfma_f32_16x16x32_bf16 v[58:61], v[162:165], v[188:191], v[58:61]
	v_mfma_f32_16x16x32_bf16 v[46:49], v[154:157], v[196:199], v[46:49]
	v_mfma_f32_16x16x32_bf16 v[42:45], v[162:165], v[196:199], v[42:45]
	v_mfma_f32_16x16x32_bf16 v[30:33], v[154:157], v[208:211], v[30:33]
	v_mfma_f32_16x16x32_bf16 v[26:29], v[162:165], v[208:211], v[26:29]
	v_mfma_f32_16x16x32_bf16 v[14:17], v[154:157], v[216:219], v[14:17]
	v_mfma_f32_16x16x32_bf16 v[10:13], v[162:165], v[216:219], v[10:13]
	v_mfma_f32_16x16x32_bf16 v[62:65], v[158:161], v[192:195], v[62:65]
	v_mfma_f32_16x16x32_bf16 v[58:61], v[166:169], v[192:195], v[58:61]
	v_mfma_f32_16x16x32_bf16 v[46:49], v[158:161], v[204:207], v[46:49]
	v_mfma_f32_16x16x32_bf16 v[42:45], v[166:169], v[204:207], v[42:45]
	v_mfma_f32_16x16x32_bf16 v[30:33], v[158:161], v[212:215], v[30:33]
	v_mfma_f32_16x16x32_bf16 v[26:29], v[166:169], v[212:215], v[26:29]
	v_mfma_f32_16x16x32_bf16 v[14:17], v[158:161], v[220:223], v[14:17]
	v_mfma_f32_16x16x32_bf16 v[10:13], v[166:169], v[220:223], v[10:13]
	v_mfma_f32_16x16x32_bf16 v[54:57], v[170:173], v[188:191], v[54:57]
	v_mfma_f32_16x16x32_bf16 v[50:53], v[180:183], v[188:191], v[50:53]
	v_mfma_f32_16x16x32_bf16 v[38:41], v[170:173], v[196:199], v[38:41]
	v_mfma_f32_16x16x32_bf16 v[34:37], v[180:183], v[196:199], v[34:37]
	v_mfma_f32_16x16x32_bf16 v[22:25], v[170:173], v[208:211], v[22:25]
	v_mfma_f32_16x16x32_bf16 v[18:21], v[180:183], v[208:211], v[18:21]
	v_mfma_f32_16x16x32_bf16 v[6:9], v[170:173], v[216:219], v[6:9]
	v_mfma_f32_16x16x32_bf16 v[2:5], v[180:183], v[216:219], v[2:5]
	v_mfma_f32_16x16x32_bf16 v[54:57], v[174:177], v[192:195], v[54:57]
	v_mfma_f32_16x16x32_bf16 v[50:53], v[184:187], v[192:195], v[50:53]
	v_mfma_f32_16x16x32_bf16 v[38:41], v[174:177], v[204:207], v[38:41]
	v_mfma_f32_16x16x32_bf16 v[34:37], v[184:187], v[204:207], v[34:37]
	v_mfma_f32_16x16x32_bf16 v[22:25], v[174:177], v[212:215], v[22:25]
	v_mfma_f32_16x16x32_bf16 v[18:21], v[184:187], v[212:215], v[18:21]
	v_mfma_f32_16x16x32_bf16 v[6:9], v[174:177], v[220:223], v[6:9]
	v_mfma_f32_16x16x32_bf16 v[2:5], v[184:187], v[220:223], v[2:5]
	s_barrier
; #define PG8_STAGE(bufoff, gbase, voff) do { _Pragma("unroll") for (int _i = 0; _i < 2; ++_i) { unsigned keep_; \
;         asm volatile("s_mov_b32 %0, m0\n\ts_mov_b32 m0, %3\n\ts_nop 0\n\tglobal_load_lds_dwordx4 %1, %2\n\ts_mov_b32 m0, %0" \
;             : "=&s"(keep_) : "v"((voff)[_i]), "s"((const void*)(gbase)), "s"(ldsb0 + (unsigned)(bufoff) + (unsigned)(_i * 8192)) : "memory"); } } while (0)
; #define PG8_LDA(dst, b, h) do { _Pragma("unroll") for (int m = 0; m < 4; ++m) _Pragma("unroll") for (int k = 0; k < 2; ++k) dst[m][k] = *(const LAS bf16x8*)(lds + PG8_SA(b, h) + aoff + m * 2048 + k * 1024); } while (0)
; #define PG8_LDB(dst, b, h) do { _Pragma("unroll") for (int n = 0; n < 2; ++n) _Pragma("unroll") for (int k = 0; k < 2; ++k) dst[n][k] = *(const LAS bf16x8*)(lds + PG8_SB(b, h) + boff + n * 2048 + k * 1024); } while (0)
; #define PG8_MMA(ai, bj, At, Bt) do { __builtin_amdgcn_s_setprio(1); _Pragma("unroll") for (int m = 0; m < 4; ++m) _Pragma("unroll") for (int n = 0; n < 2; ++n) _Pragma("unroll") for (int k = 0; k < 2; ++k) \
;         acc[ai][bj][m][n] = __builtin_amdgcn_mfma_f32_16x16x32_bf16(Bt[n][k], At[m][k], acc[ai][bj][m][n], 0, 0, 0); __builtin_amdgcn_s_setprio(0); } while (0)
; #define PG8_WAIT_V(n) asm volatile("s_waitcnt vmcnt(" #n ")" ::: "memory")
; #define PG8_WAIT_L(n) asm volatile("s_waitcnt lgkmcnt(" #n ")" ::: "memory")
; #define PG8_BAR __builtin_amdgcn_s_barrier()
; #define PG8_SCHED __builtin_amdgcn_sched_barrier(0)
; template <class Epi, class Sched, bool ALIGN_EPI>
; __device__ __forceinline__ void gemm_phase(LAS unsigned char* lds, const Gemm g, const Sched& S, const Epi& E) {
;     ...
;             PG8_LDB(B0, 1, 0); PG8_LDB(B1, 1, 1); PG8_SCHED; PG8_LDA(At, 1, 0); PG8_STAGE(PG8_SA(0, 1), a2 + hstepA, voffA);
;             PG8_WAIT_V(8); PG8_WAIT_L(0); PG8_BAR; PG8_MMA(0, 0, At, B0); PG8_MMA(0, 1, At, B1); PG8_BAR; PG8_SCHED;
;             PG8_LDA(At, 1, 1); PG8_STAGE(PG8_SB(1, 0), b3, voffB); PG8_STAGE(PG8_SB(1, 1), b3 + hstepB, voffB); PG8_STAGE(PG8_SA(1, 0), a3, voffA);
;             PG8_WAIT_V(8); PG8_WAIT_L(0); PG8_BAR; PG8_MMA(1, 0, At, B0); PG8_MMA(1, 1, At, B1); PG8_BAR; PG8_SCHED;
;         }
	ds_read_b128 v[154:157], v144
	ds_read_b128 v[158:161], v144 offset:1024
	ds_read_b128 v[162:165], v144 offset:2048
	ds_read_b128 v[166:169], v144 offset:3072
	ds_read_b128 v[170:173], v145
	ds_read_b128 v[174:177], v145 offset:1024
	ds_read_b128 v[180:183], v145 offset:2048
	ds_read_b128 v[184:187], v145 offset:3072
	ds_read_b128 v[188:191], v143 offset:32768
	ds_read_b128 v[192:195], v143 offset:33792
	ds_read_b128 v[196:199], v143 offset:34816
	ds_read_b128 v[204:207], v143 offset:35840
	ds_read_b128 v[208:211], v143 offset:36864
	ds_read_b128 v[212:215], v143 offset:37888
	ds_read_b128 v[216:219], v143 offset:38912
	ds_read_b128 v[220:223], v143 offset:39936
	s_add_u32 s26, s36, 0x80000
	s_addc_u32 s27, s37, 0
	s_mov_b32 m0, s49
	s_nop 0
	global_load_lds_dwordx4 v134, s[26:27]
	s_nop 0
	s_mov_b32 m0, s50
	s_nop 0
	global_load_lds_dwordx4 v136, s[26:27]
	s_waitcnt vmcnt(8)
	s_waitcnt lgkmcnt(0)
	s_barrier
	v_mfma_f32_16x16x32_bf16 v[126:129], v[154:157], v[188:191], v[126:129]
	v_mfma_f32_16x16x32_bf16 v[122:125], v[162:165], v[188:191], v[122:125]
	v_mfma_f32_16x16x32_bf16 v[110:113], v[154:157], v[196:199], v[110:113]
	v_mfma_f32_16x16x32_bf16 v[106:109], v[162:165], v[196:199], v[106:109]
	v_mfma_f32_16x16x32_bf16 v[94:97], v[154:157], v[208:211], v[94:97]
	v_mfma_f32_16x16x32_bf16 v[90:93], v[162:165], v[208:211], v[90:93]
	v_mfma_f32_16x16x32_bf16 v[78:81], v[154:157], v[216:219], v[78:81]
	v_mfma_f32_16x16x32_bf16 v[74:77], v[162:165], v[216:219], v[74:77]
	v_mfma_f32_16x16x32_bf16 v[126:129], v[158:161], v[192:195], v[126:129]
	v_mfma_f32_16x16x32_bf16 v[122:125], v[166:169], v[192:195], v[122:125]
	v_mfma_f32_16x16x32_bf16 v[110:113], v[158:161], v[204:207], v[110:113]
	v_mfma_f32_16x16x32_bf16 v[106:109], v[166:169], v[204:207], v[106:109]
	v_mfma_f32_16x16x32_bf16 v[94:97], v[158:161], v[212:215], v[94:97]
	v_mfma_f32_16x16x32_bf16 v[90:93], v[166:169], v[212:215], v[90:93]
	v_mfma_f32_16x16x32_bf16 v[78:81], v[158:161], v[220:223], v[78:81]
	v_mfma_f32_16x16x32_bf16 v[74:77], v[166:169], v[220:223], v[74:77]
	v_mfma_f32_16x16x32_bf16 v[118:121], v[170:173], v[188:191], v[118:121]
	v_mfma_f32_16x16x32_bf16 v[114:117], v[180:183], v[188:191], v[114:117]
	v_mfma_f32_16x16x32_bf16 v[102:105], v[170:173], v[196:199], v[102:105]
	v_mfma_f32_16x16x32_bf16 v[98:101], v[180:183], v[196:199], v[98:101]
	v_mfma_f32_16x16x32_bf16 v[86:89], v[170:173], v[208:211], v[86:89]
	v_mfma_f32_16x16x32_bf16 v[82:85], v[180:183], v[208:211], v[82:85]
	v_mfma_f32_16x16x32_bf16 v[70:73], v[170:173], v[216:219], v[70:73]
	v_mfma_f32_16x16x32_bf16 v[66:69], v[180:183], v[216:219], v[66:69]
	v_mfma_f32_16x16x32_bf16 v[118:121], v[174:177], v[192:195], v[118:121]
	v_mfma_f32_16x16x32_bf16 v[114:117], v[184:187], v[192:195], v[114:117]
	v_mfma_f32_16x16x32_bf16 v[102:105], v[174:177], v[204:207], v[102:105]
	v_mfma_f32_16x16x32_bf16 v[98:101], v[184:187], v[204:207], v[98:101]
	v_mfma_f32_16x16x32_bf16 v[86:89], v[174:177], v[212:215], v[86:89]
	v_mfma_f32_16x16x32_bf16 v[82:85], v[184:187], v[212:215], v[82:85]
	v_mfma_f32_16x16x32_bf16 v[70:73], v[174:177], v[220:223], v[70:73]
	v_mfma_f32_16x16x32_bf16 v[66:69], v[184:187], v[220:223], v[66:69]
	s_barrier
	ds_read_b128 v[188:191], v143 offset:49152
	ds_read_b128 v[192:195], v143 offset:50176
	ds_read_b128 v[196:199], v143 offset:51200
	ds_read_b128 v[204:207], v143 offset:52224
	ds_read_b128 v[208:211], v143 offset:53248
	ds_read_b128 v[212:215], v143 offset:54272
	ds_read_b128 v[216:219], v143 offset:55296
	ds_read_b128 v[220:223], v143 offset:56320
	s_add_u32 s26, s34, 0x80
	s_addc_u32 s27, s35, 0
	s_mov_b32 m0, s51
	s_nop 0
	global_load_lds_dwordx4 v135, s[26:27]
	s_nop 0
	s_mov_b32 m0, s52
	s_nop 0
	global_load_lds_dwordx4 v137, s[26:27]
	s_add_u32 s26, s34, 0x80080
	s_addc_u32 s27, s35, 0
	s_mov_b32 m0, s55
	s_nop 0
	global_load_lds_dwordx4 v135, s[26:27]
	s_nop 0
	s_mov_b32 m0, s56
	s_nop 0
	global_load_lds_dwordx4 v137, s[26:27]
	s_mov_b32 m0, s53
	s_nop 0
	global_load_lds_dwordx4 v134, s[30:31]
	s_nop 0
	s_mov_b32 m0, s54
	s_nop 0
	global_load_lds_dwordx4 v136, s[30:31]
	s_waitcnt vmcnt(8)
	s_waitcnt lgkmcnt(0)
	s_barrier
	v_mfma_f32_16x16x32_bf16 v[62:65], v[154:157], v[188:191], v[62:65]
	v_mfma_f32_16x16x32_bf16 v[58:61], v[162:165], v[188:191], v[58:61]
	v_mfma_f32_16x16x32_bf16 v[46:49], v[154:157], v[196:199], v[46:49]
	v_mfma_f32_16x16x32_bf16 v[42:45], v[162:165], v[196:199], v[42:45]
	v_mfma_f32_16x16x32_bf16 v[30:33], v[154:157], v[208:211], v[30:33]
	v_mfma_f32_16x16x32_bf16 v[26:29], v[162:165], v[208:211], v[26:29]
	v_mfma_f32_16x16x32_bf16 v[14:17], v[154:157], v[216:219], v[14:17]
	v_mfma_f32_16x16x32_bf16 v[10:13], v[162:165], v[216:219], v[10:13]
	v_mfma_f32_16x16x32_bf16 v[62:65], v[158:161], v[192:195], v[62:65]
	v_mfma_f32_16x16x32_bf16 v[58:61], v[166:169], v[192:195], v[58:61]
	v_mfma_f32_16x16x32_bf16 v[46:49], v[158:161], v[204:207], v[46:49]
	v_mfma_f32_16x16x32_bf16 v[42:45], v[166:169], v[204:207], v[42:45]
	v_mfma_f32_16x16x32_bf16 v[30:33], v[158:161], v[212:215], v[30:33]
	v_mfma_f32_16x16x32_bf16 v[26:29], v[166:169], v[212:215], v[26:29]
	v_mfma_f32_16x16x32_bf16 v[14:17], v[158:161], v[220:223], v[14:17]
	v_mfma_f32_16x16x32_bf16 v[10:13], v[166:169], v[220:223], v[10:13]
	v_mfma_f32_16x16x32_bf16 v[54:57], v[170:173], v[188:191], v[54:57]
	v_mfma_f32_16x16x32_bf16 v[50:53], v[180:183], v[188:191], v[50:53]
	v_mfma_f32_16x16x32_bf16 v[38:41], v[170:173], v[196:199], v[38:41]
	v_mfma_f32_16x16x32_bf16 v[34:37], v[180:183], v[196:199], v[34:37]
	v_mfma_f32_16x16x32_bf16 v[22:25], v[170:173], v[208:211], v[22:25]
	v_mfma_f32_16x16x32_bf16 v[18:21], v[180:183], v[208:211], v[18:21]
	v_mfma_f32_16x16x32_bf16 v[6:9], v[170:173], v[216:219], v[6:9]
	v_mfma_f32_16x16x32_bf16 v[2:5], v[180:183], v[216:219], v[2:5]
	v_mfma_f32_16x16x32_bf16 v[54:57], v[174:177], v[192:195], v[54:57]
	v_mfma_f32_16x16x32_bf16 v[50:53], v[184:187], v[192:195], v[50:53]
	v_mfma_f32_16x16x32_bf16 v[38:41], v[174:177], v[204:207], v[38:41]
	v_mfma_f32_16x16x32_bf16 v[34:37], v[184:187], v[204:207], v[34:37]
	v_mfma_f32_16x16x32_bf16 v[22:25], v[174:177], v[212:215], v[22:25]
	v_mfma_f32_16x16x32_bf16 v[18:21], v[184:187], v[212:215], v[18:21]
	v_mfma_f32_16x16x32_bf16 v[6:9], v[174:177], v[220:223], v[6:9]
	v_mfma_f32_16x16x32_bf16 v[2:5], v[184:187], v[220:223], v[2:5]
	s_barrier
	s_add_i32 s60, s60, 2
	s_add_u32 s19, s19, 0x100
	s_addc_u32 s21, s21, 0
	s_cmp_gt_u32 s60, 29
	s_mov_b64 s[26:27], s[28:29]
	s_cbranch_scc0 .LBB0_2075
	s_and_b64 vcc, exec, s[16:17]
	s_cbranch_vccz .LBB0_2078
	s_barrier

.LBB0_2152:
	s_or_b64 exec, exec, s[4:5]
	s_mov_b64 s[4:5], s[0:1]
	s_mov_b64 s[8:9], s[0:1]
	s_mov_b64 s[6:7], s[0:1]
	s_mov_b64 s[2:3], s[0:1]
	s_waitcnt lgkmcnt(0)
	s_barrier
	v_readlane_b32 s99, v242, 0
	s_nop 1
	s_cmp_gt_u32 s99, 3
	s_cbranch_scc0 .Lsp_10
	s_setprio 1

; #define PG8_STAGE(bufoff, gbase, voff) do { _Pragma("unroll") for (int _i = 0; _i < 2; ++_i) { unsigned keep_; \
;         asm volatile("s_mov_b32 %0, m0\n\ts_mov_b32 m0, %3\n\ts_nop 0\n\tglobal_load_lds_dwordx4 %1, %2\n\ts_mov_b32 m0, %0" \
;             : "=&s"(keep_) : "v"((voff)[_i]), "s"((const void*)(gbase)), "s"(ldsb0 + (unsigned)(bufoff) + (unsigned)(_i * 8192)) : "memory"); } } while (0)
; #define PG8_LDA(dst, b, h) do { _Pragma("unroll") for (int m = 0; m < 4; ++m) _Pragma("unroll") for (int k = 0; k < 2; ++k) dst[m][k] = *(const LAS bf16x8*)(lds + PG8_SA(b, h) + aoff + m * 2048 + k * 1024); } while (0)
; #define PG8_LDB(dst, b, h) do { _Pragma("unroll") for (int n = 0; n < 2; ++n) _Pragma("unroll") for (int k = 0; k < 2; ++k) dst[n][k] = *(const LAS bf16x8*)(lds + PG8_SB(b, h) + boff + n * 2048 + k * 1024); } while (0)
; #define PG8_MMA(ai, bj, At, Bt) do { __builtin_amdgcn_s_setprio(1); _Pragma("unroll") for (int m = 0; m < 4; ++m) _Pragma("unroll") for (int n = 0; n < 2; ++n) _Pragma("unroll") for (int k = 0; k < 2; ++k) \
;         acc[ai][bj][m][n] = __builtin_amdgcn_mfma_f32_16x16x32_bf16(Bt[n][k], At[m][k], acc[ai][bj][m][n], 0, 0, 0); __builtin_amdgcn_s_setprio(0); } while (0)
; #define PG8_WAIT_V(n) asm volatile("s_waitcnt vmcnt(" #n ")" ::: "memory")
; #define PG8_WAIT_L(n) asm volatile("s_waitcnt lgkmcnt(" #n ")" ::: "memory")
; #define PG8_BAR __builtin_amdgcn_s_barrier()
; #define PG8_SCHED __builtin_amdgcn_sched_barrier(0)
; template <class Epi, class Sched, bool ALIGN_EPI>
; __device__ __forceinline__ void gemm_phase(LAS unsigned char* lds, const Gemm g, const Sched& S, const Epi& E) {
;     ...
;             PG8_LDB(B0, 0, 0); PG8_LDB(B1, 0, 1); PG8_SCHED; PG8_LDA(At, 0, 0); PG8_STAGE(PG8_SA(1, 1), a1 + hstepA, voffA);
;             PG8_WAIT_V(8); PG8_WAIT_L(0); PG8_BAR; PG8_MMA(0, 0, At, B0); PG8_MMA(0, 1, At, B1); PG8_BAR; PG8_SCHED;
;             PG8_LDA(At, 0, 1); PG8_STAGE(PG8_SB(0, 0), b2, voffB); PG8_STAGE(PG8_SB(0, 1), b2 + hstepB, voffB); PG8_STAGE(PG8_SA(0, 0), a2, voffA);
;             PG8_WAIT_V(8); PG8_WAIT_L(0); PG8_BAR; PG8_MMA(1, 0, At, B0); PG8_MMA(1, 1, At, B1); PG8_BAR; PG8_SCHED;
.LBB0_2172:
	s_add_u32 s61, s22, s26
	s_addc_u32 s63, s23, s27
	s_add_u32 s28, s61, 0x100
	v_add_u32_e32 v141, 0x10000, v139
	s_addc_u32 s29, s63, 0
	ds_read_b128 v[142:145], v141
	ds_read_b128 v[146:149], v141 offset:1024
	ds_read_b128 v[150:153], v141 offset:2048
	ds_read_b128 v[154:157], v141 offset:3072
	v_add_u32_e32 v141, 0x14000, v139
	s_add_u32 s30, s20, s26
	ds_read_b128 v[158:161], v141
	ds_read_b128 v[162:165], v141 offset:1024
	ds_read_b128 v[166:169], v141 offset:2048
	ds_read_b128 v[170:173], v141 offset:3072
	s_addc_u32 s31, s21, s27
	s_add_u32 s30, s30, 0x100
	s_addc_u32 s31, s31, 0
	s_cmpk_eq_i32 s60, 0x54
	s_cselect_b32 s34, s12, s28
	s_cselect_b32 s35, s13, s29
	s_cselect_b32 s30, s24, s30
	s_cselect_b32 s31, s25, s31
	s_add_u32 s28, s34, 0x80
	s_addc_u32 s29, s35, 0
	ds_read_b128 v[174:177], v140
	ds_read_b128 v[178:181], v140 offset:1024
	ds_read_b128 v[182:185], v140 offset:2048
	ds_read_b128 v[186:189], v140 offset:3072
	ds_read_b128 v[190:193], v140 offset:4096
	ds_read_b128 v[194:197], v140 offset:5120
	ds_read_b128 v[198:201], v140 offset:6144
	ds_read_b128 v[204:207], v140 offset:7168
	s_add_u32 s62, s61, 0x160080
	s_addc_u32 s63, s63, 0
	s_mov_b32 m0, s54
	s_nop 0
	global_load_lds_dwordx4 v131, s[62:63]
	s_nop 0
	s_mov_b32 m0, s55
	s_nop 0
	global_load_lds_dwordx4 v137, s[62:63]
	s_waitcnt vmcnt(8)
	s_waitcnt lgkmcnt(0)
	s_barrier
	v_mfma_f32_16x16x32_bf16 v[126:129], v[142:145], v[174:177], v[126:129]
	v_mfma_f32_16x16x32_bf16 v[122:125], v[150:153], v[174:177], v[122:125]
	v_mfma_f32_16x16x32_bf16 v[110:113], v[142:145], v[182:185], v[110:113]
	v_mfma_f32_16x16x32_bf16 v[106:109], v[150:153], v[182:185], v[106:109]
	v_mfma_f32_16x16x32_bf16 v[94:97], v[142:145], v[190:193], v[94:97]
	v_mfma_f32_16x16x32_bf16 v[90:93], v[150:153], v[190:193], v[90:93]
	v_mfma_f32_16x16x32_bf16 v[78:81], v[142:145], v[198:201], v[78:81]
	v_mfma_f32_16x16x32_bf16 v[74:77], v[150:153], v[198:201], v[74:77]
	v_mfma_f32_16x16x32_bf16 v[126:129], v[146:149], v[178:181], v[126:129]
	v_mfma_f32_16x16x32_bf16 v[122:125], v[154:157], v[178:181], v[122:125]
	v_mfma_f32_16x16x32_bf16 v[110:113], v[146:149], v[186:189], v[110:113]
	v_mfma_f32_16x16x32_bf16 v[106:109], v[154:157], v[186:189], v[106:109]
	v_mfma_f32_16x16x32_bf16 v[94:97], v[146:149], v[194:197], v[94:97]
	v_mfma_f32_16x16x32_bf16 v[90:93], v[154:157], v[194:197], v[90:93]
	v_mfma_f32_16x16x32_bf16 v[78:81], v[146:149], v[204:207], v[78:81]
	v_mfma_f32_16x16x32_bf16 v[74:77], v[154:157], v[204:207], v[74:77]
	v_mfma_f32_16x16x32_bf16 v[118:121], v[158:161], v[174:177], v[118:121]
	v_mfma_f32_16x16x32_bf16 v[114:117], v[166:169], v[174:177], v[114:117]
	v_mfma_f32_16x16x32_bf16 v[102:105], v[158:161], v[182:185], v[102:105]
	v_mfma_f32_16x16x32_bf16 v[98:101], v[166:169], v[182:185], v[98:101]
	v_mfma_f32_16x16x32_bf16 v[86:89], v[158:161], v[190:193], v[86:89]
	v_mfma_f32_16x16x32_bf16 v[82:85], v[166:169], v[190:193], v[82:85]
	v_mfma_f32_16x16x32_bf16 v[70:73], v[158:161], v[198:201], v[70:73]
	v_mfma_f32_16x16x32_bf16 v[66:69], v[166:169], v[198:201], v[66:69]
	v_mfma_f32_16x16x32_bf16 v[118:121], v[162:165], v[178:181], v[118:121]
	v_mfma_f32_16x16x32_bf16 v[114:117], v[170:173], v[178:181], v[114:117]
	v_mfma_f32_16x16x32_bf16 v[102:105], v[162:165], v[186:189], v[102:105]
	v_mfma_f32_16x16x32_bf16 v[98:101], v[170:173], v[186:189], v[98:101]
	v_mfma_f32_16x16x32_bf16 v[86:89], v[162:165], v[194:197], v[86:89]
	v_mfma_f32_16x16x32_bf16 v[82:85], v[170:173], v[194:197], v[82:85]
	v_mfma_f32_16x16x32_bf16 v[70:73], v[162:165], v[204:207], v[70:73]
	v_mfma_f32_16x16x32_bf16 v[66:69], v[170:173], v[204:207], v[66:69]
	s_barrier
	ds_read_b128 v[174:177], v140 offset:16384
	ds_read_b128 v[178:181], v140 offset:17408
	ds_read_b128 v[182:185], v140 offset:18432
	ds_read_b128 v[186:189], v140 offset:19456
	ds_read_b128 v[190:193], v140 offset:20480
	ds_read_b128 v[194:197], v140 offset:21504
	ds_read_b128 v[198:201], v140 offset:22528
	ds_read_b128 v[204:207], v140 offset:23552
	s_mov_b32 m0, s3
	s_nop 0
	global_load_lds_dwordx4 v136, s[30:31]
	s_add_u32 s62, s30, 0x160000
	s_mov_b32 m0, s41
	s_nop 0
	global_load_lds_dwordx4 v138, s[30:31]
	s_addc_u32 s63, s31, 0
	s_mov_b32 m0, s42
	s_nop 0
	global_load_lds_dwordx4 v136, s[62:63]
	s_nop 0
	s_mov_b32 m0, s43
	s_nop 0
	global_load_lds_dwordx4 v138, s[62:63]
	s_nop 0
	s_mov_b32 m0, s2
	s_nop 0
	global_load_lds_dwordx4 v131, s[34:35]
	s_nop 0
	s_mov_b32 m0, s44
	s_nop 0
	global_load_lds_dwordx4 v137, s[34:35]
	s_waitcnt vmcnt(8)
	s_waitcnt lgkmcnt(0)
	s_barrier
; #define PG8_STAGE(bufoff, gbase, voff) do { _Pragma("unroll") for (int _i = 0; _i < 2; ++_i) { unsigned keep_; \
;         asm volatile("s_mov_b32 %0, m0\n\ts_mov_b32 m0, %3\n\ts_nop 0\n\tglobal_load_lds_dwordx4 %1, %2\n\ts_mov_b32 m0, %0" \
;             : "=&s"(keep_) : "v"((voff)[_i]), "s"((const void*)(gbase)), "s"(ldsb0 + (unsigned)(bufoff) + (unsigned)(_i * 8192)) : "memory"); } } while (0)
; #define PG8_LDA(dst, b, h) do { _Pragma("unroll") for (int m = 0; m < 4; ++m) _Pragma("unroll") for (int k = 0; k < 2; ++k) dst[m][k] = *(const LAS bf16x8*)(lds + PG8_SA(b, h) + aoff + m * 2048 + k * 1024); } while (0)
; #define PG8_LDB(dst, b, h) do { _Pragma("unroll") for (int n = 0; n < 2; ++n) _Pragma("unroll") for (int k = 0; k < 2; ++k) dst[n][k] = *(const LAS bf16x8*)(lds + PG8_SB(b, h) + boff + n * 2048 + k * 1024); } while (0)
; #define PG8_MMA(ai, bj, At, Bt) do { __builtin_amdgcn_s_setprio(1); _Pragma("unroll") for (int m = 0; m < 4; ++m) _Pragma("unroll") for (int n = 0; n < 2; ++n) _Pragma("unroll") for (int k = 0; k < 2; ++k) \
;         acc[ai][bj][m][n] = __builtin_amdgcn_mfma_f32_16x16x32_bf16(Bt[n][k], At[m][k], acc[ai][bj][m][n], 0, 0, 0); __builtin_amdgcn_s_setprio(0); } while (0)
; #define PG8_WAIT_V(n) asm volatile("s_waitcnt vmcnt(" #n ")" ::: "memory")
; #define PG8_WAIT_L(n) asm volatile("s_waitcnt lgkmcnt(" #n ")" ::: "memory")
; #define PG8_BAR __builtin_amdgcn_s_barrier()
; template <class Epi, class Sched, bool ALIGN_EPI>
; __device__ __forceinline__ void gemm_phase(LAS unsigned char* lds, const Gemm g, const Sched& S, const Epi& E) {
;     ...
;             PG8_WAIT_V(8); PG8_WAIT_L(0); PG8_BAR; PG8_MMA(0, 0, At, B0); PG8_MMA(0, 1, At, B1); PG8_BAR; PG8_SCHED;
;             PG8_LDA(At, 0, 1); PG8_STAGE(PG8_SB(0, 0), b2, voffB); PG8_STAGE(PG8_SB(0, 1), b2 + hstepB, voffB); PG8_STAGE(PG8_SA(0, 0), a2, voffA);
;             PG8_WAIT_V(8); PG8_WAIT_L(0); PG8_BAR; PG8_MMA(1, 0, At, B0); PG8_MMA(1, 1, At, B1); PG8_BAR; PG8_SCHED;
;             PG8_LDB(B0, 1, 0); PG8_LDB(B1, 1, 1); PG8_SCHED; PG8_LDA(At, 1, 0); PG8_STAGE(PG8_SA(0, 1), a2 + hstepA, voffA);
;             PG8_WAIT_V(8); PG8_WAIT_L(0); PG8_BAR; PG8_MMA(0, 0, At, B0); PG8_MMA(0, 1, At, B1); PG8_BAR; PG8_SCHED;
;             PG8_LDA(At, 1, 1); PG8_STAGE(PG8_SB(1, 0), b3, voffB); PG8_STAGE(PG8_SB(1, 1), b3 + hstepB, voffB); PG8_STAGE(PG8_SA(1, 0), a3, voffA);
	v_mfma_f32_16x16x32_bf16 v[62:65], v[142:145], v[174:177], v[62:65]
	v_mfma_f32_16x16x32_bf16 v[58:61], v[150:153], v[174:177], v[58:61]
	v_mfma_f32_16x16x32_bf16 v[46:49], v[142:145], v[182:185], v[46:49]
	v_mfma_f32_16x16x32_bf16 v[42:45], v[150:153], v[182:185], v[42:45]
	v_mfma_f32_16x16x32_bf16 v[30:33], v[142:145], v[190:193], v[30:33]
	v_mfma_f32_16x16x32_bf16 v[26:29], v[150:153], v[190:193], v[26:29]
	v_mfma_f32_16x16x32_bf16 v[14:17], v[142:145], v[198:201], v[14:17]
	v_mfma_f32_16x16x32_bf16 v[10:13], v[150:153], v[198:201], v[10:13]
	v_mfma_f32_16x16x32_bf16 v[62:65], v[146:149], v[178:181], v[62:65]
	v_mfma_f32_16x16x32_bf16 v[58:61], v[154:157], v[178:181], v[58:61]
	v_mfma_f32_16x16x32_bf16 v[46:49], v[146:149], v[186:189], v[46:49]
	v_mfma_f32_16x16x32_bf16 v[42:45], v[154:157], v[186:189], v[42:45]
	v_mfma_f32_16x16x32_bf16 v[30:33], v[146:149], v[194:197], v[30:33]
	v_mfma_f32_16x16x32_bf16 v[26:29], v[154:157], v[194:197], v[26:29]
	v_mfma_f32_16x16x32_bf16 v[14:17], v[146:149], v[204:207], v[14:17]
	v_mfma_f32_16x16x32_bf16 v[10:13], v[154:157], v[204:207], v[10:13]
	v_mfma_f32_16x16x32_bf16 v[54:57], v[158:161], v[174:177], v[54:57]
	v_mfma_f32_16x16x32_bf16 v[50:53], v[166:169], v[174:177], v[50:53]
	v_mfma_f32_16x16x32_bf16 v[38:41], v[158:161], v[182:185], v[38:41]
	v_mfma_f32_16x16x32_bf16 v[34:37], v[166:169], v[182:185], v[34:37]
	v_mfma_f32_16x16x32_bf16 v[22:25], v[158:161], v[190:193], v[22:25]
	v_mfma_f32_16x16x32_bf16 v[18:21], v[166:169], v[190:193], v[18:21]
	v_mfma_f32_16x16x32_bf16 v[6:9], v[158:161], v[198:201], v[6:9]
	v_mfma_f32_16x16x32_bf16 v[2:5], v[166:169], v[198:201], v[2:5]
	v_mfma_f32_16x16x32_bf16 v[54:57], v[162:165], v[178:181], v[54:57]
	v_mfma_f32_16x16x32_bf16 v[50:53], v[170:173], v[178:181], v[50:53]
	v_mfma_f32_16x16x32_bf16 v[38:41], v[162:165], v[186:189], v[38:41]
	v_mfma_f32_16x16x32_bf16 v[34:37], v[170:173], v[186:189], v[34:37]
	v_mfma_f32_16x16x32_bf16 v[22:25], v[162:165], v[194:197], v[22:25]
	v_mfma_f32_16x16x32_bf16 v[18:21], v[170:173], v[194:197], v[18:21]
	v_mfma_f32_16x16x32_bf16 v[6:9], v[162:165], v[204:207], v[6:9]
	v_mfma_f32_16x16x32_bf16 v[2:5], v[170:173], v[204:207], v[2:5]
	s_barrier
	v_add_u32_e32 v141, 0x18000, v139
	ds_read_b128 v[142:145], v141
	ds_read_b128 v[146:149], v141 offset:1024
	ds_read_b128 v[150:153], v141 offset:2048
	ds_read_b128 v[154:157], v141 offset:3072
	v_add_u32_e32 v141, 0x1c000, v139
	ds_read_b128 v[158:161], v141
	ds_read_b128 v[162:165], v141 offset:1024
	ds_read_b128 v[166:169], v141 offset:2048
	ds_read_b128 v[170:173], v141 offset:3072
	ds_read_b128 v[174:177], v140 offset:32768
	ds_read_b128 v[178:181], v140 offset:33792
	ds_read_b128 v[182:185], v140 offset:34816
	ds_read_b128 v[186:189], v140 offset:35840
	ds_read_b128 v[190:193], v140 offset:36864
	ds_read_b128 v[194:197], v140 offset:37888
	ds_read_b128 v[198:201], v140 offset:38912
	ds_read_b128 v[204:207], v140 offset:39936
	s_add_u32 s34, s34, 0x160000
	s_addc_u32 s35, s35, 0
	s_mov_b32 m0, s46
	s_nop 0
	global_load_lds_dwordx4 v131, s[34:35]
	s_nop 0
	s_mov_b32 m0, s47
	s_nop 0
	global_load_lds_dwordx4 v137, s[34:35]
	s_waitcnt vmcnt(8)
	s_waitcnt lgkmcnt(0)
	s_barrier
	v_mfma_f32_16x16x32_bf16 v[126:129], v[142:145], v[174:177], v[126:129]
	v_mfma_f32_16x16x32_bf16 v[122:125], v[150:153], v[174:177], v[122:125]
	v_mfma_f32_16x16x32_bf16 v[110:113], v[142:145], v[182:185], v[110:113]
	v_mfma_f32_16x16x32_bf16 v[106:109], v[150:153], v[182:185], v[106:109]
	v_mfma_f32_16x16x32_bf16 v[94:97], v[142:145], v[190:193], v[94:97]
	v_mfma_f32_16x16x32_bf16 v[90:93], v[150:153], v[190:193], v[90:93]
	v_mfma_f32_16x16x32_bf16 v[78:81], v[142:145], v[198:201], v[78:81]
	v_mfma_f32_16x16x32_bf16 v[74:77], v[150:153], v[198:201], v[74:77]
	v_mfma_f32_16x16x32_bf16 v[126:129], v[146:149], v[178:181], v[126:129]
	v_mfma_f32_16x16x32_bf16 v[122:125], v[154:157], v[178:181], v[122:125]
	v_mfma_f32_16x16x32_bf16 v[110:113], v[146:149], v[186:189], v[110:113]
	v_mfma_f32_16x16x32_bf16 v[106:109], v[154:157], v[186:189], v[106:109]
	v_mfma_f32_16x16x32_bf16 v[94:97], v[146:149], v[194:197], v[94:97]
	v_mfma_f32_16x16x32_bf16 v[90:93], v[154:157], v[194:197], v[90:93]
	v_mfma_f32_16x16x32_bf16 v[78:81], v[146:149], v[204:207], v[78:81]
	v_mfma_f32_16x16x32_bf16 v[74:77], v[154:157], v[204:207], v[74:77]
	v_mfma_f32_16x16x32_bf16 v[118:121], v[158:161], v[174:177], v[118:121]
	v_mfma_f32_16x16x32_bf16 v[114:117], v[166:169], v[174:177], v[114:117]
	v_mfma_f32_16x16x32_bf16 v[102:105], v[158:161], v[182:185], v[102:105]
	v_mfma_f32_16x16x32_bf16 v[98:101], v[166:169], v[182:185], v[98:101]
	v_mfma_f32_16x16x32_bf16 v[86:89], v[158:161], v[190:193], v[86:89]
	v_mfma_f32_16x16x32_bf16 v[82:85], v[166:169], v[190:193], v[82:85]
	v_mfma_f32_16x16x32_bf16 v[70:73], v[158:161], v[198:201], v[70:73]
	v_mfma_f32_16x16x32_bf16 v[66:69], v[166:169], v[198:201], v[66:69]
	v_mfma_f32_16x16x32_bf16 v[118:121], v[162:165], v[178:181], v[118:121]
	v_mfma_f32_16x16x32_bf16 v[114:117], v[170:173], v[178:181], v[114:117]
	v_mfma_f32_16x16x32_bf16 v[102:105], v[162:165], v[186:189], v[102:105]
	v_mfma_f32_16x16x32_bf16 v[98:101], v[170:173], v[186:189], v[98:101]
	v_mfma_f32_16x16x32_bf16 v[86:89], v[162:165], v[194:197], v[86:89]
	v_mfma_f32_16x16x32_bf16 v[82:85], v[170:173], v[194:197], v[82:85]
	v_mfma_f32_16x16x32_bf16 v[70:73], v[162:165], v[204:207], v[70:73]
	v_mfma_f32_16x16x32_bf16 v[66:69], v[170:173], v[204:207], v[66:69]
	s_barrier
; #define PG8_STAGE(bufoff, gbase, voff) do { _Pragma("unroll") for (int _i = 0; _i < 2; ++_i) { unsigned keep_; \
;         asm volatile("s_mov_b32 %0, m0\n\ts_mov_b32 m0, %3\n\ts_nop 0\n\tglobal_load_lds_dwordx4 %1, %2\n\ts_mov_b32 m0, %0" \
;             : "=&s"(keep_) : "v"((voff)[_i]), "s"((const void*)(gbase)), "s"(ldsb0 + (unsigned)(bufoff) + (unsigned)(_i * 8192)) : "memory"); } } while (0)
; #define PG8_LDA(dst, b, h) do { _Pragma("unroll") for (int m = 0; m < 4; ++m) _Pragma("unroll") for (int k = 0; k < 2; ++k) dst[m][k] = *(const LAS bf16x8*)(lds + PG8_SA(b, h) + aoff + m * 2048 + k * 1024); } while (0)
; #define PG8_MMA(ai, bj, At, Bt) do { __builtin_amdgcn_s_setprio(1); _Pragma("unroll") for (int m = 0; m < 4; ++m) _Pragma("unroll") for (int n = 0; n < 2; ++n) _Pragma("unroll") for (int k = 0; k < 2; ++k) \
;         acc[ai][bj][m][n] = __builtin_amdgcn_mfma_f32_16x16x32_bf16(Bt[n][k], At[m][k], acc[ai][bj][m][n], 0, 0, 0); __builtin_amdgcn_s_setprio(0); } while (0)
; #define PG8_WAIT_V(n) asm volatile("s_waitcnt vmcnt(" #n ")" ::: "memory")
; #define PG8_WAIT_L(n) asm volatile("s_waitcnt lgkmcnt(" #n ")" ::: "memory")
; #define PG8_BAR __builtin_amdgcn_s_barrier()
; #define PG8_SCHED __builtin_amdgcn_sched_barrier(0)
; template <class Epi, class Sched, bool ALIGN_EPI>
; __device__ __forceinline__ void gemm_phase(LAS unsigned char* lds, const Gemm g, const Sched& S, const Epi& E) {
;     ...
;             PG8_WAIT_V(8); PG8_WAIT_L(0); PG8_BAR; PG8_MMA(0, 0, At, B0); PG8_MMA(0, 1, At, B1); PG8_BAR; PG8_SCHED;
;             PG8_LDA(At, 1, 1); PG8_STAGE(PG8_SB(1, 0), b3, voffB); PG8_STAGE(PG8_SB(1, 1), b3 + hstepB, voffB); PG8_STAGE(PG8_SA(1, 0), a3, voffA);
;             PG8_WAIT_V(8); PG8_WAIT_L(0); PG8_BAR; PG8_MMA(1, 0, At, B0); PG8_MMA(1, 1, At, B1); PG8_BAR; PG8_SCHED;
;         }
;         if constexpr (ALIGN_EPI) { if (wr == 0) PG8_BAR; }
;         if constexpr (Epi::NPRE > 0) E(acc, cur, wr, wc, fr, fq, pre); else
;         if constexpr (!Epi::AFTER_DRAIN) E(acc, cur, wr, wc, fr, fq);
;         if (!has_next) break;
; #pragma unroll
;         for (int a = 0; a < 2; ++a)
; #pragma unroll
;             for (int b = 0; b < 2; ++b)
; #pragma unroll
;                 for (int m = 0; m < 4; ++m)
; #pragma unroll
;                     for (int n = 0; n < 2; ++n) acc[a][b][m][n] = (f32x4){0.f, 0.f, 0.f, 0.f};
;         cur = nxt; cA = nA; cB = nB; ++ui;
	ds_read_b128 v[174:177], v140 offset:49152
	ds_read_b128 v[178:181], v140 offset:50176
	ds_read_b128 v[182:185], v140 offset:51200
	ds_read_b128 v[186:189], v140 offset:52224
	ds_read_b128 v[190:193], v140 offset:53248
	ds_read_b128 v[194:197], v140 offset:54272
	ds_read_b128 v[198:201], v140 offset:55296
	ds_read_b128 v[204:207], v140 offset:56320
	s_add_u32 s34, s30, 0x80
	s_addc_u32 s35, s31, 0
	s_mov_b32 m0, s48
	s_nop 0
	global_load_lds_dwordx4 v136, s[34:35]
	s_add_u32 s30, s30, 0x160080
	s_mov_b32 m0, s49
	s_nop 0
	global_load_lds_dwordx4 v138, s[34:35]
	s_addc_u32 s31, s31, 0
	s_mov_b32 m0, s52
	s_nop 0
	global_load_lds_dwordx4 v136, s[30:31]
	s_nop 0
	s_mov_b32 m0, s53
	s_nop 0
	global_load_lds_dwordx4 v138, s[30:31]
	s_mov_b32 m0, s50
	s_nop 0
	global_load_lds_dwordx4 v131, s[28:29]
	s_nop 0
	s_mov_b32 m0, s51
	s_nop 0
	global_load_lds_dwordx4 v137, s[28:29]
	s_waitcnt vmcnt(8)
	s_waitcnt lgkmcnt(0)
	s_barrier
	v_mfma_f32_16x16x32_bf16 v[62:65], v[142:145], v[174:177], v[62:65]
	v_mfma_f32_16x16x32_bf16 v[58:61], v[150:153], v[174:177], v[58:61]
	v_mfma_f32_16x16x32_bf16 v[46:49], v[142:145], v[182:185], v[46:49]
	v_mfma_f32_16x16x32_bf16 v[42:45], v[150:153], v[182:185], v[42:45]
	v_mfma_f32_16x16x32_bf16 v[30:33], v[142:145], v[190:193], v[30:33]
	v_mfma_f32_16x16x32_bf16 v[26:29], v[150:153], v[190:193], v[26:29]
	v_mfma_f32_16x16x32_bf16 v[14:17], v[142:145], v[198:201], v[14:17]
	v_mfma_f32_16x16x32_bf16 v[10:13], v[150:153], v[198:201], v[10:13]
	v_mfma_f32_16x16x32_bf16 v[62:65], v[146:149], v[178:181], v[62:65]
	v_mfma_f32_16x16x32_bf16 v[58:61], v[154:157], v[178:181], v[58:61]
	v_mfma_f32_16x16x32_bf16 v[46:49], v[146:149], v[186:189], v[46:49]
	v_mfma_f32_16x16x32_bf16 v[42:45], v[154:157], v[186:189], v[42:45]
	v_mfma_f32_16x16x32_bf16 v[30:33], v[146:149], v[194:197], v[30:33]
	v_mfma_f32_16x16x32_bf16 v[26:29], v[154:157], v[194:197], v[26:29]
	v_mfma_f32_16x16x32_bf16 v[14:17], v[146:149], v[204:207], v[14:17]
	v_mfma_f32_16x16x32_bf16 v[10:13], v[154:157], v[204:207], v[10:13]
	v_mfma_f32_16x16x32_bf16 v[54:57], v[158:161], v[174:177], v[54:57]
	v_mfma_f32_16x16x32_bf16 v[50:53], v[166:169], v[174:177], v[50:53]
	v_mfma_f32_16x16x32_bf16 v[38:41], v[158:161], v[182:185], v[38:41]
	v_mfma_f32_16x16x32_bf16 v[34:37], v[166:169], v[182:185], v[34:37]
	v_mfma_f32_16x16x32_bf16 v[22:25], v[158:161], v[190:193], v[22:25]
	v_mfma_f32_16x16x32_bf16 v[18:21], v[166:169], v[190:193], v[18:21]
	v_mfma_f32_16x16x32_bf16 v[6:9], v[158:161], v[198:201], v[6:9]
	v_mfma_f32_16x16x32_bf16 v[2:5], v[166:169], v[198:201], v[2:5]
	v_mfma_f32_16x16x32_bf16 v[54:57], v[162:165], v[178:181], v[54:57]
	v_mfma_f32_16x16x32_bf16 v[50:53], v[170:173], v[178:181], v[50:53]
	v_mfma_f32_16x16x32_bf16 v[38:41], v[162:165], v[186:189], v[38:41]
	v_mfma_f32_16x16x32_bf16 v[34:37], v[170:173], v[186:189], v[34:37]
	v_mfma_f32_16x16x32_bf16 v[22:25], v[162:165], v[194:197], v[22:25]
	v_mfma_f32_16x16x32_bf16 v[18:21], v[170:173], v[194:197], v[18:21]
	v_mfma_f32_16x16x32_bf16 v[6:9], v[162:165], v[204:207], v[6:9]
	v_mfma_f32_16x16x32_bf16 v[2:5], v[170:173], v[204:207], v[2:5]
	s_barrier
	s_add_i32 s60, s60, 2
	s_add_u32 s26, s26, 0x100
	s_addc_u32 s27, s27, 0
	s_cmpk_gt_u32 s60, 0x55
	s_cbranch_scc0 .LBB0_2172
	s_and_b64 vcc, exec, s[10:11]
	s_cbranch_vccnz .LBB0_2160
	v_mov_b32_e32 v2, 0
	s_mov_b32 s45, s57
	s_mov_b32 s17, s58
	s_mov_b64 s[20:21], s[24:25]
	s_mov_b64 s[22:23], s[12:13]
	s_mov_b32 s56, s59
	v_mov_b32_e32 v3, v2
	v_mov_b32_e32 v4, v2
	v_mov_b32_e32 v5, v2
	v_mov_b32_e32 v6, v2
	v_mov_b32_e32 v7, v2
	v_mov_b32_e32 v8, v2
	v_mov_b32_e32 v9, v2
	v_mov_b32_e32 v18, v2
	v_mov_b32_e32 v19, v2
	v_mov_b32_e32 v20, v2
	v_mov_b32_e32 v21, v2
	v_mov_b32_e32 v22, v2
	v_mov_b32_e32 v23, v2
	v_mov_b32_e32 v24, v2
	v_mov_b32_e32 v25, v2
	v_mov_b32_e32 v34, v2
	v_mov_b32_e32 v35, v2
	v_mov_b32_e32 v36, v2
	v_mov_b32_e32 v37, v2
	v_mov_b32_e32 v38, v2
	v_mov_b32_e32 v39, v2
	v_mov_b32_e32 v40, v2
	v_mov_b32_e32 v41, v2
	v_mov_b32_e32 v50, v2
	v_mov_b32_e32 v51, v2
	v_mov_b32_e32 v52, v2
	v_mov_b32_e32 v53, v2
	v_mov_b32_e32 v54, v2
	v_mov_b32_e32 v55, v2
	v_mov_b32_e32 v56, v2
	v_mov_b32_e32 v57, v2
	v_mov_b32_e32 v10, v2
	v_mov_b32_e32 v11, v2
	v_mov_b32_e32 v12, v2
	v_mov_b32_e32 v13, v2
	v_mov_b32_e32 v14, v2
	v_mov_b32_e32 v15, v2
	v_mov_b32_e32 v16, v2
	v_mov_b32_e32 v17, v2
	v_mov_b32_e32 v26, v2
	v_mov_b32_e32 v27, v2
	v_mov_b32_e32 v28, v2
	v_mov_b32_e32 v29, v2
	v_mov_b32_e32 v30, v2
	v_mov_b32_e32 v31, v2
	v_mov_b32_e32 v32, v2
	v_mov_b32_e32 v33, v2
	v_mov_b32_e32 v42, v2
	v_mov_b32_e32 v43, v2
	v_mov_b32_e32 v44, v2
	v_mov_b32_e32 v45, v2
	v_mov_b32_e32 v46, v2
	v_mov_b32_e32 v47, v2
	v_mov_b32_e32 v48, v2
	v_mov_b32_e32 v49, v2
	v_mov_b32_e32 v58, v2
	v_mov_b32_e32 v59, v2
	v_mov_b32_e32 v60, v2
	v_mov_b32_e32 v61, v2
	v_mov_b32_e32 v62, v2
	v_mov_b32_e32 v63, v2
	v_mov_b32_e32 v64, v2
	v_mov_b32_e32 v65, v2
	v_mov_b32_e32 v66, v2
	v_mov_b32_e32 v67, v2
	v_mov_b32_e32 v68, v2
	v_mov_b32_e32 v69, v2
	v_mov_b32_e32 v70, v2
	v_mov_b32_e32 v71, v2
	v_mov_b32_e32 v72, v2
	v_mov_b32_e32 v73, v2
	v_mov_b32_e32 v82, v2
	v_mov_b32_e32 v83, v2
	v_mov_b32_e32 v84, v2
	v_mov_b32_e32 v85, v2
	v_mov_b32_e32 v86, v2
	v_mov_b32_e32 v87, v2
	v_mov_b32_e32 v88, v2
	v_mov_b32_e32 v89, v2
	v_mov_b32_e32 v98, v2
	v_mov_b32_e32 v99, v2
	v_mov_b32_e32 v100, v2
	v_mov_b32_e32 v101, v2
	v_mov_b32_e32 v102, v2
	v_mov_b32_e32 v103, v2
	v_mov_b32_e32 v104, v2
	v_mov_b32_e32 v105, v2
	v_mov_b32_e32 v114, v2
	v_mov_b32_e32 v115, v2
	v_mov_b32_e32 v116, v2
	v_mov_b32_e32 v117, v2
	v_mov_b32_e32 v118, v2
	v_mov_b32_e32 v119, v2
	v_mov_b32_e32 v120, v2
	v_mov_b32_e32 v121, v2
	v_mov_b32_e32 v74, v2
	v_mov_b32_e32 v75, v2
	v_mov_b32_e32 v76, v2
	v_mov_b32_e32 v77, v2
	v_mov_b32_e32 v78, v2
	v_mov_b32_e32 v79, v2
	v_mov_b32_e32 v80, v2
	v_mov_b32_e32 v81, v2
	v_mov_b32_e32 v90, v2
	v_mov_b32_e32 v91, v2
	v_mov_b32_e32 v92, v2
	v_mov_b32_e32 v93, v2
	v_mov_b32_e32 v94, v2
	v_mov_b32_e32 v95, v2
	v_mov_b32_e32 v96, v2
	v_mov_b32_e32 v97, v2
	v_mov_b32_e32 v106, v2
	v_mov_b32_e32 v107, v2
	v_mov_b32_e32 v108, v2
	v_mov_b32_e32 v109, v2
	v_mov_b32_e32 v110, v2
	v_mov_b32_e32 v111, v2
	v_mov_b32_e32 v112, v2
	v_mov_b32_e32 v113, v2
	v_mov_b32_e32 v122, v2
	v_mov_b32_e32 v123, v2
	v_mov_b32_e32 v124, v2
	v_mov_b32_e32 v125, v2
	v_mov_b32_e32 v126, v2
	v_mov_b32_e32 v127, v2
	v_mov_b32_e32 v128, v2
	v_mov_b32_e32 v129, v2
	s_branch .LBB0_2160
